# baseline (speedup 1.0000x reference)
; __device__ __forceinline__ u16 f2bf(float f) { return (u16)(cvtpk(f, f) & 0xffffu); }
; #define FOR_M _Pragma("unroll") for (int m = 0; m < 4; ++m)
; #define FOR_J _Pragma("unroll") for (int j = 0; j < 4; ++j)
; #define OPQ(x) asm volatile("" : "+v"(x))
; #define ENDM __builtin_amdgcn_sched_barrier(0)
; template <int EPI>
; __device__ __forceinline__ void epi_quad(const Params& P, f32x4 (&acc)[4][2], int rowb, int pn, int wc, int fr, int fq,
;                                          const float* xres, float* yout, const float* rstd_q) {
;     ...
;     } else if (pn < 48) {
;       char* gb_ = (char*)(P_gate + (size_t)rowb * DM + (pn - 16) * 128);
;       const unsigned vo = (r4 * DM + cg) * 2;
;       FOR_M { unsigned vom = vo + (unsigned)(m * 16 * DM) * 2; OPQ(vom);
;         FOR_J {
; #pragma unroll
;           for (int n = 0; n < 2; ++n) {
;             const float v = acc[m][n][j];
;             ST16(gb_, vom + (unsigned)(j * DM + n * 16) * 2, f2bf(v * __builtin_amdgcn_rcpf(1.f + __expf(-v))));
;           }
;         } ENDM; }
.LBB0_147:
	s_andn2_b64 vcc, exec, s[0:1]
	s_cbranch_vccnz .LBB0_149
	s_add_u32 s54, s94, s56
	s_addc_u32 s55, s95, s57
	s_lshl_b64 s[0:1], s[48:49], 1
	s_add_u32 s0, s54, s0
	s_addc_u32 s1, s55, s1
	s_add_u32 s54, s0, 0x16f0f000
	s_addc_u32 s55, s1, 0
	v_mul_f32_e32 v254, 0xbfb8aa3b, v96
	v_mul_f32_e32 v255, 0xbfb8aa3b, v97
	v_exp_f32_e32 v254, v254
	v_exp_f32_e32 v255, v255
	v_add_f32_e32 v254, 1.0, v254
	v_add_f32_e32 v255, 1.0, v255
	v_rcp_f32_e32 v254, v254
	v_rcp_f32_e32 v255, v255
	v_mul_f32_e32 v96, v96, v254
	v_mul_f32_e32 v97, v97, v255
	v_mul_f32_e32 v254, 0xbfb8aa3b, v98
	v_mul_f32_e32 v255, 0xbfb8aa3b, v99
	v_exp_f32_e32 v254, v254
	v_exp_f32_e32 v255, v255
	v_add_f32_e32 v254, 1.0, v254
	v_add_f32_e32 v255, 1.0, v255
	v_rcp_f32_e32 v254, v254
	v_rcp_f32_e32 v255, v255
	v_mul_f32_e32 v98, v98, v254
	v_mul_f32_e32 v99, v99, v255
	v_cvt_pk_bf16_f32 v96, v96, v97
	v_cvt_pk_bf16_f32 v98, v98, v99
	global_store_short v174, v96, s[54:55]
	v_add_u32_e32 v251, 0x2000, v174
	global_store_short_d16_hi v251, v96, s[54:55]
	v_add_u32_e32 v252, 0x4000, v174
	global_store_short v252, v98, s[54:55]
	v_add_u32_e32 v253, 0x6000, v174
	global_store_short_d16_hi v253, v98, s[54:55]
	v_mul_f32_e32 v254, 0xbfb8aa3b, v100
	v_mul_f32_e32 v255, 0xbfb8aa3b, v101
	v_exp_f32_e32 v254, v254
	v_exp_f32_e32 v255, v255
	v_add_f32_e32 v254, 1.0, v254
	v_add_f32_e32 v255, 1.0, v255
	v_rcp_f32_e32 v254, v254
	v_rcp_f32_e32 v255, v255
	v_mul_f32_e32 v100, v100, v254
	v_mul_f32_e32 v101, v101, v255
	v_mul_f32_e32 v254, 0xbfb8aa3b, v102
	v_mul_f32_e32 v255, 0xbfb8aa3b, v103
	v_exp_f32_e32 v254, v254
	v_exp_f32_e32 v255, v255
	v_add_f32_e32 v254, 1.0, v254
	v_add_f32_e32 v255, 1.0, v255
	v_rcp_f32_e32 v254, v254
	v_rcp_f32_e32 v255, v255
	v_mul_f32_e32 v102, v102, v254
	v_mul_f32_e32 v103, v103, v255
	v_cvt_pk_bf16_f32 v100, v100, v101
	v_cvt_pk_bf16_f32 v102, v102, v103
	global_store_short v174, v100, s[54:55] offset:32
	global_store_short_d16_hi v251, v100, s[54:55] offset:32
	global_store_short v252, v102, s[54:55] offset:32
	global_store_short_d16_hi v253, v102, s[54:55] offset:32
	v_mul_f32_e32 v254, 0xbfb8aa3b, v104
	v_mul_f32_e32 v255, 0xbfb8aa3b, v105
	v_exp_f32_e32 v254, v254
	v_exp_f32_e32 v255, v255
	v_add_f32_e32 v254, 1.0, v254
	v_add_f32_e32 v255, 1.0, v255
	v_rcp_f32_e32 v254, v254
	v_rcp_f32_e32 v255, v255
	v_mul_f32_e32 v104, v104, v254
	v_mul_f32_e32 v105, v105, v255
	v_mul_f32_e32 v254, 0xbfb8aa3b, v106
	v_mul_f32_e32 v255, 0xbfb8aa3b, v107
	v_exp_f32_e32 v254, v254
	v_exp_f32_e32 v255, v255
	v_add_f32_e32 v254, 1.0, v254
	v_add_f32_e32 v255, 1.0, v255
	v_rcp_f32_e32 v254, v254
	v_rcp_f32_e32 v255, v255
	v_mul_f32_e32 v106, v106, v254
	v_mul_f32_e32 v107, v107, v255
	v_cvt_pk_bf16_f32 v104, v104, v105
	v_cvt_pk_bf16_f32 v106, v106, v107
	global_store_short v175, v104, s[54:55]
	v_add_u32_e32 v251, 0x2000, v175
	global_store_short_d16_hi v251, v104, s[54:55]
	v_add_u32_e32 v252, 0x4000, v175
	global_store_short v252, v106, s[54:55]
	v_add_u32_e32 v253, 0x6000, v175
	global_store_short_d16_hi v253, v106, s[54:55]
	v_mul_f32_e32 v254, 0xbfb8aa3b, v108
	v_mul_f32_e32 v255, 0xbfb8aa3b, v109
	v_exp_f32_e32 v254, v254
	v_exp_f32_e32 v255, v255
	v_add_f32_e32 v254, 1.0, v254
	v_add_f32_e32 v255, 1.0, v255
	v_rcp_f32_e32 v254, v254
	v_rcp_f32_e32 v255, v255
	v_mul_f32_e32 v108, v108, v254
	v_mul_f32_e32 v109, v109, v255
	v_mul_f32_e32 v254, 0xbfb8aa3b, v110
	v_mul_f32_e32 v255, 0xbfb8aa3b, v111
	v_exp_f32_e32 v254, v254
	v_exp_f32_e32 v255, v255
	v_add_f32_e32 v254, 1.0, v254
	v_add_f32_e32 v255, 1.0, v255
	v_rcp_f32_e32 v254, v254
	v_rcp_f32_e32 v255, v255
	v_mul_f32_e32 v110, v110, v254
	v_mul_f32_e32 v111, v111, v255
	v_cvt_pk_bf16_f32 v108, v108, v109
	v_cvt_pk_bf16_f32 v110, v110, v111
	global_store_short v175, v108, s[54:55] offset:32
	global_store_short_d16_hi v251, v108, s[54:55] offset:32
; __device__ __forceinline__ u16 f2bf(float f) { return (u16)(cvtpk(f, f) & 0xffffu); }
; #define FOR_M _Pragma("unroll") for (int m = 0; m < 4; ++m)
; #define FOR_J _Pragma("unroll") for (int j = 0; j < 4; ++j)
; #define OPQ(x) asm volatile("" : "+v"(x))
; #define ENDM __builtin_amdgcn_sched_barrier(0)
; template <int EPI>
; __device__ __forceinline__ void epi_quad(const Params& P, f32x4 (&acc)[4][2], int rowb, int pn, int wc, int fr, int fq,
;                                          const float* xres, float* yout, const float* rstd_q) {
;     ...
;     } else if (pn < 48) {
;       char* gb_ = (char*)(P_gate + (size_t)rowb * DM + (pn - 16) * 128);
;       const unsigned vo = (r4 * DM + cg) * 2;
;       FOR_M { unsigned vom = vo + (unsigned)(m * 16 * DM) * 2; OPQ(vom);
;         FOR_J {
; #pragma unroll
;           for (int n = 0; n < 2; ++n) {
;             const float v = acc[m][n][j];
;             ST16(gb_, vom + (unsigned)(j * DM + n * 16) * 2, f2bf(v * __builtin_amdgcn_rcpf(1.f + __expf(-v))));
;           }
;         } ENDM; }
	global_store_short v252, v110, s[54:55] offset:32
	global_store_short_d16_hi v253, v110, s[54:55] offset:32
	v_mul_f32_e32 v254, 0xbfb8aa3b, v112
	v_mul_f32_e32 v255, 0xbfb8aa3b, v113
	v_exp_f32_e32 v254, v254
	v_exp_f32_e32 v255, v255
	v_add_f32_e32 v254, 1.0, v254
	v_add_f32_e32 v255, 1.0, v255
	v_rcp_f32_e32 v254, v254
	v_rcp_f32_e32 v255, v255
	v_mul_f32_e32 v112, v112, v254
	v_mul_f32_e32 v113, v113, v255
	v_mul_f32_e32 v254, 0xbfb8aa3b, v114
	v_mul_f32_e32 v255, 0xbfb8aa3b, v115
	v_exp_f32_e32 v254, v254
	v_exp_f32_e32 v255, v255
	v_add_f32_e32 v254, 1.0, v254
	v_add_f32_e32 v255, 1.0, v255
	v_rcp_f32_e32 v254, v254
	v_rcp_f32_e32 v255, v255
	v_mul_f32_e32 v114, v114, v254
	v_mul_f32_e32 v115, v115, v255
	v_cvt_pk_bf16_f32 v112, v112, v113
	v_cvt_pk_bf16_f32 v114, v114, v115
	global_store_short v176, v112, s[54:55]
	v_add_u32_e32 v251, 0x2000, v176
	global_store_short_d16_hi v251, v112, s[54:55]
	v_add_u32_e32 v252, 0x4000, v176
	global_store_short v252, v114, s[54:55]
	v_add_u32_e32 v253, 0x6000, v176
	global_store_short_d16_hi v253, v114, s[54:55]
	v_mul_f32_e32 v254, 0xbfb8aa3b, v116
	v_mul_f32_e32 v255, 0xbfb8aa3b, v117
	v_exp_f32_e32 v254, v254
	v_exp_f32_e32 v255, v255
	v_add_f32_e32 v254, 1.0, v254
	v_add_f32_e32 v255, 1.0, v255
	v_rcp_f32_e32 v254, v254
	v_rcp_f32_e32 v255, v255
	v_mul_f32_e32 v116, v116, v254
	v_mul_f32_e32 v117, v117, v255
	v_mul_f32_e32 v254, 0xbfb8aa3b, v118
	v_mul_f32_e32 v255, 0xbfb8aa3b, v119
	v_exp_f32_e32 v254, v254
	v_exp_f32_e32 v255, v255
	v_add_f32_e32 v254, 1.0, v254
	v_add_f32_e32 v255, 1.0, v255
	v_rcp_f32_e32 v254, v254
	v_rcp_f32_e32 v255, v255
	v_mul_f32_e32 v118, v118, v254
	v_mul_f32_e32 v119, v119, v255
	v_cvt_pk_bf16_f32 v116, v116, v117
	v_cvt_pk_bf16_f32 v118, v118, v119
	global_store_short v176, v116, s[54:55] offset:32
	global_store_short_d16_hi v251, v116, s[54:55] offset:32
	global_store_short v252, v118, s[54:55] offset:32
	global_store_short_d16_hi v253, v118, s[54:55] offset:32
	v_mul_f32_e32 v254, 0xbfb8aa3b, v120
	v_mul_f32_e32 v255, 0xbfb8aa3b, v121
	v_exp_f32_e32 v254, v254
	v_exp_f32_e32 v255, v255
	v_add_f32_e32 v254, 1.0, v254
	v_add_f32_e32 v255, 1.0, v255
	v_rcp_f32_e32 v254, v254
	v_rcp_f32_e32 v255, v255
	v_mul_f32_e32 v120, v120, v254
	v_mul_f32_e32 v121, v121, v255
	v_mul_f32_e32 v254, 0xbfb8aa3b, v122
	v_mul_f32_e32 v255, 0xbfb8aa3b, v123
	v_exp_f32_e32 v254, v254
	v_exp_f32_e32 v255, v255
	v_add_f32_e32 v254, 1.0, v254
	v_add_f32_e32 v255, 1.0, v255
	v_rcp_f32_e32 v254, v254
	v_rcp_f32_e32 v255, v255
	v_mul_f32_e32 v122, v122, v254
	v_mul_f32_e32 v123, v123, v255
	v_cvt_pk_bf16_f32 v120, v120, v121
	v_cvt_pk_bf16_f32 v122, v122, v123
	global_store_short v177, v120, s[54:55]
	v_add_u32_e32 v251, 0x2000, v177
	global_store_short_d16_hi v251, v120, s[54:55]
	v_add_u32_e32 v252, 0x4000, v177
	global_store_short v252, v122, s[54:55]
	v_add_u32_e32 v253, 0x6000, v177
	global_store_short_d16_hi v253, v122, s[54:55]
	v_mul_f32_e32 v254, 0xbfb8aa3b, v124
	v_mul_f32_e32 v255, 0xbfb8aa3b, v125
	v_exp_f32_e32 v254, v254
	v_exp_f32_e32 v255, v255
	v_add_f32_e32 v254, 1.0, v254
	v_add_f32_e32 v255, 1.0, v255
	v_rcp_f32_e32 v254, v254
	v_rcp_f32_e32 v255, v255
	v_mul_f32_e32 v124, v124, v254
	v_mul_f32_e32 v125, v125, v255
	v_mul_f32_e32 v254, 0xbfb8aa3b, v126
	v_mul_f32_e32 v255, 0xbfb8aa3b, v127
	v_exp_f32_e32 v254, v254
	v_exp_f32_e32 v255, v255
	v_add_f32_e32 v254, 1.0, v254
	v_add_f32_e32 v255, 1.0, v255
	v_rcp_f32_e32 v254, v254
	v_rcp_f32_e32 v255, v255
	v_mul_f32_e32 v126, v126, v254
	v_mul_f32_e32 v127, v127, v255
	v_cvt_pk_bf16_f32 v124, v124, v125
	v_cvt_pk_bf16_f32 v126, v126, v127
	global_store_short v177, v124, s[54:55] offset:32
	global_store_short_d16_hi v251, v124, s[54:55] offset:32
	global_store_short v252, v126, s[54:55] offset:32
	global_store_short_d16_hi v253, v126, s[54:55] offset:32

; __device__ __forceinline__ u16 f2bf(float f) { return (u16)(cvtpk(f, f) & 0xffffu); }
; #define FOR_M _Pragma("unroll") for (int m = 0; m < 4; ++m)
; #define FOR_J _Pragma("unroll") for (int j = 0; j < 4; ++j)
; #define OPQ(x) asm volatile("" : "+v"(x))
; #define ENDM __builtin_amdgcn_sched_barrier(0)
; template <int EPI>
; __device__ __forceinline__ void epi_quad(const Params& P, f32x4 (&acc)[4][2], int rowb, int pn, int wc, int fr, int fq,
;                                          const float* xres, float* yout, const float* rstd_q) {
;     ...
;     } else if (pn < 16) {
;       char* vb_ = (char*)(P_vA + ((size_t)(b * 4 + (pn - 12)) * SEQ + pos0) * 128);
;       const unsigned vo = (r4 * 128 + cg) * 2;
;       FOR_M { unsigned vom = vo + (unsigned)(m * 16 * 128) * 2; OPQ(vom);
;         FOR_J {
; #pragma unroll
;           for (int n = 0; n < 2; ++n) ST16(vb_, vom + (unsigned)(j * 128 + n * 16) * 2, f2bf(acc[m][n][j]));
;         } ENDM; }
.LBB0_150:
	s_andn2_b64 vcc, exec, s[0:1]
	s_cbranch_vccnz .LBB0_152
	s_add_i32 s0, s81, s73
	s_ashr_i32 s1, s0, 31
	s_lshl_b64 s[0:1], s[0:1], 20
	s_add_u32 s0, s86, s0
	s_addc_u32 s1, s87, s1
	s_lshl_b32 s54, s80, 1
	s_add_u32 s54, s0, s54
	s_addc_u32 s55, s1, 0
	v_mov_b32_e32 v130, v128
	v_cvt_pk_bf16_f32 v120, v120, v121
	v_cvt_pk_bf16_f32 v122, v122, v123
	global_store_short v130, v120, s[54:55]
	global_store_short_d16_hi v130, v120, s[54:55] offset:256
	global_store_short v130, v122, s[54:55] offset:512
	global_store_short_d16_hi v130, v122, s[54:55] offset:768
	v_cvt_pk_bf16_f32 v124, v124, v125
	v_cvt_pk_bf16_f32 v126, v126, v127
	global_store_short v130, v124, s[54:55] offset:32
	global_store_short_d16_hi v130, v124, s[54:55] offset:288
	global_store_short v130, v126, s[54:55] offset:544
	global_store_short_d16_hi v130, v126, s[54:55] offset:800
	v_cvt_pk_bf16_f32 v96, v96, v97
	v_cvt_pk_bf16_f32 v98, v98, v99
	global_store_short v171, v96, s[54:55]
	global_store_short_d16_hi v171, v96, s[54:55] offset:256
	global_store_short v171, v98, s[54:55] offset:512
	global_store_short_d16_hi v171, v98, s[54:55] offset:768
	v_cvt_pk_bf16_f32 v100, v100, v101
	v_cvt_pk_bf16_f32 v102, v102, v103
	global_store_short v171, v100, s[54:55] offset:32
	global_store_short_d16_hi v171, v100, s[54:55] offset:288
	global_store_short v171, v102, s[54:55] offset:544
	global_store_short_d16_hi v171, v102, s[54:55] offset:800
	v_cvt_pk_bf16_f32 v104, v104, v105
	v_cvt_pk_bf16_f32 v106, v106, v107
	global_store_short v172, v104, s[54:55]
	global_store_short_d16_hi v172, v104, s[54:55] offset:256
	global_store_short v172, v106, s[54:55] offset:512
	global_store_short_d16_hi v172, v106, s[54:55] offset:768
	v_cvt_pk_bf16_f32 v108, v108, v109
	v_cvt_pk_bf16_f32 v110, v110, v111
	global_store_short v172, v108, s[54:55] offset:32
	global_store_short_d16_hi v172, v108, s[54:55] offset:288
	global_store_short v172, v110, s[54:55] offset:544
	global_store_short_d16_hi v172, v110, s[54:55] offset:800
	v_cvt_pk_bf16_f32 v112, v112, v113
	v_cvt_pk_bf16_f32 v114, v114, v115
	global_store_short v173, v112, s[54:55]
	global_store_short_d16_hi v173, v112, s[54:55] offset:256
	global_store_short v173, v114, s[54:55] offset:512
	global_store_short_d16_hi v173, v114, s[54:55] offset:768
	v_cvt_pk_bf16_f32 v116, v116, v117
	v_cvt_pk_bf16_f32 v118, v118, v119
	global_store_short v173, v116, s[54:55] offset:32
	global_store_short_d16_hi v173, v116, s[54:55] offset:288
	global_store_short v173, v118, s[54:55] offset:544
	global_store_short_d16_hi v173, v118, s[54:55] offset:800

; __device__ __forceinline__ u16 f2bf(float f) { return (u16)(cvtpk(f, f) & 0xffffu); }
; #define FOR_M _Pragma("unroll") for (int m = 0; m < 4; ++m)
; #define FOR_J _Pragma("unroll") for (int j = 0; j < 4; ++j)
; #define OPQ(x) asm volatile("" : "+v"(x))
; #define ENDM __builtin_amdgcn_sched_barrier(0)
; template <int EPI>
; __device__ __forceinline__ void epi_quad(const Params& P, f32x4 (&acc)[4][2], int rowb, int pn, int wc, int fr, int fq,
;                                          const float* xres, float* yout, const float* rstd_q) {
;     ...
;     } else if (pn < 48) {
;       char* gb_ = (char*)(P_gate + (size_t)rowb * DM + (pn - 16) * 128);
;       const unsigned vo = (r4 * DM + cg) * 2;
;       FOR_M { unsigned vom = vo + (unsigned)(m * 16 * DM) * 2; OPQ(vom);
;         FOR_J {
; #pragma unroll
;           for (int n = 0; n < 2; ++n) {
;             const float v = acc[m][n][j];
;             ST16(gb_, vom + (unsigned)(j * DM + n * 16) * 2, f2bf(v * __builtin_amdgcn_rcpf(1.f + __expf(-v))));
;           }
;         } ENDM; }
.LBB0_197:
	s_andn2_b64 vcc, exec, s[0:1]
	s_cbranch_vccnz .LBB0_199
	s_add_u32 s0, s94, s56
	s_addc_u32 s1, s95, s57
	s_lshl_b32 s51, s74, 8
	s_add_u32 s0, s0, s51
	s_addc_u32 s1, s1, 0
	s_add_u32 s56, s0, 0x16f0f000
	s_addc_u32 s57, s1, 0
	v_mul_f32_e32 v254, 0xbfb8aa3b, v64
	v_mul_f32_e32 v255, 0xbfb8aa3b, v65
	v_exp_f32_e32 v254, v254
	v_exp_f32_e32 v255, v255
	v_add_f32_e32 v254, 1.0, v254
	v_add_f32_e32 v255, 1.0, v255
	v_rcp_f32_e32 v254, v254
	v_rcp_f32_e32 v255, v255
	v_mul_f32_e32 v64, v64, v254
	v_mul_f32_e32 v65, v65, v255
	v_mul_f32_e32 v254, 0xbfb8aa3b, v66
	v_mul_f32_e32 v255, 0xbfb8aa3b, v67
	v_exp_f32_e32 v254, v254
	v_exp_f32_e32 v255, v255
	v_add_f32_e32 v254, 1.0, v254
	v_add_f32_e32 v255, 1.0, v255
	v_rcp_f32_e32 v254, v254
	v_rcp_f32_e32 v255, v255
	v_mul_f32_e32 v66, v66, v254
	v_mul_f32_e32 v67, v67, v255
	v_cvt_pk_bf16_f32 v64, v64, v65
	v_cvt_pk_bf16_f32 v66, v66, v67
	global_store_short v174, v64, s[56:57]
	v_add_u32_e32 v251, 0x2000, v174
	global_store_short_d16_hi v251, v64, s[56:57]
	v_add_u32_e32 v252, 0x4000, v174
	global_store_short v252, v66, s[56:57]
	v_add_u32_e32 v253, 0x6000, v174
	global_store_short_d16_hi v253, v66, s[56:57]
	v_mul_f32_e32 v254, 0xbfb8aa3b, v68
	v_mul_f32_e32 v255, 0xbfb8aa3b, v69
	v_exp_f32_e32 v254, v254
	v_exp_f32_e32 v255, v255
	v_add_f32_e32 v254, 1.0, v254
	v_add_f32_e32 v255, 1.0, v255
	v_rcp_f32_e32 v254, v254
	v_rcp_f32_e32 v255, v255
	v_mul_f32_e32 v68, v68, v254
	v_mul_f32_e32 v69, v69, v255
	v_mul_f32_e32 v254, 0xbfb8aa3b, v70
	v_mul_f32_e32 v255, 0xbfb8aa3b, v71
	v_exp_f32_e32 v254, v254
	v_exp_f32_e32 v255, v255
	v_add_f32_e32 v254, 1.0, v254
	v_add_f32_e32 v255, 1.0, v255
	v_rcp_f32_e32 v254, v254
	v_rcp_f32_e32 v255, v255
	v_mul_f32_e32 v70, v70, v254
	v_mul_f32_e32 v71, v71, v255
	v_cvt_pk_bf16_f32 v68, v68, v69
	v_cvt_pk_bf16_f32 v70, v70, v71
	global_store_short v174, v68, s[56:57] offset:32
	global_store_short_d16_hi v251, v68, s[56:57] offset:32
	global_store_short v252, v70, s[56:57] offset:32
	global_store_short_d16_hi v253, v70, s[56:57] offset:32
	v_mul_f32_e32 v254, 0xbfb8aa3b, v72
	v_mul_f32_e32 v255, 0xbfb8aa3b, v73
	v_exp_f32_e32 v254, v254
	v_exp_f32_e32 v255, v255
	v_add_f32_e32 v254, 1.0, v254
	v_add_f32_e32 v255, 1.0, v255
	v_rcp_f32_e32 v254, v254
	v_rcp_f32_e32 v255, v255
	v_mul_f32_e32 v72, v72, v254
	v_mul_f32_e32 v73, v73, v255
	v_mul_f32_e32 v254, 0xbfb8aa3b, v74
	v_mul_f32_e32 v255, 0xbfb8aa3b, v75
	v_exp_f32_e32 v254, v254
	v_exp_f32_e32 v255, v255
	v_add_f32_e32 v254, 1.0, v254
	v_add_f32_e32 v255, 1.0, v255
	v_rcp_f32_e32 v254, v254
	v_rcp_f32_e32 v255, v255
	v_mul_f32_e32 v74, v74, v254
	v_mul_f32_e32 v75, v75, v255
	v_cvt_pk_bf16_f32 v72, v72, v73
	v_cvt_pk_bf16_f32 v74, v74, v75
	global_store_short v175, v72, s[56:57]
	v_add_u32_e32 v251, 0x2000, v175
	global_store_short_d16_hi v251, v72, s[56:57]
	v_add_u32_e32 v252, 0x4000, v175
	global_store_short v252, v74, s[56:57]
	v_add_u32_e32 v253, 0x6000, v175
	global_store_short_d16_hi v253, v74, s[56:57]
	v_mul_f32_e32 v254, 0xbfb8aa3b, v76
	v_mul_f32_e32 v255, 0xbfb8aa3b, v77
	v_exp_f32_e32 v254, v254
	v_exp_f32_e32 v255, v255
	v_add_f32_e32 v254, 1.0, v254
	v_add_f32_e32 v255, 1.0, v255
	v_rcp_f32_e32 v254, v254
	v_rcp_f32_e32 v255, v255
	v_mul_f32_e32 v76, v76, v254
	v_mul_f32_e32 v77, v77, v255
	v_mul_f32_e32 v254, 0xbfb8aa3b, v78
	v_mul_f32_e32 v255, 0xbfb8aa3b, v79
	v_exp_f32_e32 v254, v254
	v_exp_f32_e32 v255, v255
	v_add_f32_e32 v254, 1.0, v254
	v_add_f32_e32 v255, 1.0, v255
	v_rcp_f32_e32 v254, v254
	v_rcp_f32_e32 v255, v255
	v_mul_f32_e32 v78, v78, v254
	v_mul_f32_e32 v79, v79, v255
	v_cvt_pk_bf16_f32 v76, v76, v77
	v_cvt_pk_bf16_f32 v78, v78, v79
	global_store_short v175, v76, s[56:57] offset:32
	global_store_short_d16_hi v251, v76, s[56:57] offset:32
; __device__ __forceinline__ u16 f2bf(float f) { return (u16)(cvtpk(f, f) & 0xffffu); }
; #define FOR_M _Pragma("unroll") for (int m = 0; m < 4; ++m)
; #define FOR_J _Pragma("unroll") for (int j = 0; j < 4; ++j)
; #define OPQ(x) asm volatile("" : "+v"(x))
; #define ENDM __builtin_amdgcn_sched_barrier(0)
; template <int EPI>
; __device__ __forceinline__ void epi_quad(const Params& P, f32x4 (&acc)[4][2], int rowb, int pn, int wc, int fr, int fq,
;                                          const float* xres, float* yout, const float* rstd_q) {
;     ...
;     } else if (pn < 48) {
;       char* gb_ = (char*)(P_gate + (size_t)rowb * DM + (pn - 16) * 128);
;       const unsigned vo = (r4 * DM + cg) * 2;
;       FOR_M { unsigned vom = vo + (unsigned)(m * 16 * DM) * 2; OPQ(vom);
;         FOR_J {
; #pragma unroll
;           for (int n = 0; n < 2; ++n) {
;             const float v = acc[m][n][j];
;             ST16(gb_, vom + (unsigned)(j * DM + n * 16) * 2, f2bf(v * __builtin_amdgcn_rcpf(1.f + __expf(-v))));
;           }
;         } ENDM; }
	global_store_short v252, v78, s[56:57] offset:32
	global_store_short_d16_hi v253, v78, s[56:57] offset:32
	v_mul_f32_e32 v254, 0xbfb8aa3b, v80
	v_mul_f32_e32 v255, 0xbfb8aa3b, v81
	v_exp_f32_e32 v254, v254
	v_exp_f32_e32 v255, v255
	v_add_f32_e32 v254, 1.0, v254
	v_add_f32_e32 v255, 1.0, v255
	v_rcp_f32_e32 v254, v254
	v_rcp_f32_e32 v255, v255
	v_mul_f32_e32 v80, v80, v254
	v_mul_f32_e32 v81, v81, v255
	v_mul_f32_e32 v254, 0xbfb8aa3b, v82
	v_mul_f32_e32 v255, 0xbfb8aa3b, v83
	v_exp_f32_e32 v254, v254
	v_exp_f32_e32 v255, v255
	v_add_f32_e32 v254, 1.0, v254
	v_add_f32_e32 v255, 1.0, v255
	v_rcp_f32_e32 v254, v254
	v_rcp_f32_e32 v255, v255
	v_mul_f32_e32 v82, v82, v254
	v_mul_f32_e32 v83, v83, v255
	v_cvt_pk_bf16_f32 v80, v80, v81
	v_cvt_pk_bf16_f32 v82, v82, v83
	global_store_short v176, v80, s[56:57]
	v_add_u32_e32 v251, 0x2000, v176
	global_store_short_d16_hi v251, v80, s[56:57]
	v_add_u32_e32 v252, 0x4000, v176
	global_store_short v252, v82, s[56:57]
	v_add_u32_e32 v253, 0x6000, v176
	global_store_short_d16_hi v253, v82, s[56:57]
	v_mul_f32_e32 v254, 0xbfb8aa3b, v84
	v_mul_f32_e32 v255, 0xbfb8aa3b, v85
	v_exp_f32_e32 v254, v254
	v_exp_f32_e32 v255, v255
	v_add_f32_e32 v254, 1.0, v254
	v_add_f32_e32 v255, 1.0, v255
	v_rcp_f32_e32 v254, v254
	v_rcp_f32_e32 v255, v255
	v_mul_f32_e32 v84, v84, v254
	v_mul_f32_e32 v85, v85, v255
	v_mul_f32_e32 v254, 0xbfb8aa3b, v86
	v_mul_f32_e32 v255, 0xbfb8aa3b, v87
	v_exp_f32_e32 v254, v254
	v_exp_f32_e32 v255, v255
	v_add_f32_e32 v254, 1.0, v254
	v_add_f32_e32 v255, 1.0, v255
	v_rcp_f32_e32 v254, v254
	v_rcp_f32_e32 v255, v255
	v_mul_f32_e32 v86, v86, v254
	v_mul_f32_e32 v87, v87, v255
	v_cvt_pk_bf16_f32 v84, v84, v85
	v_cvt_pk_bf16_f32 v86, v86, v87
	global_store_short v176, v84, s[56:57] offset:32
	global_store_short_d16_hi v251, v84, s[56:57] offset:32
	global_store_short v252, v86, s[56:57] offset:32
	global_store_short_d16_hi v253, v86, s[56:57] offset:32
	v_mul_f32_e32 v254, 0xbfb8aa3b, v88
	v_mul_f32_e32 v255, 0xbfb8aa3b, v89
	v_exp_f32_e32 v254, v254
	v_exp_f32_e32 v255, v255
	v_add_f32_e32 v254, 1.0, v254
	v_add_f32_e32 v255, 1.0, v255
	v_rcp_f32_e32 v254, v254
	v_rcp_f32_e32 v255, v255
	v_mul_f32_e32 v88, v88, v254
	v_mul_f32_e32 v89, v89, v255
	v_mul_f32_e32 v254, 0xbfb8aa3b, v90
	v_mul_f32_e32 v255, 0xbfb8aa3b, v91
	v_exp_f32_e32 v254, v254
	v_exp_f32_e32 v255, v255
	v_add_f32_e32 v254, 1.0, v254
	v_add_f32_e32 v255, 1.0, v255
	v_rcp_f32_e32 v254, v254
	v_rcp_f32_e32 v255, v255
	v_mul_f32_e32 v90, v90, v254
	v_mul_f32_e32 v91, v91, v255
	v_cvt_pk_bf16_f32 v88, v88, v89
	v_cvt_pk_bf16_f32 v90, v90, v91
	global_store_short v177, v88, s[56:57]
	v_add_u32_e32 v251, 0x2000, v177
	global_store_short_d16_hi v251, v88, s[56:57]
	v_add_u32_e32 v252, 0x4000, v177
	global_store_short v252, v90, s[56:57]
	v_add_u32_e32 v253, 0x6000, v177
	global_store_short_d16_hi v253, v90, s[56:57]
	v_mul_f32_e32 v254, 0xbfb8aa3b, v92
	v_mul_f32_e32 v255, 0xbfb8aa3b, v93
	v_exp_f32_e32 v254, v254
	v_exp_f32_e32 v255, v255
	v_add_f32_e32 v254, 1.0, v254
	v_add_f32_e32 v255, 1.0, v255
	v_rcp_f32_e32 v254, v254
	v_rcp_f32_e32 v255, v255
	v_mul_f32_e32 v92, v92, v254
	v_mul_f32_e32 v93, v93, v255
	v_mul_f32_e32 v254, 0xbfb8aa3b, v94
	v_mul_f32_e32 v255, 0xbfb8aa3b, v95
	v_exp_f32_e32 v254, v254
	v_exp_f32_e32 v255, v255
	v_add_f32_e32 v254, 1.0, v254
	v_add_f32_e32 v255, 1.0, v255
	v_rcp_f32_e32 v254, v254
	v_rcp_f32_e32 v255, v255
	v_mul_f32_e32 v94, v94, v254
	v_mul_f32_e32 v95, v95, v255
	v_cvt_pk_bf16_f32 v92, v92, v93
	v_cvt_pk_bf16_f32 v94, v94, v95
	global_store_short v177, v92, s[56:57] offset:32
	global_store_short_d16_hi v251, v92, s[56:57] offset:32
	global_store_short v252, v94, s[56:57] offset:32
	global_store_short_d16_hi v253, v94, s[56:57] offset:32

; __device__ __forceinline__ u16 f2bf(float f) { return (u16)(cvtpk(f, f) & 0xffffu); }
; #define FOR_M _Pragma("unroll") for (int m = 0; m < 4; ++m)
; #define FOR_J _Pragma("unroll") for (int j = 0; j < 4; ++j)
; #define OPQ(x) asm volatile("" : "+v"(x))
; #define ENDM __builtin_amdgcn_sched_barrier(0)
; template <int EPI>
; __device__ __forceinline__ void epi_quad(const Params& P, f32x4 (&acc)[4][2], int rowb, int pn, int wc, int fr, int fq,
;                                          const float* xres, float* yout, const float* rstd_q) {
;     ...
;     } else if (pn < 16) {
;       char* vb_ = (char*)(P_vA + ((size_t)(b * 4 + (pn - 12)) * SEQ + pos0) * 128);
;       const unsigned vo = (r4 * 128 + cg) * 2;
;       FOR_M { unsigned vom = vo + (unsigned)(m * 16 * 128) * 2; OPQ(vom);
;         FOR_J {
; #pragma unroll
;           for (int n = 0; n < 2; ++n) ST16(vb_, vom + (unsigned)(j * 128 + n * 16) * 2, f2bf(acc[m][n][j]));
;         } ENDM; }
.LBB0_200:
	s_andn2_b64 vcc, exec, s[0:1]
	s_cbranch_vccnz .LBB0_202
	s_add_i32 s0, s81, s74
	s_ashr_i32 s1, s0, 31
	s_lshl_b64 s[0:1], s[0:1], 20
	s_add_u32 s0, s86, s0
	s_addc_u32 s1, s87, s1
	s_lshl_b32 s51, s80, 1
	s_add_u32 s56, s0, s51
	s_addc_u32 s57, s1, 0
	v_mov_b32_e32 v194, v128
	v_cvt_pk_bf16_f32 v64, v64, v65
	v_cvt_pk_bf16_f32 v66, v66, v67
	global_store_short v171, v64, s[56:57]
	global_store_short_d16_hi v171, v64, s[56:57] offset:256
	global_store_short v171, v66, s[56:57] offset:512
	global_store_short_d16_hi v171, v66, s[56:57] offset:768
	v_cvt_pk_bf16_f32 v68, v68, v69
	v_cvt_pk_bf16_f32 v70, v70, v71
	global_store_short v171, v68, s[56:57] offset:32
	global_store_short_d16_hi v171, v68, s[56:57] offset:288
	global_store_short v171, v70, s[56:57] offset:544
	global_store_short_d16_hi v171, v70, s[56:57] offset:800
	v_cvt_pk_bf16_f32 v72, v72, v73
	v_cvt_pk_bf16_f32 v74, v74, v75
	global_store_short v172, v72, s[56:57]
	global_store_short_d16_hi v172, v72, s[56:57] offset:256
	global_store_short v172, v74, s[56:57] offset:512
	global_store_short_d16_hi v172, v74, s[56:57] offset:768
	v_cvt_pk_bf16_f32 v76, v76, v77
	v_cvt_pk_bf16_f32 v78, v78, v79
	global_store_short v172, v76, s[56:57] offset:32
	global_store_short_d16_hi v172, v76, s[56:57] offset:288
	global_store_short v172, v78, s[56:57] offset:544
	global_store_short_d16_hi v172, v78, s[56:57] offset:800
	v_cvt_pk_bf16_f32 v80, v80, v81
	v_cvt_pk_bf16_f32 v82, v82, v83
	global_store_short v173, v80, s[56:57]
	global_store_short_d16_hi v173, v80, s[56:57] offset:256
	global_store_short v173, v82, s[56:57] offset:512
	global_store_short_d16_hi v173, v82, s[56:57] offset:768
	v_cvt_pk_bf16_f32 v84, v84, v85
	v_cvt_pk_bf16_f32 v86, v86, v87
	global_store_short v173, v84, s[56:57] offset:32
	global_store_short_d16_hi v173, v84, s[56:57] offset:288
	global_store_short v173, v86, s[56:57] offset:544
	global_store_short_d16_hi v173, v86, s[56:57] offset:800
	v_cvt_pk_bf16_f32 v88, v88, v89
	v_cvt_pk_bf16_f32 v90, v90, v91
	global_store_short v194, v88, s[56:57]
	global_store_short_d16_hi v194, v88, s[56:57] offset:256
	global_store_short v194, v90, s[56:57] offset:512
	global_store_short_d16_hi v194, v90, s[56:57] offset:768
	v_cvt_pk_bf16_f32 v92, v92, v93
	v_cvt_pk_bf16_f32 v94, v94, v95
	global_store_short v194, v92, s[56:57] offset:32
	global_store_short_d16_hi v194, v92, s[56:57] offset:288
	global_store_short v194, v94, s[56:57] offset:544
	global_store_short_d16_hi v194, v94, s[56:57] offset:800

; __device__ __forceinline__ u16 f2bf(float f) { return (u16)(cvtpk(f, f) & 0xffffu); }
; #define FOR_M _Pragma("unroll") for (int m = 0; m < 4; ++m)
; #define FOR_J _Pragma("unroll") for (int j = 0; j < 4; ++j)
; #define OPQ(x) asm volatile("" : "+v"(x))
; #define ENDM __builtin_amdgcn_sched_barrier(0)
; template <int EPI>
; __device__ __forceinline__ void epi_quad(const Params& P, f32x4 (&acc)[4][2], int rowb, int pn, int wc, int fr, int fq,
;                                          const float* xres, float* yout, const float* rstd_q) {
;     ...
;     } else if (pn < 48) {
;       char* gb_ = (char*)(P_gate + (size_t)rowb * DM + (pn - 16) * 128);
;       const unsigned vo = (r4 * DM + cg) * 2;
;       FOR_M { unsigned vom = vo + (unsigned)(m * 16 * DM) * 2; OPQ(vom);
;         FOR_J {
; #pragma unroll
;           for (int n = 0; n < 2; ++n) {
;             const float v = acc[m][n][j];
;             ST16(gb_, vom + (unsigned)(j * DM + n * 16) * 2, f2bf(v * __builtin_amdgcn_rcpf(1.f + __expf(-v))));
;           }
;         } ENDM; }
.LBB0_245:
	s_andn2_b64 vcc, exec, s[0:1]
	s_cbranch_vccnz .LBB0_247
	s_add_u32 s52, s94, s50
	s_addc_u32 s53, s95, s51
	s_lshl_b64 s[0:1], s[48:49], 1
	s_add_u32 s0, s52, s0
	s_addc_u32 s1, s53, s1
	s_add_u32 s52, s0, 0x16f0f000
	s_addc_u32 s53, s1, 0
	v_mul_f32_e32 v254, 0xbfb8aa3b, v32
	v_mul_f32_e32 v255, 0xbfb8aa3b, v33
	v_exp_f32_e32 v254, v254
	v_exp_f32_e32 v255, v255
	v_add_f32_e32 v254, 1.0, v254
	v_add_f32_e32 v255, 1.0, v255
	v_rcp_f32_e32 v254, v254
	v_rcp_f32_e32 v255, v255
	v_mul_f32_e32 v32, v32, v254
	v_mul_f32_e32 v33, v33, v255
	v_mul_f32_e32 v254, 0xbfb8aa3b, v34
	v_mul_f32_e32 v255, 0xbfb8aa3b, v35
	v_exp_f32_e32 v254, v254
	v_exp_f32_e32 v255, v255
	v_add_f32_e32 v254, 1.0, v254
	v_add_f32_e32 v255, 1.0, v255
	v_rcp_f32_e32 v254, v254
	v_rcp_f32_e32 v255, v255
	v_mul_f32_e32 v34, v34, v254
	v_mul_f32_e32 v35, v35, v255
	v_cvt_pk_bf16_f32 v32, v32, v33
	v_cvt_pk_bf16_f32 v34, v34, v35
	global_store_short v174, v32, s[52:53]
	v_add_u32_e32 v251, 0x2000, v174
	global_store_short_d16_hi v251, v32, s[52:53]
	v_add_u32_e32 v252, 0x4000, v174
	global_store_short v252, v34, s[52:53]
	v_add_u32_e32 v253, 0x6000, v174
	global_store_short_d16_hi v253, v34, s[52:53]
	v_mul_f32_e32 v254, 0xbfb8aa3b, v36
	v_mul_f32_e32 v255, 0xbfb8aa3b, v37
	v_exp_f32_e32 v254, v254
	v_exp_f32_e32 v255, v255
	v_add_f32_e32 v254, 1.0, v254
	v_add_f32_e32 v255, 1.0, v255
	v_rcp_f32_e32 v254, v254
	v_rcp_f32_e32 v255, v255
	v_mul_f32_e32 v36, v36, v254
	v_mul_f32_e32 v37, v37, v255
	v_mul_f32_e32 v254, 0xbfb8aa3b, v38
	v_mul_f32_e32 v255, 0xbfb8aa3b, v39
	v_exp_f32_e32 v254, v254
	v_exp_f32_e32 v255, v255
	v_add_f32_e32 v254, 1.0, v254
	v_add_f32_e32 v255, 1.0, v255
	v_rcp_f32_e32 v254, v254
	v_rcp_f32_e32 v255, v255
	v_mul_f32_e32 v38, v38, v254
	v_mul_f32_e32 v39, v39, v255
	v_cvt_pk_bf16_f32 v36, v36, v37
	v_cvt_pk_bf16_f32 v38, v38, v39
	global_store_short v174, v36, s[52:53] offset:32
	global_store_short_d16_hi v251, v36, s[52:53] offset:32
	global_store_short v252, v38, s[52:53] offset:32
	global_store_short_d16_hi v253, v38, s[52:53] offset:32
	v_mul_f32_e32 v254, 0xbfb8aa3b, v40
	v_mul_f32_e32 v255, 0xbfb8aa3b, v41
	v_exp_f32_e32 v254, v254
	v_exp_f32_e32 v255, v255
	v_add_f32_e32 v254, 1.0, v254
	v_add_f32_e32 v255, 1.0, v255
	v_rcp_f32_e32 v254, v254
	v_rcp_f32_e32 v255, v255
	v_mul_f32_e32 v40, v40, v254
	v_mul_f32_e32 v41, v41, v255
	v_mul_f32_e32 v254, 0xbfb8aa3b, v42
	v_mul_f32_e32 v255, 0xbfb8aa3b, v43
	v_exp_f32_e32 v254, v254
	v_exp_f32_e32 v255, v255
	v_add_f32_e32 v254, 1.0, v254
	v_add_f32_e32 v255, 1.0, v255
	v_rcp_f32_e32 v254, v254
	v_rcp_f32_e32 v255, v255
	v_mul_f32_e32 v42, v42, v254
	v_mul_f32_e32 v43, v43, v255
	v_cvt_pk_bf16_f32 v40, v40, v41
	v_cvt_pk_bf16_f32 v42, v42, v43
	global_store_short v175, v40, s[52:53]
	v_add_u32_e32 v251, 0x2000, v175
	global_store_short_d16_hi v251, v40, s[52:53]
	v_add_u32_e32 v252, 0x4000, v175
	global_store_short v252, v42, s[52:53]
	v_add_u32_e32 v253, 0x6000, v175
	global_store_short_d16_hi v253, v42, s[52:53]
	v_mul_f32_e32 v254, 0xbfb8aa3b, v44
	v_mul_f32_e32 v255, 0xbfb8aa3b, v45
	v_exp_f32_e32 v254, v254
	v_exp_f32_e32 v255, v255
	v_add_f32_e32 v254, 1.0, v254
	v_add_f32_e32 v255, 1.0, v255
	v_rcp_f32_e32 v254, v254
	v_rcp_f32_e32 v255, v255
	v_mul_f32_e32 v44, v44, v254
	v_mul_f32_e32 v45, v45, v255
	v_mul_f32_e32 v254, 0xbfb8aa3b, v46
	v_mul_f32_e32 v255, 0xbfb8aa3b, v47
	v_exp_f32_e32 v254, v254
	v_exp_f32_e32 v255, v255
	v_add_f32_e32 v254, 1.0, v254
	v_add_f32_e32 v255, 1.0, v255
	v_rcp_f32_e32 v254, v254
	v_rcp_f32_e32 v255, v255
	v_mul_f32_e32 v46, v46, v254
	v_mul_f32_e32 v47, v47, v255
	v_cvt_pk_bf16_f32 v44, v44, v45
	v_cvt_pk_bf16_f32 v46, v46, v47
	global_store_short v175, v44, s[52:53] offset:32
	global_store_short_d16_hi v251, v44, s[52:53] offset:32
; __device__ __forceinline__ u16 f2bf(float f) { return (u16)(cvtpk(f, f) & 0xffffu); }
; #define FOR_M _Pragma("unroll") for (int m = 0; m < 4; ++m)
; #define FOR_J _Pragma("unroll") for (int j = 0; j < 4; ++j)
; #define OPQ(x) asm volatile("" : "+v"(x))
; #define ENDM __builtin_amdgcn_sched_barrier(0)
; template <int EPI>
; __device__ __forceinline__ void epi_quad(const Params& P, f32x4 (&acc)[4][2], int rowb, int pn, int wc, int fr, int fq,
;                                          const float* xres, float* yout, const float* rstd_q) {
;     ...
;     } else if (pn < 48) {
;       char* gb_ = (char*)(P_gate + (size_t)rowb * DM + (pn - 16) * 128);
;       const unsigned vo = (r4 * DM + cg) * 2;
;       FOR_M { unsigned vom = vo + (unsigned)(m * 16 * DM) * 2; OPQ(vom);
;         FOR_J {
; #pragma unroll
;           for (int n = 0; n < 2; ++n) {
;             const float v = acc[m][n][j];
;             ST16(gb_, vom + (unsigned)(j * DM + n * 16) * 2, f2bf(v * __builtin_amdgcn_rcpf(1.f + __expf(-v))));
;           }
;         } ENDM; }
	global_store_short v252, v46, s[52:53] offset:32
	global_store_short_d16_hi v253, v46, s[52:53] offset:32
	v_mul_f32_e32 v254, 0xbfb8aa3b, v48
	v_mul_f32_e32 v255, 0xbfb8aa3b, v49
	v_exp_f32_e32 v254, v254
	v_exp_f32_e32 v255, v255
	v_add_f32_e32 v254, 1.0, v254
	v_add_f32_e32 v255, 1.0, v255
	v_rcp_f32_e32 v254, v254
	v_rcp_f32_e32 v255, v255
	v_mul_f32_e32 v48, v48, v254
	v_mul_f32_e32 v49, v49, v255
	v_mul_f32_e32 v254, 0xbfb8aa3b, v50
	v_mul_f32_e32 v255, 0xbfb8aa3b, v51
	v_exp_f32_e32 v254, v254
	v_exp_f32_e32 v255, v255
	v_add_f32_e32 v254, 1.0, v254
	v_add_f32_e32 v255, 1.0, v255
	v_rcp_f32_e32 v254, v254
	v_rcp_f32_e32 v255, v255
	v_mul_f32_e32 v50, v50, v254
	v_mul_f32_e32 v51, v51, v255
	v_cvt_pk_bf16_f32 v48, v48, v49
	v_cvt_pk_bf16_f32 v50, v50, v51
	global_store_short v176, v48, s[52:53]
	v_add_u32_e32 v251, 0x2000, v176
	global_store_short_d16_hi v251, v48, s[52:53]
	v_add_u32_e32 v252, 0x4000, v176
	global_store_short v252, v50, s[52:53]
	v_add_u32_e32 v253, 0x6000, v176
	global_store_short_d16_hi v253, v50, s[52:53]
	v_mul_f32_e32 v254, 0xbfb8aa3b, v52
	v_mul_f32_e32 v255, 0xbfb8aa3b, v53
	v_exp_f32_e32 v254, v254
	v_exp_f32_e32 v255, v255
	v_add_f32_e32 v254, 1.0, v254
	v_add_f32_e32 v255, 1.0, v255
	v_rcp_f32_e32 v254, v254
	v_rcp_f32_e32 v255, v255
	v_mul_f32_e32 v52, v52, v254
	v_mul_f32_e32 v53, v53, v255
	v_mul_f32_e32 v254, 0xbfb8aa3b, v54
	v_mul_f32_e32 v255, 0xbfb8aa3b, v55
	v_exp_f32_e32 v254, v254
	v_exp_f32_e32 v255, v255
	v_add_f32_e32 v254, 1.0, v254
	v_add_f32_e32 v255, 1.0, v255
	v_rcp_f32_e32 v254, v254
	v_rcp_f32_e32 v255, v255
	v_mul_f32_e32 v54, v54, v254
	v_mul_f32_e32 v55, v55, v255
	v_cvt_pk_bf16_f32 v52, v52, v53
	v_cvt_pk_bf16_f32 v54, v54, v55
	global_store_short v176, v52, s[52:53] offset:32
	global_store_short_d16_hi v251, v52, s[52:53] offset:32
	global_store_short v252, v54, s[52:53] offset:32
	global_store_short_d16_hi v253, v54, s[52:53] offset:32
	v_mul_f32_e32 v254, 0xbfb8aa3b, v56
	v_mul_f32_e32 v255, 0xbfb8aa3b, v57
	v_exp_f32_e32 v254, v254
	v_exp_f32_e32 v255, v255
	v_add_f32_e32 v254, 1.0, v254
	v_add_f32_e32 v255, 1.0, v255
	v_rcp_f32_e32 v254, v254
	v_rcp_f32_e32 v255, v255
	v_mul_f32_e32 v56, v56, v254
	v_mul_f32_e32 v57, v57, v255
	v_mul_f32_e32 v254, 0xbfb8aa3b, v58
	v_mul_f32_e32 v255, 0xbfb8aa3b, v59
	v_exp_f32_e32 v254, v254
	v_exp_f32_e32 v255, v255
	v_add_f32_e32 v254, 1.0, v254
	v_add_f32_e32 v255, 1.0, v255
	v_rcp_f32_e32 v254, v254
	v_rcp_f32_e32 v255, v255
	v_mul_f32_e32 v58, v58, v254
	v_mul_f32_e32 v59, v59, v255
	v_cvt_pk_bf16_f32 v56, v56, v57
	v_cvt_pk_bf16_f32 v58, v58, v59
	global_store_short v177, v56, s[52:53]
	v_add_u32_e32 v251, 0x2000, v177
	global_store_short_d16_hi v251, v56, s[52:53]
	v_add_u32_e32 v252, 0x4000, v177
	global_store_short v252, v58, s[52:53]
	v_add_u32_e32 v253, 0x6000, v177
	global_store_short_d16_hi v253, v58, s[52:53]
	v_mul_f32_e32 v254, 0xbfb8aa3b, v60
	v_mul_f32_e32 v255, 0xbfb8aa3b, v61
	v_exp_f32_e32 v254, v254
	v_exp_f32_e32 v255, v255
	v_add_f32_e32 v254, 1.0, v254
	v_add_f32_e32 v255, 1.0, v255
	v_rcp_f32_e32 v254, v254
	v_rcp_f32_e32 v255, v255
	v_mul_f32_e32 v60, v60, v254
	v_mul_f32_e32 v61, v61, v255
	v_mul_f32_e32 v254, 0xbfb8aa3b, v62
	v_mul_f32_e32 v255, 0xbfb8aa3b, v63
	v_exp_f32_e32 v254, v254
	v_exp_f32_e32 v255, v255
	v_add_f32_e32 v254, 1.0, v254
	v_add_f32_e32 v255, 1.0, v255
	v_rcp_f32_e32 v254, v254
	v_rcp_f32_e32 v255, v255
	v_mul_f32_e32 v62, v62, v254
	v_mul_f32_e32 v63, v63, v255
	v_cvt_pk_bf16_f32 v60, v60, v61
	v_cvt_pk_bf16_f32 v62, v62, v63
	global_store_short v177, v60, s[52:53] offset:32
	global_store_short_d16_hi v251, v60, s[52:53] offset:32
	global_store_short v252, v62, s[52:53] offset:32
	global_store_short_d16_hi v253, v62, s[52:53] offset:32

; __device__ __forceinline__ u16 f2bf(float f) { return (u16)(cvtpk(f, f) & 0xffffu); }
; #define FOR_M _Pragma("unroll") for (int m = 0; m < 4; ++m)
; #define FOR_J _Pragma("unroll") for (int j = 0; j < 4; ++j)
; #define OPQ(x) asm volatile("" : "+v"(x))
; #define ENDM __builtin_amdgcn_sched_barrier(0)
; template <int EPI>
; __device__ __forceinline__ void epi_quad(const Params& P, f32x4 (&acc)[4][2], int rowb, int pn, int wc, int fr, int fq,
;                                          const float* xres, float* yout, const float* rstd_q) {
;     ...
;     } else if (pn < 16) {
;       char* vb_ = (char*)(P_vA + ((size_t)(b * 4 + (pn - 12)) * SEQ + pos0) * 128);
;       const unsigned vo = (r4 * 128 + cg) * 2;
;       FOR_M { unsigned vom = vo + (unsigned)(m * 16 * 128) * 2; OPQ(vom);
;         FOR_J {
; #pragma unroll
;           for (int n = 0; n < 2; ++n) ST16(vb_, vom + (unsigned)(j * 128 + n * 16) * 2, f2bf(acc[m][n][j]));
;         } ENDM; }
.LBB0_248:
	s_andn2_b64 vcc, exec, s[0:1]
	s_cbranch_vccnz .LBB0_250
	s_add_i32 s0, s79, s73
	s_ashr_i32 s1, s0, 31
	s_lshl_b64 s[0:1], s[0:1], 20
	s_add_u32 s0, s86, s0
	s_addc_u32 s1, s87, s1
	s_lshl_b32 s52, s78, 1
	s_add_u32 s52, s0, s52
	s_addc_u32 s53, s1, 0
	v_mov_b32_e32 v187, v128
	v_cvt_pk_bf16_f32 v32, v32, v33
	v_cvt_pk_bf16_f32 v34, v34, v35
	global_store_short v171, v32, s[52:53]
	global_store_short_d16_hi v171, v32, s[52:53] offset:256
	global_store_short v171, v34, s[52:53] offset:512
	global_store_short_d16_hi v171, v34, s[52:53] offset:768
	v_cvt_pk_bf16_f32 v36, v36, v37
	v_cvt_pk_bf16_f32 v38, v38, v39
	global_store_short v171, v36, s[52:53] offset:32
	global_store_short_d16_hi v171, v36, s[52:53] offset:288
	global_store_short v171, v38, s[52:53] offset:544
	global_store_short_d16_hi v171, v38, s[52:53] offset:800
	v_cvt_pk_bf16_f32 v40, v40, v41
	v_cvt_pk_bf16_f32 v42, v42, v43
	global_store_short v172, v40, s[52:53]
	global_store_short_d16_hi v172, v40, s[52:53] offset:256
	global_store_short v172, v42, s[52:53] offset:512
	global_store_short_d16_hi v172, v42, s[52:53] offset:768
	v_cvt_pk_bf16_f32 v44, v44, v45
	v_cvt_pk_bf16_f32 v46, v46, v47
	global_store_short v172, v44, s[52:53] offset:32
	global_store_short_d16_hi v172, v44, s[52:53] offset:288
	global_store_short v172, v46, s[52:53] offset:544
	global_store_short_d16_hi v172, v46, s[52:53] offset:800
	v_cvt_pk_bf16_f32 v48, v48, v49
	v_cvt_pk_bf16_f32 v50, v50, v51
	global_store_short v173, v48, s[52:53]
	global_store_short_d16_hi v173, v48, s[52:53] offset:256
	global_store_short v173, v50, s[52:53] offset:512
	global_store_short_d16_hi v173, v50, s[52:53] offset:768
	v_cvt_pk_bf16_f32 v52, v52, v53
	v_cvt_pk_bf16_f32 v54, v54, v55
	global_store_short v173, v52, s[52:53] offset:32
	global_store_short_d16_hi v173, v52, s[52:53] offset:288
	global_store_short v173, v54, s[52:53] offset:544
	global_store_short_d16_hi v173, v54, s[52:53] offset:800
	v_cvt_pk_bf16_f32 v56, v56, v57
	v_cvt_pk_bf16_f32 v58, v58, v59
	global_store_short v187, v56, s[52:53]
	global_store_short_d16_hi v187, v56, s[52:53] offset:256
	global_store_short v187, v58, s[52:53] offset:512
	global_store_short_d16_hi v187, v58, s[52:53] offset:768
	v_cvt_pk_bf16_f32 v60, v60, v61
	v_cvt_pk_bf16_f32 v62, v62, v63
	global_store_short v187, v60, s[52:53] offset:32
	global_store_short_d16_hi v187, v60, s[52:53] offset:288
	global_store_short v187, v62, s[52:53] offset:544
	global_store_short_d16_hi v187, v62, s[52:53] offset:800

; __device__ __forceinline__ u16 f2bf(float f) { return (u16)(cvtpk(f, f) & 0xffffu); }
; #define FOR_M _Pragma("unroll") for (int m = 0; m < 4; ++m)
; #define FOR_J _Pragma("unroll") for (int j = 0; j < 4; ++j)
; #define OPQ(x) asm volatile("" : "+v"(x))
; #define ENDM __builtin_amdgcn_sched_barrier(0)
; template <int EPI>
; __device__ __forceinline__ void epi_quad(const Params& P, f32x4 (&acc)[4][2], int rowb, int pn, int wc, int fr, int fq,
;                                          const float* xres, float* yout, const float* rstd_q) {
;     ...
;     } else if (pn < 48) {
;       char* gb_ = (char*)(P_gate + (size_t)rowb * DM + (pn - 16) * 128);
;       const unsigned vo = (r4 * DM + cg) * 2;
;       FOR_M { unsigned vom = vo + (unsigned)(m * 16 * DM) * 2; OPQ(vom);
;         FOR_J {
; #pragma unroll
;           for (int n = 0; n < 2; ++n) {
;             const float v = acc[m][n][j];
;             ST16(gb_, vom + (unsigned)(j * DM + n * 16) * 2, f2bf(v * __builtin_amdgcn_rcpf(1.f + __expf(-v))));
;           }
;         } ENDM; }
.LBB0_261:
	s_andn2_b64 vcc, exec, s[0:1]
	s_cbranch_vccnz .LBB0_263
	s_add_u32 s0, s94, s50
	s_addc_u32 s1, s95, s51
	s_lshl_b32 s47, s74, 8
	s_add_u32 s0, s0, s47
	s_addc_u32 s1, s1, 0
	s_add_u32 s48, s0, 0x16f0f000
	s_addc_u32 s49, s1, 0
	v_mul_f32_e32 v254, 0xbfb8aa3b, v0
	v_mul_f32_e32 v255, 0xbfb8aa3b, v1
	v_exp_f32_e32 v254, v254
	v_exp_f32_e32 v255, v255
	v_add_f32_e32 v254, 1.0, v254
	v_add_f32_e32 v255, 1.0, v255
	v_rcp_f32_e32 v254, v254
	v_rcp_f32_e32 v255, v255
	v_mul_f32_e32 v0, v0, v254
	v_mul_f32_e32 v1, v1, v255
	v_mul_f32_e32 v254, 0xbfb8aa3b, v2
	v_mul_f32_e32 v255, 0xbfb8aa3b, v3
	v_exp_f32_e32 v254, v254
	v_exp_f32_e32 v255, v255
	v_add_f32_e32 v254, 1.0, v254
	v_add_f32_e32 v255, 1.0, v255
	v_rcp_f32_e32 v254, v254
	v_rcp_f32_e32 v255, v255
	v_mul_f32_e32 v2, v2, v254
	v_mul_f32_e32 v3, v3, v255
	v_cvt_pk_bf16_f32 v0, v0, v1
	v_cvt_pk_bf16_f32 v2, v2, v3
	global_store_short v174, v0, s[48:49]
	v_add_u32_e32 v251, 0x2000, v174
	global_store_short_d16_hi v251, v0, s[48:49]
	v_add_u32_e32 v252, 0x4000, v174
	global_store_short v252, v2, s[48:49]
	v_add_u32_e32 v253, 0x6000, v174
	global_store_short_d16_hi v253, v2, s[48:49]
	v_mul_f32_e32 v254, 0xbfb8aa3b, v4
	v_mul_f32_e32 v255, 0xbfb8aa3b, v5
	v_exp_f32_e32 v254, v254
	v_exp_f32_e32 v255, v255
	v_add_f32_e32 v254, 1.0, v254
	v_add_f32_e32 v255, 1.0, v255
	v_rcp_f32_e32 v254, v254
	v_rcp_f32_e32 v255, v255
	v_mul_f32_e32 v4, v4, v254
	v_mul_f32_e32 v5, v5, v255
	v_mul_f32_e32 v254, 0xbfb8aa3b, v6
	v_mul_f32_e32 v255, 0xbfb8aa3b, v7
	v_exp_f32_e32 v254, v254
	v_exp_f32_e32 v255, v255
	v_add_f32_e32 v254, 1.0, v254
	v_add_f32_e32 v255, 1.0, v255
	v_rcp_f32_e32 v254, v254
	v_rcp_f32_e32 v255, v255
	v_mul_f32_e32 v6, v6, v254
	v_mul_f32_e32 v7, v7, v255
	v_cvt_pk_bf16_f32 v4, v4, v5
	v_cvt_pk_bf16_f32 v6, v6, v7
	global_store_short v174, v4, s[48:49] offset:32
	global_store_short_d16_hi v251, v4, s[48:49] offset:32
	global_store_short v252, v6, s[48:49] offset:32
	global_store_short_d16_hi v253, v6, s[48:49] offset:32
	v_mul_f32_e32 v254, 0xbfb8aa3b, v8
	v_mul_f32_e32 v255, 0xbfb8aa3b, v9
	v_exp_f32_e32 v254, v254
	v_exp_f32_e32 v255, v255
	v_add_f32_e32 v254, 1.0, v254
	v_add_f32_e32 v255, 1.0, v255
	v_rcp_f32_e32 v254, v254
	v_rcp_f32_e32 v255, v255
	v_mul_f32_e32 v8, v8, v254
	v_mul_f32_e32 v9, v9, v255
	v_mul_f32_e32 v254, 0xbfb8aa3b, v10
	v_mul_f32_e32 v255, 0xbfb8aa3b, v11
	v_exp_f32_e32 v254, v254
	v_exp_f32_e32 v255, v255
	v_add_f32_e32 v254, 1.0, v254
	v_add_f32_e32 v255, 1.0, v255
	v_rcp_f32_e32 v254, v254
	v_rcp_f32_e32 v255, v255
	v_mul_f32_e32 v10, v10, v254
	v_mul_f32_e32 v11, v11, v255
	v_cvt_pk_bf16_f32 v8, v8, v9
	v_cvt_pk_bf16_f32 v10, v10, v11
	global_store_short v175, v8, s[48:49]
	v_add_u32_e32 v251, 0x2000, v175
	global_store_short_d16_hi v251, v8, s[48:49]
	v_add_u32_e32 v252, 0x4000, v175
	global_store_short v252, v10, s[48:49]
	v_add_u32_e32 v253, 0x6000, v175
	global_store_short_d16_hi v253, v10, s[48:49]
	v_mul_f32_e32 v254, 0xbfb8aa3b, v12
	v_mul_f32_e32 v255, 0xbfb8aa3b, v13
	v_exp_f32_e32 v254, v254
	v_exp_f32_e32 v255, v255
	v_add_f32_e32 v254, 1.0, v254
	v_add_f32_e32 v255, 1.0, v255
	v_rcp_f32_e32 v254, v254
	v_rcp_f32_e32 v255, v255
	v_mul_f32_e32 v12, v12, v254
	v_mul_f32_e32 v13, v13, v255
	v_mul_f32_e32 v254, 0xbfb8aa3b, v14
	v_mul_f32_e32 v255, 0xbfb8aa3b, v15
	v_exp_f32_e32 v254, v254
	v_exp_f32_e32 v255, v255
	v_add_f32_e32 v254, 1.0, v254
	v_add_f32_e32 v255, 1.0, v255
	v_rcp_f32_e32 v254, v254
	v_rcp_f32_e32 v255, v255
	v_mul_f32_e32 v14, v14, v254
	v_mul_f32_e32 v15, v15, v255
	v_cvt_pk_bf16_f32 v12, v12, v13
	v_cvt_pk_bf16_f32 v14, v14, v15
	global_store_short v175, v12, s[48:49] offset:32
	global_store_short_d16_hi v251, v12, s[48:49] offset:32
; __device__ __forceinline__ u16 f2bf(float f) { return (u16)(cvtpk(f, f) & 0xffffu); }
; #define FOR_M _Pragma("unroll") for (int m = 0; m < 4; ++m)
; #define FOR_J _Pragma("unroll") for (int j = 0; j < 4; ++j)
; #define OPQ(x) asm volatile("" : "+v"(x))
; #define ENDM __builtin_amdgcn_sched_barrier(0)
; template <int EPI>
; __device__ __forceinline__ void epi_quad(const Params& P, f32x4 (&acc)[4][2], int rowb, int pn, int wc, int fr, int fq,
;                                          const float* xres, float* yout, const float* rstd_q) {
;     ...
;     } else if (pn < 48) {
;       char* gb_ = (char*)(P_gate + (size_t)rowb * DM + (pn - 16) * 128);
;       const unsigned vo = (r4 * DM + cg) * 2;
;       FOR_M { unsigned vom = vo + (unsigned)(m * 16 * DM) * 2; OPQ(vom);
;         FOR_J {
; #pragma unroll
;           for (int n = 0; n < 2; ++n) {
;             const float v = acc[m][n][j];
;             ST16(gb_, vom + (unsigned)(j * DM + n * 16) * 2, f2bf(v * __builtin_amdgcn_rcpf(1.f + __expf(-v))));
;           }
;         } ENDM; }
	global_store_short v252, v14, s[48:49] offset:32
	global_store_short_d16_hi v253, v14, s[48:49] offset:32
	v_mul_f32_e32 v254, 0xbfb8aa3b, v16
	v_mul_f32_e32 v255, 0xbfb8aa3b, v17
	v_exp_f32_e32 v254, v254
	v_exp_f32_e32 v255, v255
	v_add_f32_e32 v254, 1.0, v254
	v_add_f32_e32 v255, 1.0, v255
	v_rcp_f32_e32 v254, v254
	v_rcp_f32_e32 v255, v255
	v_mul_f32_e32 v16, v16, v254
	v_mul_f32_e32 v17, v17, v255
	v_mul_f32_e32 v254, 0xbfb8aa3b, v18
	v_mul_f32_e32 v255, 0xbfb8aa3b, v19
	v_exp_f32_e32 v254, v254
	v_exp_f32_e32 v255, v255
	v_add_f32_e32 v254, 1.0, v254
	v_add_f32_e32 v255, 1.0, v255
	v_rcp_f32_e32 v254, v254
	v_rcp_f32_e32 v255, v255
	v_mul_f32_e32 v18, v18, v254
	v_mul_f32_e32 v19, v19, v255
	v_cvt_pk_bf16_f32 v16, v16, v17
	v_cvt_pk_bf16_f32 v18, v18, v19
	global_store_short v176, v16, s[48:49]
	v_add_u32_e32 v251, 0x2000, v176
	global_store_short_d16_hi v251, v16, s[48:49]
	v_add_u32_e32 v252, 0x4000, v176
	global_store_short v252, v18, s[48:49]
	v_add_u32_e32 v253, 0x6000, v176
	global_store_short_d16_hi v253, v18, s[48:49]
	v_mul_f32_e32 v254, 0xbfb8aa3b, v20
	v_mul_f32_e32 v255, 0xbfb8aa3b, v21
	v_exp_f32_e32 v254, v254
	v_exp_f32_e32 v255, v255
	v_add_f32_e32 v254, 1.0, v254
	v_add_f32_e32 v255, 1.0, v255
	v_rcp_f32_e32 v254, v254
	v_rcp_f32_e32 v255, v255
	v_mul_f32_e32 v20, v20, v254
	v_mul_f32_e32 v21, v21, v255
	v_mul_f32_e32 v254, 0xbfb8aa3b, v22
	v_mul_f32_e32 v255, 0xbfb8aa3b, v23
	v_exp_f32_e32 v254, v254
	v_exp_f32_e32 v255, v255
	v_add_f32_e32 v254, 1.0, v254
	v_add_f32_e32 v255, 1.0, v255
	v_rcp_f32_e32 v254, v254
	v_rcp_f32_e32 v255, v255
	v_mul_f32_e32 v22, v22, v254
	v_mul_f32_e32 v23, v23, v255
	v_cvt_pk_bf16_f32 v20, v20, v21
	v_cvt_pk_bf16_f32 v22, v22, v23
	global_store_short v176, v20, s[48:49] offset:32
	global_store_short_d16_hi v251, v20, s[48:49] offset:32
	global_store_short v252, v22, s[48:49] offset:32
	global_store_short_d16_hi v253, v22, s[48:49] offset:32
	v_mul_f32_e32 v254, 0xbfb8aa3b, v24
	v_mul_f32_e32 v255, 0xbfb8aa3b, v25
	v_exp_f32_e32 v254, v254
	v_exp_f32_e32 v255, v255
	v_add_f32_e32 v254, 1.0, v254
	v_add_f32_e32 v255, 1.0, v255
	v_rcp_f32_e32 v254, v254
	v_rcp_f32_e32 v255, v255
	v_mul_f32_e32 v24, v24, v254
	v_mul_f32_e32 v25, v25, v255
	v_mul_f32_e32 v254, 0xbfb8aa3b, v26
	v_mul_f32_e32 v255, 0xbfb8aa3b, v27
	v_exp_f32_e32 v254, v254
	v_exp_f32_e32 v255, v255
	v_add_f32_e32 v254, 1.0, v254
	v_add_f32_e32 v255, 1.0, v255
	v_rcp_f32_e32 v254, v254
	v_rcp_f32_e32 v255, v255
	v_mul_f32_e32 v26, v26, v254
	v_mul_f32_e32 v27, v27, v255
	v_cvt_pk_bf16_f32 v24, v24, v25
	v_cvt_pk_bf16_f32 v26, v26, v27
	global_store_short v177, v24, s[48:49]
	v_add_u32_e32 v251, 0x2000, v177
	global_store_short_d16_hi v251, v24, s[48:49]
	v_add_u32_e32 v252, 0x4000, v177
	global_store_short v252, v26, s[48:49]
	v_add_u32_e32 v253, 0x6000, v177
	global_store_short_d16_hi v253, v26, s[48:49]
	v_mul_f32_e32 v254, 0xbfb8aa3b, v28
	v_mul_f32_e32 v255, 0xbfb8aa3b, v29
	v_exp_f32_e32 v254, v254
	v_exp_f32_e32 v255, v255
	v_add_f32_e32 v254, 1.0, v254
	v_add_f32_e32 v255, 1.0, v255
	v_rcp_f32_e32 v254, v254
	v_rcp_f32_e32 v255, v255
	v_mul_f32_e32 v28, v28, v254
	v_mul_f32_e32 v29, v29, v255
	v_mul_f32_e32 v254, 0xbfb8aa3b, v30
	v_mul_f32_e32 v255, 0xbfb8aa3b, v31
	v_exp_f32_e32 v254, v254
	v_exp_f32_e32 v255, v255
	v_add_f32_e32 v254, 1.0, v254
	v_add_f32_e32 v255, 1.0, v255
	v_rcp_f32_e32 v254, v254
	v_rcp_f32_e32 v255, v255
	v_mul_f32_e32 v30, v30, v254
	v_mul_f32_e32 v31, v31, v255
	v_cvt_pk_bf16_f32 v28, v28, v29
	v_cvt_pk_bf16_f32 v30, v30, v31
	global_store_short v177, v28, s[48:49] offset:32
	global_store_short_d16_hi v251, v28, s[48:49] offset:32
	global_store_short v252, v30, s[48:49] offset:32
	global_store_short_d16_hi v253, v30, s[48:49] offset:32

; __device__ __forceinline__ u16 f2bf(float f) { return (u16)(cvtpk(f, f) & 0xffffu); }
; #define FOR_M _Pragma("unroll") for (int m = 0; m < 4; ++m)
; #define FOR_J _Pragma("unroll") for (int j = 0; j < 4; ++j)
; #define OPQ(x) asm volatile("" : "+v"(x))
; #define ENDM __builtin_amdgcn_sched_barrier(0)
; template <int EPI>
; __device__ __forceinline__ void epi_quad(const Params& P, f32x4 (&acc)[4][2], int rowb, int pn, int wc, int fr, int fq,
;                                          const float* xres, float* yout, const float* rstd_q) {
;     ...
;     } else if (pn < 16) {
;       char* vb_ = (char*)(P_vA + ((size_t)(b * 4 + (pn - 12)) * SEQ + pos0) * 128);
;       const unsigned vo = (r4 * 128 + cg) * 2;
;       FOR_M { unsigned vom = vo + (unsigned)(m * 16 * 128) * 2; OPQ(vom);
;         FOR_J {
; #pragma unroll
;           for (int n = 0; n < 2; ++n) ST16(vb_, vom + (unsigned)(j * 128 + n * 16) * 2, f2bf(acc[m][n][j]));
;         } ENDM; }
.LBB0_264:
	s_andn2_b64 vcc, exec, s[0:1]
	s_cbranch_vccnz .LBB0_266
	s_add_i32 s0, s79, s74
	s_ashr_i32 s1, s0, 31
	s_lshl_b64 s[0:1], s[0:1], 20
	s_add_u32 s0, s86, s0
	s_addc_u32 s1, s87, s1
	s_lshl_b32 s47, s78, 1
	s_add_u32 s48, s0, s47
	s_addc_u32 s49, s1, 0
	v_cvt_pk_bf16_f32 v24, v24, v25
	v_cvt_pk_bf16_f32 v26, v26, v27
	global_store_short v128, v24, s[48:49]
	global_store_short_d16_hi v128, v24, s[48:49] offset:256
	global_store_short v128, v26, s[48:49] offset:512
	global_store_short_d16_hi v128, v26, s[48:49] offset:768
	v_cvt_pk_bf16_f32 v28, v28, v29
	v_cvt_pk_bf16_f32 v30, v30, v31
	global_store_short v128, v28, s[48:49] offset:32
	global_store_short_d16_hi v128, v28, s[48:49] offset:288
	global_store_short v128, v30, s[48:49] offset:544
	global_store_short_d16_hi v128, v30, s[48:49] offset:800
	v_cvt_pk_bf16_f32 v0, v0, v1
	v_cvt_pk_bf16_f32 v2, v2, v3
	global_store_short v171, v0, s[48:49]
	global_store_short_d16_hi v171, v0, s[48:49] offset:256
	global_store_short v171, v2, s[48:49] offset:512
	global_store_short_d16_hi v171, v2, s[48:49] offset:768
	v_cvt_pk_bf16_f32 v4, v4, v5
	v_cvt_pk_bf16_f32 v6, v6, v7
	global_store_short v171, v4, s[48:49] offset:32
	global_store_short_d16_hi v171, v4, s[48:49] offset:288
	global_store_short v171, v6, s[48:49] offset:544
	global_store_short_d16_hi v171, v6, s[48:49] offset:800
	v_cvt_pk_bf16_f32 v8, v8, v9
	v_cvt_pk_bf16_f32 v10, v10, v11
	global_store_short v172, v8, s[48:49]
	global_store_short_d16_hi v172, v8, s[48:49] offset:256
	global_store_short v172, v10, s[48:49] offset:512
	global_store_short_d16_hi v172, v10, s[48:49] offset:768
	v_cvt_pk_bf16_f32 v12, v12, v13
	v_cvt_pk_bf16_f32 v14, v14, v15
	global_store_short v172, v12, s[48:49] offset:32
	global_store_short_d16_hi v172, v12, s[48:49] offset:288
	global_store_short v172, v14, s[48:49] offset:544
	global_store_short_d16_hi v172, v14, s[48:49] offset:800
	v_cvt_pk_bf16_f32 v16, v16, v17
	v_cvt_pk_bf16_f32 v18, v18, v19
	global_store_short v173, v16, s[48:49]
	global_store_short_d16_hi v173, v16, s[48:49] offset:256
	global_store_short v173, v18, s[48:49] offset:512
	global_store_short_d16_hi v173, v18, s[48:49] offset:768
	v_cvt_pk_bf16_f32 v20, v20, v21
	v_cvt_pk_bf16_f32 v22, v22, v23
	global_store_short v173, v20, s[48:49] offset:32
	global_store_short_d16_hi v173, v20, s[48:49] offset:288
	global_store_short v173, v22, s[48:49] offset:544
	global_store_short_d16_hi v173, v22, s[48:49] offset:800

; __device__ __forceinline__ u16 f2bf(float f) { return (u16)(cvtpk(f, f) & 0xffffu); }
; #define FOR_M _Pragma("unroll") for (int m = 0; m < 4; ++m)
; #define FOR_J _Pragma("unroll") for (int j = 0; j < 4; ++j)
; #define OPQ(x) asm volatile("" : "+v"(x))
; #define ENDM __builtin_amdgcn_sched_barrier(0)
; template <int EPI>
; __device__ __forceinline__ void epi_quad(const Params& P, f32x4 (&acc)[4][2], int rowb, int pn, int wc, int fr, int fq,
;                                          const float* xres, float* yout, const float* rstd_q) {
;     ...
;   if constexpr (EPI == EPI_OUT) {
;     char* hb_ = (char*)((u16*)yout + (size_t)rowb * DM + pn * 128);
;     const unsigned vo = (r4 * DM + cg) * 2;
;     FOR_M { unsigned vom = vo + (unsigned)(m * 16 * DM) * 2; OPQ(vom);
;       FOR_J {
; #pragma unroll
;         for (int n = 0; n < 2; ++n) ST16(hb_, vom + (unsigned)(j * DM + n * 16) * 2, f2bf(acc[m][n][j]));
;       } ENDM; }
; template <int EPI, bool SPLIT>
; __device__ __forceinline__ void gemm_phase(const Params& P, const u16* __restrict__ A, const u16* __restrict__ Bt, int NT  , int K,
;                                            const float* xres, float* yout, char* lds) {
;     ...
; #pragma unroll
;     for (int ai = 0; ai < 2; ++ai)
; #pragma unroll
;       for (int bj = 0; bj < 2; ++bj)
;         epi_quad<EPI>(P, acc[ai][bj], brow + ai * 128 + wr * 64, pn * 2 + bj, wc, fr_e, fq_e, xres, yout, rstd_l + ai * 128 + wr * 64);
;     }
;     __syncthreads();
.LBB0_757:
	s_add_i32 s0, s10, s2
	s_ashr_i32 s1, s0, 31
	v_mov_b32_e32 v128, v132
	v_mov_b32_e32 v158, v133
	s_lshl_b64 s[0:1], s[0:1], 13
	s_add_u32 s10, s16, s0
	v_lshlrev_b32_e32 v158, 15, v158
	v_lshlrev_b32_e32 v128, 1, v128
	s_addc_u32 s42, s17, s1
	s_lshl_b64 s[0:1], s[40:41], 1
	v_add3_u32 v160, v128, s3, v158
	s_add_u32 s40, s10, s0
	s_addc_u32 s41, s42, s1
	v_mov_b32_e32 v161, v160
	v_cvt_pk_bf16_f32 v92, v92, v93
	v_cvt_pk_bf16_f32 v94, v94, v95
	global_store_short v160, v92, s[40:41] offset:256
	v_add_u32_e32 v251, 0x2000, v160
	global_store_short_d16_hi v251, v92, s[40:41] offset:256
	v_add_u32_e32 v252, 0x4000, v160
	global_store_short v252, v94, s[40:41] offset:256
	v_add_u32_e32 v253, 0x6000, v160
	global_store_short_d16_hi v253, v94, s[40:41] offset:256
	v_cvt_pk_bf16_f32 v88, v88, v89
	v_cvt_pk_bf16_f32 v90, v90, v91
	global_store_short v160, v88, s[40:41] offset:288
	global_store_short_d16_hi v251, v88, s[40:41] offset:288
	global_store_short v252, v90, s[40:41] offset:288
	global_store_short_d16_hi v253, v90, s[40:41] offset:288
	v_cvt_pk_bf16_f32 v116, v116, v117
	v_cvt_pk_bf16_f32 v118, v118, v119
	v_add_u32_e32 v251, 0x20000, v160
	global_store_short v251, v116, s[40:41]
	v_add_u32_e32 v252, 0x22000, v160
	global_store_short_d16_hi v252, v116, s[40:41]
	v_add_u32_e32 v253, 0x24000, v160
	global_store_short v253, v118, s[40:41]
	v_add_u32_e32 v251, 0x26000, v160
	global_store_short_d16_hi v251, v118, s[40:41]
	v_cvt_pk_bf16_f32 v112, v112, v113
	v_cvt_pk_bf16_f32 v114, v114, v115
	v_add_u32_e32 v252, 0x20000, v160
	global_store_short v252, v112, s[40:41] offset:32
	v_add_u32_e32 v253, 0x22000, v160
	global_store_short_d16_hi v253, v112, s[40:41] offset:32
	v_add_u32_e32 v251, 0x24000, v160
	global_store_short v251, v114, s[40:41] offset:32
	v_add_u32_e32 v252, 0x26000, v160
	global_store_short_d16_hi v252, v114, s[40:41] offset:32
	v_cvt_pk_bf16_f32 v84, v84, v85
	v_cvt_pk_bf16_f32 v86, v86, v87
	v_add_u32_e32 v253, 0x20000, v160
	global_store_short v253, v84, s[40:41] offset:256
	v_add_u32_e32 v251, 0x22000, v160
	global_store_short_d16_hi v251, v84, s[40:41] offset:256
	v_add_u32_e32 v252, 0x24000, v160
	global_store_short v252, v86, s[40:41] offset:256
	v_add_u32_e32 v253, 0x26000, v160
	global_store_short_d16_hi v253, v86, s[40:41] offset:256
	v_cvt_pk_bf16_f32 v80, v80, v81
	v_cvt_pk_bf16_f32 v82, v82, v83
	v_add_u32_e32 v251, 0x20000, v160
	global_store_short v251, v80, s[40:41] offset:288
	v_add_u32_e32 v252, 0x22000, v160
	global_store_short_d16_hi v252, v80, s[40:41] offset:288
	v_add_u32_e32 v253, 0x24000, v160
	global_store_short v253, v82, s[40:41] offset:288
	v_add_u32_e32 v251, 0x26000, v160
	global_store_short_d16_hi v251, v82, s[40:41] offset:288
	v_cvt_pk_bf16_f32 v108, v108, v109
	v_cvt_pk_bf16_f32 v110, v110, v111
	v_add_u32_e32 v252, 0x40000, v160
	global_store_short v252, v108, s[40:41]
	v_add_u32_e32 v253, 0x42000, v160
	global_store_short_d16_hi v253, v108, s[40:41]
	v_add_u32_e32 v251, 0x44000, v160
	global_store_short v251, v110, s[40:41]
	v_add_u32_e32 v252, 0x46000, v160
	global_store_short_d16_hi v252, v110, s[40:41]
	v_cvt_pk_bf16_f32 v104, v104, v105
	v_cvt_pk_bf16_f32 v106, v106, v107
	v_add_u32_e32 v253, 0x40000, v160
	global_store_short v253, v104, s[40:41] offset:32
	v_add_u32_e32 v251, 0x42000, v160
	global_store_short_d16_hi v251, v104, s[40:41] offset:32
	v_add_u32_e32 v252, 0x44000, v160
	global_store_short v252, v106, s[40:41] offset:32
	v_add_u32_e32 v253, 0x46000, v160
	global_store_short_d16_hi v253, v106, s[40:41] offset:32
	v_cvt_pk_bf16_f32 v76, v76, v77
	v_cvt_pk_bf16_f32 v78, v78, v79
	v_add_u32_e32 v251, 0x40000, v160
	global_store_short v251, v76, s[40:41] offset:256
	v_add_u32_e32 v252, 0x42000, v160
	global_store_short_d16_hi v252, v76, s[40:41] offset:256
	v_add_u32_e32 v253, 0x44000, v160
	global_store_short v253, v78, s[40:41] offset:256
	v_add_u32_e32 v251, 0x46000, v160
	global_store_short_d16_hi v251, v78, s[40:41] offset:256
	v_cvt_pk_bf16_f32 v72, v72, v73
	v_cvt_pk_bf16_f32 v74, v74, v75
	v_add_u32_e32 v252, 0x40000, v160
	global_store_short v252, v72, s[40:41] offset:288
	v_add_u32_e32 v253, 0x42000, v160
	global_store_short_d16_hi v253, v72, s[40:41] offset:288
	v_add_u32_e32 v251, 0x44000, v160
	global_store_short v251, v74, s[40:41] offset:288
	v_add_u32_e32 v252, 0x46000, v160
	global_store_short_d16_hi v252, v74, s[40:41] offset:288
	v_cvt_pk_bf16_f32 v100, v100, v101
	v_cvt_pk_bf16_f32 v102, v102, v103
	v_add_u32_e32 v253, 0x60000, v160
	global_store_short v253, v100, s[40:41]
	v_add_u32_e32 v251, 0x62000, v160
	global_store_short_d16_hi v251, v100, s[40:41]
	v_add_u32_e32 v252, 0x64000, v160
	global_store_short v252, v102, s[40:41]
	v_add_u32_e32 v253, 0x66000, v160
	global_store_short_d16_hi v253, v102, s[40:41]
	v_cvt_pk_bf16_f32 v96, v96, v97
	v_cvt_pk_bf16_f32 v98, v98, v99
	v_add_u32_e32 v251, 0x60000, v160
	global_store_short v251, v96, s[40:41] offset:32
	v_add_u32_e32 v252, 0x62000, v160
	global_store_short_d16_hi v252, v96, s[40:41] offset:32
	v_add_u32_e32 v253, 0x64000, v160
	global_store_short v253, v98, s[40:41] offset:32
	v_add_u32_e32 v251, 0x66000, v160
	global_store_short_d16_hi v251, v98, s[40:41] offset:32
	v_cvt_pk_bf16_f32 v68, v68, v69
	v_cvt_pk_bf16_f32 v70, v70, v71
	v_add_u32_e32 v252, 0x60000, v160
	global_store_short v252, v68, s[40:41] offset:256
	v_add_u32_e32 v253, 0x62000, v160
	global_store_short_d16_hi v253, v68, s[40:41] offset:256
	v_add_u32_e32 v251, 0x64000, v160
	global_store_short v251, v70, s[40:41] offset:256
	v_add_u32_e32 v252, 0x66000, v160
	global_store_short_d16_hi v252, v70, s[40:41] offset:256
; __device__ __forceinline__ u16 f2bf(float f) { return (u16)(cvtpk(f, f) & 0xffffu); }
; #define FOR_M _Pragma("unroll") for (int m = 0; m < 4; ++m)
; #define FOR_J _Pragma("unroll") for (int j = 0; j < 4; ++j)
; #define OPQ(x) asm volatile("" : "+v"(x))
; #define ENDM __builtin_amdgcn_sched_barrier(0)
; template <int EPI>
; __device__ __forceinline__ void epi_quad(const Params& P, f32x4 (&acc)[4][2], int rowb, int pn, int wc, int fr, int fq,
;                                          const float* xres, float* yout, const float* rstd_q) {
;     ...
;   if constexpr (EPI == EPI_OUT) {
;     char* hb_ = (char*)((u16*)yout + (size_t)rowb * DM + pn * 128);
;     const unsigned vo = (r4 * DM + cg) * 2;
;     FOR_M { unsigned vom = vo + (unsigned)(m * 16 * DM) * 2; OPQ(vom);
;       FOR_J {
; #pragma unroll
;         for (int n = 0; n < 2; ++n) ST16(hb_, vom + (unsigned)(j * DM + n * 16) * 2, f2bf(acc[m][n][j]));
;       } ENDM; }
; template <int EPI, bool SPLIT>
; __device__ __forceinline__ void gemm_phase(const Params& P, const u16* __restrict__ A, const u16* __restrict__ Bt, int NT  , int K,
;                                            const float* xres, float* yout, char* lds) {
;     ...
; #pragma unroll
;     for (int ai = 0; ai < 2; ++ai)
; #pragma unroll
;       for (int bj = 0; bj < 2; ++bj)
;         epi_quad<EPI>(P, acc[ai][bj], brow + ai * 128 + wr * 64, pn * 2 + bj, wc, fr_e, fq_e, xres, yout, rstd_l + ai * 128 + wr * 64);
;     }
;     __syncthreads();
	v_cvt_pk_bf16_f32 v64, v64, v65
	v_cvt_pk_bf16_f32 v66, v66, v67
	v_add_u32_e32 v253, 0x60000, v160
	global_store_short v253, v64, s[40:41] offset:288
	v_add_u32_e32 v251, 0x62000, v160
	global_store_short_d16_hi v251, v64, s[40:41] offset:288
	v_add_u32_e32 v252, 0x64000, v160
	global_store_short v252, v66, s[40:41] offset:288
	v_add_u32_e32 v253, 0x66000, v160
	global_store_short_d16_hi v253, v66, s[40:41] offset:288
	v_cvt_pk_bf16_f32 v124, v124, v125
	v_cvt_pk_bf16_f32 v126, v126, v127
	global_store_short v161, v124, s[40:41]
	v_add_u32_e32 v251, 0x2000, v161
	global_store_short_d16_hi v251, v124, s[40:41]
	v_add_u32_e32 v252, 0x4000, v161
	global_store_short v252, v126, s[40:41]
	v_add_u32_e32 v253, 0x6000, v161
	global_store_short_d16_hi v253, v126, s[40:41]
	v_cvt_pk_bf16_f32 v120, v120, v121
	v_cvt_pk_bf16_f32 v122, v122, v123
	global_store_short v161, v120, s[40:41] offset:32
	global_store_short_d16_hi v251, v120, s[40:41] offset:32
	global_store_short v252, v122, s[40:41] offset:32
	global_store_short_d16_hi v253, v122, s[40:41] offset:32
	s_add_u32 s40, s40, 0x100000
	s_addc_u32 s41, s41, 0
	v_cvt_pk_bf16_f32 v60, v60, v61
	v_cvt_pk_bf16_f32 v62, v62, v63
	global_store_short v160, v60, s[40:41]
	v_add_u32_e32 v251, 0x2000, v160
	global_store_short_d16_hi v251, v60, s[40:41]
	v_add_u32_e32 v252, 0x4000, v160
	global_store_short v252, v62, s[40:41]
	v_add_u32_e32 v253, 0x6000, v160
	global_store_short_d16_hi v253, v62, s[40:41]
	v_cvt_pk_bf16_f32 v56, v56, v57
	v_cvt_pk_bf16_f32 v58, v58, v59
	global_store_short v160, v56, s[40:41] offset:32
	global_store_short_d16_hi v251, v56, s[40:41] offset:32
	global_store_short v252, v58, s[40:41] offset:32
	global_store_short_d16_hi v253, v58, s[40:41] offset:32
	v_cvt_pk_bf16_f32 v28, v28, v29
	v_cvt_pk_bf16_f32 v30, v30, v31
	global_store_short v160, v28, s[40:41] offset:256
	global_store_short_d16_hi v251, v28, s[40:41] offset:256
	global_store_short v252, v30, s[40:41] offset:256
	global_store_short_d16_hi v253, v30, s[40:41] offset:256
	v_cvt_pk_bf16_f32 v24, v24, v25
	v_cvt_pk_bf16_f32 v26, v26, v27
	global_store_short v160, v24, s[40:41] offset:288
	global_store_short_d16_hi v251, v24, s[40:41] offset:288
	global_store_short v252, v26, s[40:41] offset:288
	global_store_short_d16_hi v253, v26, s[40:41] offset:288
	v_cvt_pk_bf16_f32 v52, v52, v53
	v_cvt_pk_bf16_f32 v54, v54, v55
	v_add_u32_e32 v251, 0x20000, v160
	global_store_short v251, v52, s[40:41]
	v_add_u32_e32 v252, 0x22000, v160
	global_store_short_d16_hi v252, v52, s[40:41]
	v_add_u32_e32 v253, 0x24000, v160
	global_store_short v253, v54, s[40:41]
	v_add_u32_e32 v251, 0x26000, v160
	global_store_short_d16_hi v251, v54, s[40:41]
	v_cvt_pk_bf16_f32 v48, v48, v49
	v_cvt_pk_bf16_f32 v50, v50, v51
	v_add_u32_e32 v252, 0x20000, v160
	global_store_short v252, v48, s[40:41] offset:32
	v_add_u32_e32 v253, 0x22000, v160
	global_store_short_d16_hi v253, v48, s[40:41] offset:32
	v_add_u32_e32 v251, 0x24000, v160
	global_store_short v251, v50, s[40:41] offset:32
	v_add_u32_e32 v252, 0x26000, v160
	global_store_short_d16_hi v252, v50, s[40:41] offset:32
	v_cvt_pk_bf16_f32 v20, v20, v21
	v_cvt_pk_bf16_f32 v22, v22, v23
	v_add_u32_e32 v253, 0x20000, v160
	global_store_short v253, v20, s[40:41] offset:256
	v_add_u32_e32 v251, 0x22000, v160
	global_store_short_d16_hi v251, v20, s[40:41] offset:256
	v_add_u32_e32 v252, 0x24000, v160
	global_store_short v252, v22, s[40:41] offset:256
	v_add_u32_e32 v253, 0x26000, v160
	global_store_short_d16_hi v253, v22, s[40:41] offset:256
	v_cvt_pk_bf16_f32 v16, v16, v17
	v_cvt_pk_bf16_f32 v18, v18, v19
	v_add_u32_e32 v251, 0x20000, v160
	global_store_short v251, v16, s[40:41] offset:288
; __device__ __forceinline__ u16 f2bf(float f) { return (u16)(cvtpk(f, f) & 0xffffu); }
; #define FOR_M _Pragma("unroll") for (int m = 0; m < 4; ++m)
; #define FOR_J _Pragma("unroll") for (int j = 0; j < 4; ++j)
; #define OPQ(x) asm volatile("" : "+v"(x))
; #define ENDM __builtin_amdgcn_sched_barrier(0)
; template <int EPI>
; __device__ __forceinline__ void epi_quad(const Params& P, f32x4 (&acc)[4][2], int rowb, int pn, int wc, int fr, int fq,
;                                          const float* xres, float* yout, const float* rstd_q) {
;     ...
;   if constexpr (EPI == EPI_OUT) {
;     char* hb_ = (char*)((u16*)yout + (size_t)rowb * DM + pn * 128);
;     const unsigned vo = (r4 * DM + cg) * 2;
;     FOR_M { unsigned vom = vo + (unsigned)(m * 16 * DM) * 2; OPQ(vom);
;       FOR_J {
; #pragma unroll
;         for (int n = 0; n < 2; ++n) ST16(hb_, vom + (unsigned)(j * DM + n * 16) * 2, f2bf(acc[m][n][j]));
;       } ENDM; }
; template <int EPI, bool SPLIT>
; __device__ __forceinline__ void gemm_phase(const Params& P, const u16* __restrict__ A, const u16* __restrict__ Bt, int NT  , int K,
;                                            const float* xres, float* yout, char* lds) {
;     ...
; #pragma unroll
;     for (int ai = 0; ai < 2; ++ai)
; #pragma unroll
;       for (int bj = 0; bj < 2; ++bj)
;         epi_quad<EPI>(P, acc[ai][bj], brow + ai * 128 + wr * 64, pn * 2 + bj, wc, fr_e, fq_e, xres, yout, rstd_l + ai * 128 + wr * 64);
;     }
;     __syncthreads();
;   }
	v_add_u32_e32 v252, 0x22000, v160
	global_store_short_d16_hi v252, v16, s[40:41] offset:288
	v_add_u32_e32 v253, 0x24000, v160
	global_store_short v253, v18, s[40:41] offset:288
	v_add_u32_e32 v251, 0x26000, v160
	global_store_short_d16_hi v251, v18, s[40:41] offset:288
	v_cvt_pk_bf16_f32 v44, v44, v45
	v_cvt_pk_bf16_f32 v46, v46, v47
	v_add_u32_e32 v252, 0x40000, v160
	global_store_short v252, v44, s[40:41]
	v_add_u32_e32 v253, 0x42000, v160
	global_store_short_d16_hi v253, v44, s[40:41]
	v_add_u32_e32 v251, 0x44000, v160
	global_store_short v251, v46, s[40:41]
	v_add_u32_e32 v252, 0x46000, v160
	global_store_short_d16_hi v252, v46, s[40:41]
	v_cvt_pk_bf16_f32 v40, v40, v41
	v_cvt_pk_bf16_f32 v42, v42, v43
	v_add_u32_e32 v253, 0x40000, v160
	global_store_short v253, v40, s[40:41] offset:32
	v_add_u32_e32 v251, 0x42000, v160
	global_store_short_d16_hi v251, v40, s[40:41] offset:32
	v_add_u32_e32 v252, 0x44000, v160
	global_store_short v252, v42, s[40:41] offset:32
	v_add_u32_e32 v253, 0x46000, v160
	global_store_short_d16_hi v253, v42, s[40:41] offset:32
	v_cvt_pk_bf16_f32 v12, v12, v13
	v_cvt_pk_bf16_f32 v14, v14, v15
	v_add_u32_e32 v251, 0x40000, v160
	global_store_short v251, v12, s[40:41] offset:256
	v_add_u32_e32 v252, 0x42000, v160
	global_store_short_d16_hi v252, v12, s[40:41] offset:256
	v_add_u32_e32 v253, 0x44000, v160
	global_store_short v253, v14, s[40:41] offset:256
	v_add_u32_e32 v251, 0x46000, v160
	global_store_short_d16_hi v251, v14, s[40:41] offset:256
	v_cvt_pk_bf16_f32 v8, v8, v9
	v_cvt_pk_bf16_f32 v10, v10, v11
	v_add_u32_e32 v252, 0x40000, v160
	global_store_short v252, v8, s[40:41] offset:288
	v_add_u32_e32 v253, 0x42000, v160
	global_store_short_d16_hi v253, v8, s[40:41] offset:288
	v_add_u32_e32 v251, 0x44000, v160
	global_store_short v251, v10, s[40:41] offset:288
	v_add_u32_e32 v252, 0x46000, v160
	global_store_short_d16_hi v252, v10, s[40:41] offset:288
	v_cvt_pk_bf16_f32 v36, v36, v37
	v_cvt_pk_bf16_f32 v38, v38, v39
	v_add_u32_e32 v253, 0x60000, v160
	global_store_short v253, v36, s[40:41]
	v_add_u32_e32 v251, 0x62000, v160
	global_store_short_d16_hi v251, v36, s[40:41]
	v_add_u32_e32 v252, 0x64000, v160
	global_store_short v252, v38, s[40:41]
	v_add_u32_e32 v253, 0x66000, v160
	global_store_short_d16_hi v253, v38, s[40:41]
	v_cvt_pk_bf16_f32 v32, v32, v33
	v_cvt_pk_bf16_f32 v34, v34, v35
	v_add_u32_e32 v251, 0x60000, v160
	global_store_short v251, v32, s[40:41] offset:32
	v_add_u32_e32 v252, 0x62000, v160
	global_store_short_d16_hi v252, v32, s[40:41] offset:32
	v_add_u32_e32 v253, 0x64000, v160
	global_store_short v253, v34, s[40:41] offset:32
	v_add_u32_e32 v251, 0x66000, v160
	global_store_short_d16_hi v251, v34, s[40:41] offset:32
	v_cvt_pk_bf16_f32 v4, v4, v5
	v_cvt_pk_bf16_f32 v6, v6, v7
	v_add_u32_e32 v252, 0x60000, v160
	global_store_short v252, v4, s[40:41] offset:256
	v_add_u32_e32 v253, 0x62000, v160
	global_store_short_d16_hi v253, v4, s[40:41] offset:256
	v_add_u32_e32 v251, 0x64000, v160
	global_store_short v251, v6, s[40:41] offset:256
	v_add_u32_e32 v252, 0x66000, v160
	global_store_short_d16_hi v252, v6, s[40:41] offset:256
	v_cvt_pk_bf16_f32 v0, v0, v1
	v_cvt_pk_bf16_f32 v2, v2, v3
	v_add_u32_e32 v253, 0x60000, v160
	global_store_short v253, v0, s[40:41] offset:288
	v_add_u32_e32 v251, 0x62000, v160
	global_store_short_d16_hi v251, v0, s[40:41] offset:288
	v_add_u32_e32 v252, 0x64000, v160
	global_store_short v252, v2, s[40:41] offset:288
	v_add_u32_e32 v253, 0x66000, v160
	global_store_short_d16_hi v253, v2, s[40:41] offset:288
	s_add_i32 s54, s54, s90
	s_add_i32 s33, s33, s84
	s_cmpk_lt_i32 s54, 0x200
	s_waitcnt vmcnt(0)
	s_barrier
	s_cbranch_scc0 .LBB0_768

; __device__ __forceinline__ u16 f2bf(float f) { return (u16)(cvtpk(f, f) & 0xffffu); }
; #define FOR_M _Pragma("unroll") for (int m = 0; m < 4; ++m)
; #define FOR_J _Pragma("unroll") for (int j = 0; j < 4; ++j)
; #define OPQ(x) asm volatile("" : "+v"(x))
; #define ENDM __builtin_amdgcn_sched_barrier(0)
; template <int EPI>
; __device__ __forceinline__ void epi_quad(const Params& P, f32x4 (&acc)[4][2], int rowb, int pn, int wc, int fr, int fq,
;                                          const float* xres, float* yout, const float* rstd_q) {
;     ...
;     } else if (pn < 128) {
;       char* gb_ = (char*)(P_gate + (size_t)rowb * DM + (pn - 96) * 128);
;       const unsigned vo = (r4 * DM + cg) * 2;
;       FOR_M { unsigned vom = vo + (unsigned)(m * 16 * DM) * 2; OPQ(vom);
;         FOR_J {
; #pragma unroll
;           for (int n = 0; n < 2; ++n) {
;             const float v = acc[m][n][j];
;             ST16(gb_, vom + (unsigned)(j * DM + n * 16) * 2, f2bf(v * __builtin_amdgcn_rcpf(1.f + __expf(-v))));
;           }
;         } ENDM; }
.LBB0_884:
	s_andn2_b64 vcc, exec, s[2:3]
	s_cbranch_vccnz .LBB0_886
	s_add_u32 s1, s91, s64
	s_addc_u32 s2, s80, s65
	s_add_u32 s60, s1, 0x16f0a000
	s_addc_u32 s61, s2, 0
	v_mul_f32_e32 v254, 0xbfb8aa3b, v120
	v_mul_f32_e32 v255, 0xbfb8aa3b, v121
	v_exp_f32_e32 v254, v254
	v_exp_f32_e32 v255, v255
	v_add_f32_e32 v254, 1.0, v254
	v_add_f32_e32 v255, 1.0, v255
	v_rcp_f32_e32 v254, v254
	v_rcp_f32_e32 v255, v255
	v_mul_f32_e32 v120, v120, v254
	v_mul_f32_e32 v121, v121, v255
	v_mul_f32_e32 v254, 0xbfb8aa3b, v122
	v_mul_f32_e32 v255, 0xbfb8aa3b, v123
	v_exp_f32_e32 v254, v254
	v_exp_f32_e32 v255, v255
	v_add_f32_e32 v254, 1.0, v254
	v_add_f32_e32 v255, 1.0, v255
	v_rcp_f32_e32 v254, v254
	v_rcp_f32_e32 v255, v255
	v_mul_f32_e32 v122, v122, v254
	v_mul_f32_e32 v123, v123, v255
	v_cvt_pk_bf16_f32 v120, v120, v121
	v_cvt_pk_bf16_f32 v122, v122, v123
	global_store_short v132, v120, s[60:61]
	v_add_u32_e32 v251, 0x2000, v132
	global_store_short_d16_hi v251, v120, s[60:61]
	v_add_u32_e32 v252, 0x4000, v132
	global_store_short v252, v122, s[60:61]
	v_add_u32_e32 v253, 0x6000, v132
	global_store_short_d16_hi v253, v122, s[60:61]
	v_mul_f32_e32 v254, 0xbfb8aa3b, v124
	v_mul_f32_e32 v255, 0xbfb8aa3b, v125
	v_exp_f32_e32 v254, v254
	v_exp_f32_e32 v255, v255
	v_add_f32_e32 v254, 1.0, v254
	v_add_f32_e32 v255, 1.0, v255
	v_rcp_f32_e32 v254, v254
	v_rcp_f32_e32 v255, v255
	v_mul_f32_e32 v124, v124, v254
	v_mul_f32_e32 v125, v125, v255
	v_mul_f32_e32 v254, 0xbfb8aa3b, v126
	v_mul_f32_e32 v255, 0xbfb8aa3b, v127
	v_exp_f32_e32 v254, v254
	v_exp_f32_e32 v255, v255
	v_add_f32_e32 v254, 1.0, v254
	v_add_f32_e32 v255, 1.0, v255
	v_rcp_f32_e32 v254, v254
	v_rcp_f32_e32 v255, v255
	v_mul_f32_e32 v126, v126, v254
	v_mul_f32_e32 v127, v127, v255
	v_cvt_pk_bf16_f32 v124, v124, v125
	v_cvt_pk_bf16_f32 v126, v126, v127
	global_store_short v132, v124, s[60:61] offset:32
	global_store_short_d16_hi v251, v124, s[60:61] offset:32
	global_store_short v252, v126, s[60:61] offset:32
	global_store_short_d16_hi v253, v126, s[60:61] offset:32
	v_mul_f32_e32 v254, 0xbfb8aa3b, v96
	v_mul_f32_e32 v255, 0xbfb8aa3b, v97
	v_exp_f32_e32 v254, v254
	v_exp_f32_e32 v255, v255
	v_add_f32_e32 v254, 1.0, v254
	v_add_f32_e32 v255, 1.0, v255
	v_rcp_f32_e32 v254, v254
	v_rcp_f32_e32 v255, v255
	v_mul_f32_e32 v96, v96, v254
	v_mul_f32_e32 v97, v97, v255
	v_mul_f32_e32 v254, 0xbfb8aa3b, v98
	v_mul_f32_e32 v255, 0xbfb8aa3b, v99
	v_exp_f32_e32 v254, v254
	v_exp_f32_e32 v255, v255
	v_add_f32_e32 v254, 1.0, v254
	v_add_f32_e32 v255, 1.0, v255
	v_rcp_f32_e32 v254, v254
	v_rcp_f32_e32 v255, v255
	v_mul_f32_e32 v98, v98, v254
	v_mul_f32_e32 v99, v99, v255
	v_cvt_pk_bf16_f32 v96, v96, v97
	v_cvt_pk_bf16_f32 v98, v98, v99
	global_store_short v181, v96, s[60:61]
	v_add_u32_e32 v251, 0x2000, v181
	global_store_short_d16_hi v251, v96, s[60:61]
	v_add_u32_e32 v252, 0x4000, v181
	global_store_short v252, v98, s[60:61]
	v_add_u32_e32 v253, 0x6000, v181
	global_store_short_d16_hi v253, v98, s[60:61]
	v_mul_f32_e32 v254, 0xbfb8aa3b, v100
	v_mul_f32_e32 v255, 0xbfb8aa3b, v101
	v_exp_f32_e32 v254, v254
	v_exp_f32_e32 v255, v255
	v_add_f32_e32 v254, 1.0, v254
	v_add_f32_e32 v255, 1.0, v255
	v_rcp_f32_e32 v254, v254
	v_rcp_f32_e32 v255, v255
	v_mul_f32_e32 v100, v100, v254
	v_mul_f32_e32 v101, v101, v255
	v_mul_f32_e32 v254, 0xbfb8aa3b, v102
	v_mul_f32_e32 v255, 0xbfb8aa3b, v103
	v_exp_f32_e32 v254, v254
	v_exp_f32_e32 v255, v255
	v_add_f32_e32 v254, 1.0, v254
	v_add_f32_e32 v255, 1.0, v255
	v_rcp_f32_e32 v254, v254
	v_rcp_f32_e32 v255, v255
	v_mul_f32_e32 v102, v102, v254
	v_mul_f32_e32 v103, v103, v255
	v_cvt_pk_bf16_f32 v100, v100, v101
	v_cvt_pk_bf16_f32 v102, v102, v103
	global_store_short v181, v100, s[60:61] offset:32
	global_store_short_d16_hi v251, v100, s[60:61] offset:32
	global_store_short v252, v102, s[60:61] offset:32
; __device__ __forceinline__ u16 f2bf(float f) { return (u16)(cvtpk(f, f) & 0xffffu); }
; #define FOR_M _Pragma("unroll") for (int m = 0; m < 4; ++m)
; #define FOR_J _Pragma("unroll") for (int j = 0; j < 4; ++j)
; #define OPQ(x) asm volatile("" : "+v"(x))
; #define ENDM __builtin_amdgcn_sched_barrier(0)
; template <int EPI>
; __device__ __forceinline__ void epi_quad(const Params& P, f32x4 (&acc)[4][2], int rowb, int pn, int wc, int fr, int fq,
;                                          const float* xres, float* yout, const float* rstd_q) {
;     ...
;     } else if (pn < 128) {
;       char* gb_ = (char*)(P_gate + (size_t)rowb * DM + (pn - 96) * 128);
;       const unsigned vo = (r4 * DM + cg) * 2;
;       FOR_M { unsigned vom = vo + (unsigned)(m * 16 * DM) * 2; OPQ(vom);
;         FOR_J {
; #pragma unroll
;           for (int n = 0; n < 2; ++n) {
;             const float v = acc[m][n][j];
;             ST16(gb_, vom + (unsigned)(j * DM + n * 16) * 2, f2bf(v * __builtin_amdgcn_rcpf(1.f + __expf(-v))));
;           }
;         } ENDM; }
	global_store_short_d16_hi v253, v102, s[60:61] offset:32
	v_mul_f32_e32 v254, 0xbfb8aa3b, v104
	v_mul_f32_e32 v255, 0xbfb8aa3b, v105
	v_exp_f32_e32 v254, v254
	v_exp_f32_e32 v255, v255
	v_add_f32_e32 v254, 1.0, v254
	v_add_f32_e32 v255, 1.0, v255
	v_rcp_f32_e32 v254, v254
	v_rcp_f32_e32 v255, v255
	v_mul_f32_e32 v104, v104, v254
	v_mul_f32_e32 v105, v105, v255
	v_mul_f32_e32 v254, 0xbfb8aa3b, v106
	v_mul_f32_e32 v255, 0xbfb8aa3b, v107
	v_exp_f32_e32 v254, v254
	v_exp_f32_e32 v255, v255
	v_add_f32_e32 v254, 1.0, v254
	v_add_f32_e32 v255, 1.0, v255
	v_rcp_f32_e32 v254, v254
	v_rcp_f32_e32 v255, v255
	v_mul_f32_e32 v106, v106, v254
	v_mul_f32_e32 v107, v107, v255
	v_cvt_pk_bf16_f32 v104, v104, v105
	v_cvt_pk_bf16_f32 v106, v106, v107
	global_store_short v182, v104, s[60:61]
	v_add_u32_e32 v251, 0x2000, v182
	global_store_short_d16_hi v251, v104, s[60:61]
	v_add_u32_e32 v252, 0x4000, v182
	global_store_short v252, v106, s[60:61]
	v_add_u32_e32 v253, 0x6000, v182
	global_store_short_d16_hi v253, v106, s[60:61]
	v_mul_f32_e32 v254, 0xbfb8aa3b, v108
	v_mul_f32_e32 v255, 0xbfb8aa3b, v109
	v_exp_f32_e32 v254, v254
	v_exp_f32_e32 v255, v255
	v_add_f32_e32 v254, 1.0, v254
	v_add_f32_e32 v255, 1.0, v255
	v_rcp_f32_e32 v254, v254
	v_rcp_f32_e32 v255, v255
	v_mul_f32_e32 v108, v108, v254
	v_mul_f32_e32 v109, v109, v255
	v_mul_f32_e32 v254, 0xbfb8aa3b, v110
	v_mul_f32_e32 v255, 0xbfb8aa3b, v111
	v_exp_f32_e32 v254, v254
	v_exp_f32_e32 v255, v255
	v_add_f32_e32 v254, 1.0, v254
	v_add_f32_e32 v255, 1.0, v255
	v_rcp_f32_e32 v254, v254
	v_rcp_f32_e32 v255, v255
	v_mul_f32_e32 v110, v110, v254
	v_mul_f32_e32 v111, v111, v255
	v_cvt_pk_bf16_f32 v108, v108, v109
	v_cvt_pk_bf16_f32 v110, v110, v111
	global_store_short v182, v108, s[60:61] offset:32
	global_store_short_d16_hi v251, v108, s[60:61] offset:32
	global_store_short v252, v110, s[60:61] offset:32
	global_store_short_d16_hi v253, v110, s[60:61] offset:32
	v_mul_f32_e32 v254, 0xbfb8aa3b, v112
	v_mul_f32_e32 v255, 0xbfb8aa3b, v113
	v_exp_f32_e32 v254, v254
	v_exp_f32_e32 v255, v255
	v_add_f32_e32 v254, 1.0, v254
	v_add_f32_e32 v255, 1.0, v255
	v_rcp_f32_e32 v254, v254
	v_rcp_f32_e32 v255, v255
	v_mul_f32_e32 v112, v112, v254
	v_mul_f32_e32 v113, v113, v255
	v_mul_f32_e32 v254, 0xbfb8aa3b, v114
	v_mul_f32_e32 v255, 0xbfb8aa3b, v115
	v_exp_f32_e32 v254, v254
	v_exp_f32_e32 v255, v255
	v_add_f32_e32 v254, 1.0, v254
	v_add_f32_e32 v255, 1.0, v255
	v_rcp_f32_e32 v254, v254
	v_rcp_f32_e32 v255, v255
	v_mul_f32_e32 v114, v114, v254
	v_mul_f32_e32 v115, v115, v255
	v_cvt_pk_bf16_f32 v112, v112, v113
	v_cvt_pk_bf16_f32 v114, v114, v115
	global_store_short v183, v112, s[60:61]
	v_add_u32_e32 v251, 0x2000, v183
	global_store_short_d16_hi v251, v112, s[60:61]
	v_add_u32_e32 v252, 0x4000, v183
	global_store_short v252, v114, s[60:61]
	v_add_u32_e32 v253, 0x6000, v183
	global_store_short_d16_hi v253, v114, s[60:61]
	v_mul_f32_e32 v254, 0xbfb8aa3b, v116
	v_mul_f32_e32 v255, 0xbfb8aa3b, v117
	v_exp_f32_e32 v254, v254
	v_exp_f32_e32 v255, v255
	v_add_f32_e32 v254, 1.0, v254
	v_add_f32_e32 v255, 1.0, v255
	v_rcp_f32_e32 v254, v254
	v_rcp_f32_e32 v255, v255
	v_mul_f32_e32 v116, v116, v254
	v_mul_f32_e32 v117, v117, v255
	v_mul_f32_e32 v254, 0xbfb8aa3b, v118
	v_mul_f32_e32 v255, 0xbfb8aa3b, v119
	v_exp_f32_e32 v254, v254
	v_exp_f32_e32 v255, v255
	v_add_f32_e32 v254, 1.0, v254
	v_add_f32_e32 v255, 1.0, v255
	v_rcp_f32_e32 v254, v254
	v_rcp_f32_e32 v255, v255
	v_mul_f32_e32 v118, v118, v254
	v_mul_f32_e32 v119, v119, v255
	v_cvt_pk_bf16_f32 v116, v116, v117
	v_cvt_pk_bf16_f32 v118, v118, v119
	global_store_short v183, v116, s[60:61] offset:32
	global_store_short_d16_hi v251, v116, s[60:61] offset:32
	global_store_short v252, v118, s[60:61] offset:32
	global_store_short_d16_hi v253, v118, s[60:61] offset:32

; __device__ __forceinline__ u16 f2bf(float f) { return (u16)(cvtpk(f, f) & 0xffffu); }
; #define FOR_M _Pragma("unroll") for (int m = 0; m < 4; ++m)
; #define FOR_J _Pragma("unroll") for (int j = 0; j < 4; ++j)
; #define OPQ(x) asm volatile("" : "+v"(x))
; #define ENDM __builtin_amdgcn_sched_barrier(0)
; template <int EPI>
; __device__ __forceinline__ void epi_quad(const Params& P, f32x4 (&acc)[4][2], int rowb, int pn, int wc, int fr, int fq,
;                                          const float* xres, float* yout, const float* rstd_q) {
;     ...
;     if (pn < 96) {
;       const int which = pn >> 5, h = pn & 31;
;       u16* base = which == 0 ? P_q1 : (which == 1 ? P_k1 : P_v1);
;       const float sc = which == 0 ? QSCALE : 1.f;
;       char* ob_ = (char*)(base + ((size_t)(b * 32 + h) * SEQ + pos0) * 128);
;       const unsigned vo = (r4 * 128 + cg) * 2;
;       FOR_M { unsigned vom = vo + (unsigned)(m * 16 * 128) * 2; OPQ(vom);
;         FOR_J {
; #pragma unroll
;           for (int n = 0; n < 2; ++n) ST16(ob_, vom + (unsigned)(j * 128 + n * 16) * 2, f2bf(acc[m][n][j] * sc));
;         } ENDM; }
;     } else if (pn < 128) {
;       char* gb_ = (char*)(P_gate + (size_t)rowb * DM + (pn - 96) * 128);
;       const unsigned vo = (r4 * DM + cg) * 2;
;       FOR_M { unsigned vom = vo + (unsigned)(m * 16 * DM) * 2; OPQ(vom);
;         FOR_J {
; #pragma unroll
;           for (int n = 0; n < 2; ++n) {
;             const float v = acc[m][n][j];
;             ST16(gb_, vom + (unsigned)(j * DM + n * 16) * 2, f2bf(v * __builtin_amdgcn_rcpf(1.f + __expf(-v))));
;           }
;         } ENDM; }
.LBB0_887:
	s_movk_i32 s1, 0x8400
	v_mad_u64_u32 v[136:137], s[60:61], v180, s1, v[132:133]
	s_and_b32 s81, s84, 30
	v_add_u32_e32 v187, 0x1000, v136
	v_add_u32_e32 v186, 0x2000, v136
	v_add_u32_e32 v131, 0x3000, v136
	v_cndmask_b32_e64 v137, 1.0, v179, s[6:7]
	s_andn2_b64 vcc, exec, s[2:3]
	s_lshl_b32 s1, s85, 7
	s_cbranch_vccnz .LBB0_889
	s_or_b32 s2, s86, s81
	s_ashr_i32 s3, s2, 31
	s_lshl_b64 s[2:3], s[2:3], 20
	s_add_u32 s2, s55, s2
	s_addc_u32 s3, s66, s3
	s_lshl_b32 s6, s1, 1
	s_add_u32 s6, s2, s6
	s_addc_u32 s7, s3, 0
	v_mul_f32_e32 v96, v137, v96
	v_mul_f32_e32 v97, v137, v97
	v_mul_f32_e32 v98, v137, v98
	v_mul_f32_e32 v99, v137, v99
	v_cvt_pk_bf16_f32 v96, v96, v97
	v_cvt_pk_bf16_f32 v98, v98, v99
	global_store_short v131, v96, s[6:7]
	global_store_short_d16_hi v131, v96, s[6:7] offset:256
	global_store_short v131, v98, s[6:7] offset:512
	global_store_short_d16_hi v131, v98, s[6:7] offset:768
	v_mul_f32_e32 v100, v137, v100
	v_mul_f32_e32 v101, v137, v101
	v_mul_f32_e32 v102, v137, v102
	v_mul_f32_e32 v103, v137, v103
	v_cvt_pk_bf16_f32 v100, v100, v101
	v_cvt_pk_bf16_f32 v102, v102, v103
	global_store_short v131, v100, s[6:7] offset:32
	global_store_short_d16_hi v131, v100, s[6:7] offset:288
	global_store_short v131, v102, s[6:7] offset:544
	global_store_short_d16_hi v131, v102, s[6:7] offset:800
	v_mul_f32_e32 v120, v137, v120
	v_mul_f32_e32 v121, v137, v121
	v_mul_f32_e32 v122, v137, v122
	v_mul_f32_e32 v123, v137, v123
	v_cvt_pk_bf16_f32 v120, v120, v121
	v_cvt_pk_bf16_f32 v122, v122, v123
	global_store_short v136, v120, s[6:7]
	global_store_short_d16_hi v136, v120, s[6:7] offset:256
	global_store_short v136, v122, s[6:7] offset:512
	global_store_short_d16_hi v136, v122, s[6:7] offset:768
	v_mul_f32_e32 v124, v137, v124
	v_mul_f32_e32 v125, v137, v125
	v_mul_f32_e32 v126, v137, v126
	v_mul_f32_e32 v127, v137, v127
	v_cvt_pk_bf16_f32 v124, v124, v125
	v_cvt_pk_bf16_f32 v126, v126, v127
	global_store_short v136, v124, s[6:7] offset:32
	global_store_short_d16_hi v136, v124, s[6:7] offset:288
	global_store_short v136, v126, s[6:7] offset:544
	global_store_short_d16_hi v136, v126, s[6:7] offset:800
	v_mul_f32_e32 v104, v137, v104
	v_mul_f32_e32 v105, v137, v105
	v_mul_f32_e32 v106, v137, v106
	v_mul_f32_e32 v107, v137, v107
	v_cvt_pk_bf16_f32 v104, v104, v105
	v_cvt_pk_bf16_f32 v106, v106, v107
	global_store_short v186, v104, s[6:7]
	global_store_short_d16_hi v186, v104, s[6:7] offset:256
	global_store_short v186, v106, s[6:7] offset:512
	global_store_short_d16_hi v186, v106, s[6:7] offset:768
	v_mul_f32_e32 v108, v137, v108
	v_mul_f32_e32 v109, v137, v109
	v_mul_f32_e32 v110, v137, v110
	v_mul_f32_e32 v111, v137, v111
	v_cvt_pk_bf16_f32 v108, v108, v109
	v_cvt_pk_bf16_f32 v110, v110, v111
	global_store_short v186, v108, s[6:7] offset:32
	global_store_short_d16_hi v186, v108, s[6:7] offset:288
	global_store_short v186, v110, s[6:7] offset:544
	global_store_short_d16_hi v186, v110, s[6:7] offset:800
	v_mul_f32_e32 v112, v137, v112
	v_mul_f32_e32 v113, v137, v113
	v_mul_f32_e32 v114, v137, v114
	v_mul_f32_e32 v115, v137, v115
	v_cvt_pk_bf16_f32 v112, v112, v113
	v_cvt_pk_bf16_f32 v114, v114, v115
	global_store_short v187, v112, s[6:7]
	global_store_short_d16_hi v187, v112, s[6:7] offset:256
	global_store_short v187, v114, s[6:7] offset:512
	global_store_short_d16_hi v187, v114, s[6:7] offset:768
	v_mul_f32_e32 v116, v137, v116
	v_mul_f32_e32 v117, v137, v117
	v_mul_f32_e32 v118, v137, v118
	v_mul_f32_e32 v119, v137, v119
	v_cvt_pk_bf16_f32 v116, v116, v117
	v_cvt_pk_bf16_f32 v118, v118, v119
	global_store_short v187, v116, s[6:7] offset:32
	global_store_short_d16_hi v187, v116, s[6:7] offset:288
	global_store_short v187, v118, s[6:7] offset:544
	global_store_short_d16_hi v187, v118, s[6:7] offset:800
.LBB0_889:
	s_or_b32 s33, s84, 1
	s_cmpk_gt_i32 s33, 0x5f
	s_cselect_b64 s[60:61], -1, 0
	s_lshl_b32 s2, s33, 8
	s_add_u32 s84, s94, s2
	s_addc_u32 s85, s95, 0
	v_cndmask_b32_e64 v140, 0, 1, s[62:63]
	s_cmpk_lt_i32 s33, 0x60
	s_mov_b64 s[2:3], -1
	v_cmp_ne_u32_e64 s[6:7], 1, v140
	s_cbranch_scc1 .LBB0_893
	s_and_b64 vcc, exec, s[6:7]
	s_cbranch_vccnz .LBB0_892
	s_add_u32 s2, s84, s64
	s_addc_u32 s3, s85, s65
	s_add_u32 s62, s2, 0x16f0a000
	s_addc_u32 s63, s3, 0
	v_mul_f32_e32 v254, 0xbfb8aa3b, v88
	v_mul_f32_e32 v255, 0xbfb8aa3b, v89
	v_exp_f32_e32 v254, v254
	v_exp_f32_e32 v255, v255
	v_add_f32_e32 v254, 1.0, v254
	v_add_f32_e32 v255, 1.0, v255
	v_rcp_f32_e32 v254, v254
	v_rcp_f32_e32 v255, v255
	v_mul_f32_e32 v88, v88, v254
	v_mul_f32_e32 v89, v89, v255
	v_mul_f32_e32 v254, 0xbfb8aa3b, v90
	v_mul_f32_e32 v255, 0xbfb8aa3b, v91
	v_exp_f32_e32 v254, v254
	v_exp_f32_e32 v255, v255
	v_add_f32_e32 v254, 1.0, v254
	v_add_f32_e32 v255, 1.0, v255
	v_rcp_f32_e32 v254, v254
	v_rcp_f32_e32 v255, v255
	v_mul_f32_e32 v90, v90, v254
	v_mul_f32_e32 v91, v91, v255
	v_cvt_pk_bf16_f32 v88, v88, v89
	v_cvt_pk_bf16_f32 v90, v90, v91
	global_store_short v132, v88, s[62:63]
	v_add_u32_e32 v251, 0x2000, v132
	global_store_short_d16_hi v251, v88, s[62:63]
	v_add_u32_e32 v252, 0x4000, v132
	global_store_short v252, v90, s[62:63]
	v_add_u32_e32 v253, 0x6000, v132
	global_store_short_d16_hi v253, v90, s[62:63]
	v_mul_f32_e32 v254, 0xbfb8aa3b, v92
	v_mul_f32_e32 v255, 0xbfb8aa3b, v93
	v_exp_f32_e32 v254, v254
	v_exp_f32_e32 v255, v255
	v_add_f32_e32 v254, 1.0, v254
	v_add_f32_e32 v255, 1.0, v255
	v_rcp_f32_e32 v254, v254
	v_rcp_f32_e32 v255, v255
	v_mul_f32_e32 v92, v92, v254
	v_mul_f32_e32 v93, v93, v255
	v_mul_f32_e32 v254, 0xbfb8aa3b, v94
	v_mul_f32_e32 v255, 0xbfb8aa3b, v95
	v_exp_f32_e32 v254, v254
	v_exp_f32_e32 v255, v255
	v_add_f32_e32 v254, 1.0, v254
; __device__ __forceinline__ u16 f2bf(float f) { return (u16)(cvtpk(f, f) & 0xffffu); }
; #define FOR_M _Pragma("unroll") for (int m = 0; m < 4; ++m)
; #define FOR_J _Pragma("unroll") for (int j = 0; j < 4; ++j)
; #define OPQ(x) asm volatile("" : "+v"(x))
; #define ENDM __builtin_amdgcn_sched_barrier(0)
; template <int EPI>
; __device__ __forceinline__ void epi_quad(const Params& P, f32x4 (&acc)[4][2], int rowb, int pn, int wc, int fr, int fq,
;                                          const float* xres, float* yout, const float* rstd_q) {
;     ...
;     } else if (pn < 128) {
;       char* gb_ = (char*)(P_gate + (size_t)rowb * DM + (pn - 96) * 128);
;       const unsigned vo = (r4 * DM + cg) * 2;
;       FOR_M { unsigned vom = vo + (unsigned)(m * 16 * DM) * 2; OPQ(vom);
;         FOR_J {
; #pragma unroll
;           for (int n = 0; n < 2; ++n) {
;             const float v = acc[m][n][j];
;             ST16(gb_, vom + (unsigned)(j * DM + n * 16) * 2, f2bf(v * __builtin_amdgcn_rcpf(1.f + __expf(-v))));
;           }
;         } ENDM; }
	v_add_f32_e32 v255, 1.0, v255
	v_rcp_f32_e32 v254, v254
	v_rcp_f32_e32 v255, v255
	v_mul_f32_e32 v94, v94, v254
	v_mul_f32_e32 v95, v95, v255
	v_cvt_pk_bf16_f32 v92, v92, v93
	v_cvt_pk_bf16_f32 v94, v94, v95
	global_store_short v132, v92, s[62:63] offset:32
	global_store_short_d16_hi v251, v92, s[62:63] offset:32
	global_store_short v252, v94, s[62:63] offset:32
	global_store_short_d16_hi v253, v94, s[62:63] offset:32
	v_mul_f32_e32 v254, 0xbfb8aa3b, v64
	v_mul_f32_e32 v255, 0xbfb8aa3b, v65
	v_exp_f32_e32 v254, v254
	v_exp_f32_e32 v255, v255
	v_add_f32_e32 v254, 1.0, v254
	v_add_f32_e32 v255, 1.0, v255
	v_rcp_f32_e32 v254, v254
	v_rcp_f32_e32 v255, v255
	v_mul_f32_e32 v64, v64, v254
	v_mul_f32_e32 v65, v65, v255
	v_mul_f32_e32 v254, 0xbfb8aa3b, v66
	v_mul_f32_e32 v255, 0xbfb8aa3b, v67
	v_exp_f32_e32 v254, v254
	v_exp_f32_e32 v255, v255
	v_add_f32_e32 v254, 1.0, v254
	v_add_f32_e32 v255, 1.0, v255
	v_rcp_f32_e32 v254, v254
	v_rcp_f32_e32 v255, v255
	v_mul_f32_e32 v66, v66, v254
	v_mul_f32_e32 v67, v67, v255
	v_cvt_pk_bf16_f32 v64, v64, v65
	v_cvt_pk_bf16_f32 v66, v66, v67
	global_store_short v181, v64, s[62:63]
	v_add_u32_e32 v251, 0x2000, v181
	global_store_short_d16_hi v251, v64, s[62:63]
	v_add_u32_e32 v252, 0x4000, v181
	global_store_short v252, v66, s[62:63]
	v_add_u32_e32 v253, 0x6000, v181
	global_store_short_d16_hi v253, v66, s[62:63]
	v_mul_f32_e32 v254, 0xbfb8aa3b, v68
	v_mul_f32_e32 v255, 0xbfb8aa3b, v69
	v_exp_f32_e32 v254, v254
	v_exp_f32_e32 v255, v255
	v_add_f32_e32 v254, 1.0, v254
	v_add_f32_e32 v255, 1.0, v255
	v_rcp_f32_e32 v254, v254
	v_rcp_f32_e32 v255, v255
	v_mul_f32_e32 v68, v68, v254
	v_mul_f32_e32 v69, v69, v255
	v_mul_f32_e32 v254, 0xbfb8aa3b, v70
	v_mul_f32_e32 v255, 0xbfb8aa3b, v71
	v_exp_f32_e32 v254, v254
	v_exp_f32_e32 v255, v255
	v_add_f32_e32 v254, 1.0, v254
	v_add_f32_e32 v255, 1.0, v255
	v_rcp_f32_e32 v254, v254
	v_rcp_f32_e32 v255, v255
	v_mul_f32_e32 v70, v70, v254
	v_mul_f32_e32 v71, v71, v255
	v_cvt_pk_bf16_f32 v68, v68, v69
	v_cvt_pk_bf16_f32 v70, v70, v71
	global_store_short v181, v68, s[62:63] offset:32
	global_store_short_d16_hi v251, v68, s[62:63] offset:32
	global_store_short v252, v70, s[62:63] offset:32
	global_store_short_d16_hi v253, v70, s[62:63] offset:32
	v_mul_f32_e32 v254, 0xbfb8aa3b, v72
	v_mul_f32_e32 v255, 0xbfb8aa3b, v73
	v_exp_f32_e32 v254, v254
	v_exp_f32_e32 v255, v255
	v_add_f32_e32 v254, 1.0, v254
	v_add_f32_e32 v255, 1.0, v255
	v_rcp_f32_e32 v254, v254
	v_rcp_f32_e32 v255, v255
	v_mul_f32_e32 v72, v72, v254
	v_mul_f32_e32 v73, v73, v255
	v_mul_f32_e32 v254, 0xbfb8aa3b, v74
	v_mul_f32_e32 v255, 0xbfb8aa3b, v75
	v_exp_f32_e32 v254, v254
	v_exp_f32_e32 v255, v255
	v_add_f32_e32 v254, 1.0, v254
	v_add_f32_e32 v255, 1.0, v255
	v_rcp_f32_e32 v254, v254
	v_rcp_f32_e32 v255, v255
	v_mul_f32_e32 v74, v74, v254
	v_mul_f32_e32 v75, v75, v255
	v_cvt_pk_bf16_f32 v72, v72, v73
	v_cvt_pk_bf16_f32 v74, v74, v75
	global_store_short v182, v72, s[62:63]
	v_add_u32_e32 v251, 0x2000, v182
	global_store_short_d16_hi v251, v72, s[62:63]
	v_add_u32_e32 v252, 0x4000, v182
	global_store_short v252, v74, s[62:63]
	v_add_u32_e32 v253, 0x6000, v182
	global_store_short_d16_hi v253, v74, s[62:63]
	v_mul_f32_e32 v254, 0xbfb8aa3b, v76
	v_mul_f32_e32 v255, 0xbfb8aa3b, v77
	v_exp_f32_e32 v254, v254
	v_exp_f32_e32 v255, v255
	v_add_f32_e32 v254, 1.0, v254
	v_add_f32_e32 v255, 1.0, v255
	v_rcp_f32_e32 v254, v254
	v_rcp_f32_e32 v255, v255
	v_mul_f32_e32 v76, v76, v254
	v_mul_f32_e32 v77, v77, v255
	v_mul_f32_e32 v254, 0xbfb8aa3b, v78
	v_mul_f32_e32 v255, 0xbfb8aa3b, v79
	v_exp_f32_e32 v254, v254
	v_exp_f32_e32 v255, v255
	v_add_f32_e32 v254, 1.0, v254
	v_add_f32_e32 v255, 1.0, v255
	v_rcp_f32_e32 v254, v254
	v_rcp_f32_e32 v255, v255
	v_mul_f32_e32 v78, v78, v254
	v_mul_f32_e32 v79, v79, v255
	v_cvt_pk_bf16_f32 v76, v76, v77
	v_cvt_pk_bf16_f32 v78, v78, v79
	global_store_short v182, v76, s[62:63] offset:32
	global_store_short_d16_hi v251, v76, s[62:63] offset:32
	global_store_short v252, v78, s[62:63] offset:32
	global_store_short_d16_hi v253, v78, s[62:63] offset:32
	v_mul_f32_e32 v254, 0xbfb8aa3b, v80
	v_mul_f32_e32 v255, 0xbfb8aa3b, v81
	v_exp_f32_e32 v254, v254
	v_exp_f32_e32 v255, v255
	v_add_f32_e32 v254, 1.0, v254
	v_add_f32_e32 v255, 1.0, v255
	v_rcp_f32_e32 v254, v254
	v_rcp_f32_e32 v255, v255
	v_mul_f32_e32 v80, v80, v254
	v_mul_f32_e32 v81, v81, v255
	v_mul_f32_e32 v254, 0xbfb8aa3b, v82
	v_mul_f32_e32 v255, 0xbfb8aa3b, v83
	v_exp_f32_e32 v254, v254
	v_exp_f32_e32 v255, v255
	v_add_f32_e32 v254, 1.0, v254
	v_add_f32_e32 v255, 1.0, v255
	v_rcp_f32_e32 v254, v254
	v_rcp_f32_e32 v255, v255
	v_mul_f32_e32 v82, v82, v254
	v_mul_f32_e32 v83, v83, v255
	v_cvt_pk_bf16_f32 v80, v80, v81
	v_cvt_pk_bf16_f32 v82, v82, v83
	global_store_short v183, v80, s[62:63]
	v_add_u32_e32 v251, 0x2000, v183
	global_store_short_d16_hi v251, v80, s[62:63]
	v_add_u32_e32 v252, 0x4000, v183
	global_store_short v252, v82, s[62:63]
	v_add_u32_e32 v253, 0x6000, v183
	global_store_short_d16_hi v253, v82, s[62:63]
	v_mul_f32_e32 v254, 0xbfb8aa3b, v84
	v_mul_f32_e32 v255, 0xbfb8aa3b, v85
	v_exp_f32_e32 v254, v254
	v_exp_f32_e32 v255, v255
	v_add_f32_e32 v254, 1.0, v254
	v_add_f32_e32 v255, 1.0, v255
	v_rcp_f32_e32 v254, v254
	v_rcp_f32_e32 v255, v255
	v_mul_f32_e32 v84, v84, v254
	v_mul_f32_e32 v85, v85, v255
	v_mul_f32_e32 v254, 0xbfb8aa3b, v86
	v_mul_f32_e32 v255, 0xbfb8aa3b, v87
	v_exp_f32_e32 v254, v254
	v_exp_f32_e32 v255, v255
	v_add_f32_e32 v254, 1.0, v254
	v_add_f32_e32 v255, 1.0, v255
	v_rcp_f32_e32 v254, v254
	v_rcp_f32_e32 v255, v255
	v_mul_f32_e32 v86, v86, v254
	v_mul_f32_e32 v87, v87, v255
	v_cvt_pk_bf16_f32 v84, v84, v85
	v_cvt_pk_bf16_f32 v86, v86, v87
	global_store_short v183, v84, s[62:63] offset:32
	global_store_short_d16_hi v251, v84, s[62:63] offset:32
	global_store_short v252, v86, s[62:63] offset:32
	global_store_short_d16_hi v253, v86, s[62:63] offset:32

; __device__ __forceinline__ u16 f2bf(float f) { return (u16)(cvtpk(f, f) & 0xffffu); }
; #define FOR_M _Pragma("unroll") for (int m = 0; m < 4; ++m)
; #define FOR_J _Pragma("unroll") for (int j = 0; j < 4; ++j)
; #define OPQ(x) asm volatile("" : "+v"(x))
; #define ENDM __builtin_amdgcn_sched_barrier(0)
; template <int EPI>
; __device__ __forceinline__ void epi_quad(const Params& P, f32x4 (&acc)[4][2], int rowb, int pn, int wc, int fr, int fq,
;                                          const float* xres, float* yout, const float* rstd_q) {
;     ...
;     if (pn < 96) {
;       const int which = pn >> 5, h = pn & 31;
;       u16* base = which == 0 ? P_q1 : (which == 1 ? P_k1 : P_v1);
;       const float sc = which == 0 ? QSCALE : 1.f;
;       char* ob_ = (char*)(base + ((size_t)(b * 32 + h) * SEQ + pos0) * 128);
;       const unsigned vo = (r4 * 128 + cg) * 2;
;       FOR_M { unsigned vom = vo + (unsigned)(m * 16 * 128) * 2; OPQ(vom);
;         FOR_J {
; #pragma unroll
;           for (int n = 0; n < 2; ++n) ST16(ob_, vom + (unsigned)(j * 128 + n * 16) * 2, f2bf(acc[m][n][j] * sc));
;         } ENDM; }
.LBB0_893:
	s_andn2_b64 vcc, exec, s[2:3]
	s_and_b32 s64, s33, 31
	s_cbranch_vccnz .LBB0_895
	s_or_b32 s2, s86, s64
	s_ashr_i32 s3, s2, 31
	s_lshl_b64 s[2:3], s[2:3], 20
	s_add_u32 s2, s55, s2
	s_addc_u32 s3, s66, s3
	s_lshl_b32 s1, s1, 1
	s_add_u32 s62, s2, s1
	s_addc_u32 s63, s3, 0
	v_mul_f32_e32 v64, v137, v64
	v_mul_f32_e32 v65, v137, v65
	v_mul_f32_e32 v66, v137, v66
	v_mul_f32_e32 v67, v137, v67
	v_cvt_pk_bf16_f32 v64, v64, v65
	v_cvt_pk_bf16_f32 v66, v66, v67
	global_store_short v131, v64, s[62:63]
	global_store_short_d16_hi v131, v64, s[62:63] offset:256
	global_store_short v131, v66, s[62:63] offset:512
	global_store_short_d16_hi v131, v66, s[62:63] offset:768
	v_mul_f32_e32 v68, v137, v68
	v_mul_f32_e32 v69, v137, v69
	v_mul_f32_e32 v70, v137, v70
	v_mul_f32_e32 v71, v137, v71
	v_cvt_pk_bf16_f32 v68, v68, v69
	v_cvt_pk_bf16_f32 v70, v70, v71
	global_store_short v131, v68, s[62:63] offset:32
	global_store_short_d16_hi v131, v68, s[62:63] offset:288
	global_store_short v131, v70, s[62:63] offset:544
	global_store_short_d16_hi v131, v70, s[62:63] offset:800
	v_mul_f32_e32 v88, v137, v88
	v_mul_f32_e32 v89, v137, v89
	v_mul_f32_e32 v90, v137, v90
	v_mul_f32_e32 v91, v137, v91
	v_cvt_pk_bf16_f32 v88, v88, v89
	v_cvt_pk_bf16_f32 v90, v90, v91
	global_store_short v136, v88, s[62:63]
	global_store_short_d16_hi v136, v88, s[62:63] offset:256
	global_store_short v136, v90, s[62:63] offset:512
	global_store_short_d16_hi v136, v90, s[62:63] offset:768
	v_mul_f32_e32 v92, v137, v92
	v_mul_f32_e32 v93, v137, v93
	v_mul_f32_e32 v94, v137, v94
	v_mul_f32_e32 v95, v137, v95
	v_cvt_pk_bf16_f32 v92, v92, v93
	v_cvt_pk_bf16_f32 v94, v94, v95
	global_store_short v136, v92, s[62:63] offset:32
	global_store_short_d16_hi v136, v92, s[62:63] offset:288
	global_store_short v136, v94, s[62:63] offset:544
	global_store_short_d16_hi v136, v94, s[62:63] offset:800
	v_mul_f32_e32 v72, v137, v72
	v_mul_f32_e32 v73, v137, v73
	v_mul_f32_e32 v74, v137, v74
	v_mul_f32_e32 v75, v137, v75
	v_cvt_pk_bf16_f32 v72, v72, v73
	v_cvt_pk_bf16_f32 v74, v74, v75
	global_store_short v186, v72, s[62:63]
	global_store_short_d16_hi v186, v72, s[62:63] offset:256
	global_store_short v186, v74, s[62:63] offset:512
	global_store_short_d16_hi v186, v74, s[62:63] offset:768
	v_mul_f32_e32 v76, v137, v76
	v_mul_f32_e32 v77, v137, v77
	v_mul_f32_e32 v78, v137, v78
	v_mul_f32_e32 v79, v137, v79
	v_cvt_pk_bf16_f32 v76, v76, v77
	v_cvt_pk_bf16_f32 v78, v78, v79
	global_store_short v186, v76, s[62:63] offset:32
	global_store_short_d16_hi v186, v76, s[62:63] offset:288
	global_store_short v186, v78, s[62:63] offset:544
	global_store_short_d16_hi v186, v78, s[62:63] offset:800
	v_mul_f32_e32 v80, v137, v80
	v_mul_f32_e32 v81, v137, v81
	v_mul_f32_e32 v82, v137, v82
	v_mul_f32_e32 v83, v137, v83
	v_cvt_pk_bf16_f32 v80, v80, v81
	v_cvt_pk_bf16_f32 v82, v82, v83
	global_store_short v187, v80, s[62:63]
	global_store_short_d16_hi v187, v80, s[62:63] offset:256
	global_store_short v187, v82, s[62:63] offset:512
	global_store_short_d16_hi v187, v82, s[62:63] offset:768
	v_mul_f32_e32 v84, v137, v84
	v_mul_f32_e32 v85, v137, v85
	v_mul_f32_e32 v86, v137, v86
	v_mul_f32_e32 v87, v137, v87
	v_cvt_pk_bf16_f32 v84, v84, v85
	v_cvt_pk_bf16_f32 v86, v86, v87
	global_store_short v187, v84, s[62:63] offset:32
	global_store_short_d16_hi v187, v84, s[62:63] offset:288
	global_store_short v187, v86, s[62:63] offset:544
	global_store_short_d16_hi v187, v86, s[62:63] offset:800

; __device__ __forceinline__ u16 f2bf(float f) { return (u16)(cvtpk(f, f) & 0xffffu); }
; #define FOR_M _Pragma("unroll") for (int m = 0; m < 4; ++m)
; #define FOR_J _Pragma("unroll") for (int j = 0; j < 4; ++j)
; #define OPQ(x) asm volatile("" : "+v"(x))
; #define ENDM __builtin_amdgcn_sched_barrier(0)
; template <int EPI>
; __device__ __forceinline__ void epi_quad(const Params& P, f32x4 (&acc)[4][2], int rowb, int pn, int wc, int fr, int fq,
;                                          const float* xres, float* yout, const float* rstd_q) {
;     ...
;     } else if (pn < 128) {
;       char* gb_ = (char*)(P_gate + (size_t)rowb * DM + (pn - 96) * 128);
;       const unsigned vo = (r4 * DM + cg) * 2;
;       FOR_M { unsigned vom = vo + (unsigned)(m * 16 * DM) * 2; OPQ(vom);
;         FOR_J {
; #pragma unroll
;           for (int n = 0; n < 2; ++n) {
;             const float v = acc[m][n][j];
;             ST16(gb_, vom + (unsigned)(j * DM + n * 16) * 2, f2bf(v * __builtin_amdgcn_rcpf(1.f + __expf(-v))));
;           }
;         } ENDM; }
.LBB0_900:
	s_andn2_b64 vcc, exec, s[2:3]
	s_cbranch_vccnz .LBB0_902
	s_add_u32 s2, s91, s0
	s_addc_u32 s3, s80, s1
	s_add_u32 s56, s2, 0x16f0a000
	s_addc_u32 s57, s3, 0
	v_mul_f32_e32 v254, 0xbfb8aa3b, v56
	v_mul_f32_e32 v255, 0xbfb8aa3b, v57
	v_exp_f32_e32 v254, v254
	v_exp_f32_e32 v255, v255
	v_add_f32_e32 v254, 1.0, v254
	v_add_f32_e32 v255, 1.0, v255
	v_rcp_f32_e32 v254, v254
	v_rcp_f32_e32 v255, v255
	v_mul_f32_e32 v56, v56, v254
	v_mul_f32_e32 v57, v57, v255
	v_mul_f32_e32 v254, 0xbfb8aa3b, v58
	v_mul_f32_e32 v255, 0xbfb8aa3b, v59
	v_exp_f32_e32 v254, v254
	v_exp_f32_e32 v255, v255
	v_add_f32_e32 v254, 1.0, v254
	v_add_f32_e32 v255, 1.0, v255
	v_rcp_f32_e32 v254, v254
	v_rcp_f32_e32 v255, v255
	v_mul_f32_e32 v58, v58, v254
	v_mul_f32_e32 v59, v59, v255
	v_cvt_pk_bf16_f32 v56, v56, v57
	v_cvt_pk_bf16_f32 v58, v58, v59
	global_store_short v132, v56, s[56:57]
	v_add_u32_e32 v251, 0x2000, v132
	global_store_short_d16_hi v251, v56, s[56:57]
	v_add_u32_e32 v252, 0x4000, v132
	global_store_short v252, v58, s[56:57]
	v_add_u32_e32 v253, 0x6000, v132
	global_store_short_d16_hi v253, v58, s[56:57]
	v_mul_f32_e32 v254, 0xbfb8aa3b, v60
	v_mul_f32_e32 v255, 0xbfb8aa3b, v61
	v_exp_f32_e32 v254, v254
	v_exp_f32_e32 v255, v255
	v_add_f32_e32 v254, 1.0, v254
	v_add_f32_e32 v255, 1.0, v255
	v_rcp_f32_e32 v254, v254
	v_rcp_f32_e32 v255, v255
	v_mul_f32_e32 v60, v60, v254
	v_mul_f32_e32 v61, v61, v255
	v_mul_f32_e32 v254, 0xbfb8aa3b, v62
	v_mul_f32_e32 v255, 0xbfb8aa3b, v63
	v_exp_f32_e32 v254, v254
	v_exp_f32_e32 v255, v255
	v_add_f32_e32 v254, 1.0, v254
	v_add_f32_e32 v255, 1.0, v255
	v_rcp_f32_e32 v254, v254
	v_rcp_f32_e32 v255, v255
	v_mul_f32_e32 v62, v62, v254
	v_mul_f32_e32 v63, v63, v255
	v_cvt_pk_bf16_f32 v60, v60, v61
	v_cvt_pk_bf16_f32 v62, v62, v63
	global_store_short v132, v60, s[56:57] offset:32
	global_store_short_d16_hi v251, v60, s[56:57] offset:32
	global_store_short v252, v62, s[56:57] offset:32
	global_store_short_d16_hi v253, v62, s[56:57] offset:32
	v_mul_f32_e32 v254, 0xbfb8aa3b, v32
	v_mul_f32_e32 v255, 0xbfb8aa3b, v33
	v_exp_f32_e32 v254, v254
	v_exp_f32_e32 v255, v255
	v_add_f32_e32 v254, 1.0, v254
	v_add_f32_e32 v255, 1.0, v255
	v_rcp_f32_e32 v254, v254
	v_rcp_f32_e32 v255, v255
	v_mul_f32_e32 v32, v32, v254
	v_mul_f32_e32 v33, v33, v255
	v_mul_f32_e32 v254, 0xbfb8aa3b, v34
	v_mul_f32_e32 v255, 0xbfb8aa3b, v35
	v_exp_f32_e32 v254, v254
	v_exp_f32_e32 v255, v255
	v_add_f32_e32 v254, 1.0, v254
	v_add_f32_e32 v255, 1.0, v255
	v_rcp_f32_e32 v254, v254
	v_rcp_f32_e32 v255, v255
	v_mul_f32_e32 v34, v34, v254
	v_mul_f32_e32 v35, v35, v255
	v_cvt_pk_bf16_f32 v32, v32, v33
	v_cvt_pk_bf16_f32 v34, v34, v35
	global_store_short v181, v32, s[56:57]
	v_add_u32_e32 v251, 0x2000, v181
	global_store_short_d16_hi v251, v32, s[56:57]
	v_add_u32_e32 v252, 0x4000, v181
	global_store_short v252, v34, s[56:57]
	v_add_u32_e32 v253, 0x6000, v181
	global_store_short_d16_hi v253, v34, s[56:57]
	v_mul_f32_e32 v254, 0xbfb8aa3b, v36
	v_mul_f32_e32 v255, 0xbfb8aa3b, v37
	v_exp_f32_e32 v254, v254
	v_exp_f32_e32 v255, v255
	v_add_f32_e32 v254, 1.0, v254
	v_add_f32_e32 v255, 1.0, v255
	v_rcp_f32_e32 v254, v254
	v_rcp_f32_e32 v255, v255
	v_mul_f32_e32 v36, v36, v254
	v_mul_f32_e32 v37, v37, v255
	v_mul_f32_e32 v254, 0xbfb8aa3b, v38
	v_mul_f32_e32 v255, 0xbfb8aa3b, v39
	v_exp_f32_e32 v254, v254
	v_exp_f32_e32 v255, v255
	v_add_f32_e32 v254, 1.0, v254
	v_add_f32_e32 v255, 1.0, v255
	v_rcp_f32_e32 v254, v254
	v_rcp_f32_e32 v255, v255
	v_mul_f32_e32 v38, v38, v254
	v_mul_f32_e32 v39, v39, v255
	v_cvt_pk_bf16_f32 v36, v36, v37
	v_cvt_pk_bf16_f32 v38, v38, v39
	global_store_short v181, v36, s[56:57] offset:32
	global_store_short_d16_hi v251, v36, s[56:57] offset:32
; __device__ __forceinline__ u16 f2bf(float f) { return (u16)(cvtpk(f, f) & 0xffffu); }
; #define FOR_M _Pragma("unroll") for (int m = 0; m < 4; ++m)
; #define FOR_J _Pragma("unroll") for (int j = 0; j < 4; ++j)
; #define OPQ(x) asm volatile("" : "+v"(x))
; #define ENDM __builtin_amdgcn_sched_barrier(0)
; template <int EPI>
; __device__ __forceinline__ void epi_quad(const Params& P, f32x4 (&acc)[4][2], int rowb, int pn, int wc, int fr, int fq,
;                                          const float* xres, float* yout, const float* rstd_q) {
;     ...
;     } else if (pn < 128) {
;       char* gb_ = (char*)(P_gate + (size_t)rowb * DM + (pn - 96) * 128);
;       const unsigned vo = (r4 * DM + cg) * 2;
;       FOR_M { unsigned vom = vo + (unsigned)(m * 16 * DM) * 2; OPQ(vom);
;         FOR_J {
; #pragma unroll
;           for (int n = 0; n < 2; ++n) {
;             const float v = acc[m][n][j];
;             ST16(gb_, vom + (unsigned)(j * DM + n * 16) * 2, f2bf(v * __builtin_amdgcn_rcpf(1.f + __expf(-v))));
;           }
;         } ENDM; }
	global_store_short v252, v38, s[56:57] offset:32
	global_store_short_d16_hi v253, v38, s[56:57] offset:32
	v_mul_f32_e32 v254, 0xbfb8aa3b, v40
	v_mul_f32_e32 v255, 0xbfb8aa3b, v41
	v_exp_f32_e32 v254, v254
	v_exp_f32_e32 v255, v255
	v_add_f32_e32 v254, 1.0, v254
	v_add_f32_e32 v255, 1.0, v255
	v_rcp_f32_e32 v254, v254
	v_rcp_f32_e32 v255, v255
	v_mul_f32_e32 v40, v40, v254
	v_mul_f32_e32 v41, v41, v255
	v_mul_f32_e32 v254, 0xbfb8aa3b, v42
	v_mul_f32_e32 v255, 0xbfb8aa3b, v43
	v_exp_f32_e32 v254, v254
	v_exp_f32_e32 v255, v255
	v_add_f32_e32 v254, 1.0, v254
	v_add_f32_e32 v255, 1.0, v255
	v_rcp_f32_e32 v254, v254
	v_rcp_f32_e32 v255, v255
	v_mul_f32_e32 v42, v42, v254
	v_mul_f32_e32 v43, v43, v255
	v_cvt_pk_bf16_f32 v40, v40, v41
	v_cvt_pk_bf16_f32 v42, v42, v43
	global_store_short v182, v40, s[56:57]
	v_add_u32_e32 v251, 0x2000, v182
	global_store_short_d16_hi v251, v40, s[56:57]
	v_add_u32_e32 v252, 0x4000, v182
	global_store_short v252, v42, s[56:57]
	v_add_u32_e32 v253, 0x6000, v182
	global_store_short_d16_hi v253, v42, s[56:57]
	v_mul_f32_e32 v254, 0xbfb8aa3b, v44
	v_mul_f32_e32 v255, 0xbfb8aa3b, v45
	v_exp_f32_e32 v254, v254
	v_exp_f32_e32 v255, v255
	v_add_f32_e32 v254, 1.0, v254
	v_add_f32_e32 v255, 1.0, v255
	v_rcp_f32_e32 v254, v254
	v_rcp_f32_e32 v255, v255
	v_mul_f32_e32 v44, v44, v254
	v_mul_f32_e32 v45, v45, v255
	v_mul_f32_e32 v254, 0xbfb8aa3b, v46
	v_mul_f32_e32 v255, 0xbfb8aa3b, v47
	v_exp_f32_e32 v254, v254
	v_exp_f32_e32 v255, v255
	v_add_f32_e32 v254, 1.0, v254
	v_add_f32_e32 v255, 1.0, v255
	v_rcp_f32_e32 v254, v254
	v_rcp_f32_e32 v255, v255
	v_mul_f32_e32 v46, v46, v254
	v_mul_f32_e32 v47, v47, v255
	v_cvt_pk_bf16_f32 v44, v44, v45
	v_cvt_pk_bf16_f32 v46, v46, v47
	global_store_short v182, v44, s[56:57] offset:32
	global_store_short_d16_hi v251, v44, s[56:57] offset:32
	global_store_short v252, v46, s[56:57] offset:32
	global_store_short_d16_hi v253, v46, s[56:57] offset:32
	v_mul_f32_e32 v254, 0xbfb8aa3b, v48
	v_mul_f32_e32 v255, 0xbfb8aa3b, v49
	v_exp_f32_e32 v254, v254
	v_exp_f32_e32 v255, v255
	v_add_f32_e32 v254, 1.0, v254
	v_add_f32_e32 v255, 1.0, v255
	v_rcp_f32_e32 v254, v254
	v_rcp_f32_e32 v255, v255
	v_mul_f32_e32 v48, v48, v254
	v_mul_f32_e32 v49, v49, v255
	v_mul_f32_e32 v254, 0xbfb8aa3b, v50
	v_mul_f32_e32 v255, 0xbfb8aa3b, v51
	v_exp_f32_e32 v254, v254
	v_exp_f32_e32 v255, v255
	v_add_f32_e32 v254, 1.0, v254
	v_add_f32_e32 v255, 1.0, v255
	v_rcp_f32_e32 v254, v254
	v_rcp_f32_e32 v255, v255
	v_mul_f32_e32 v50, v50, v254
	v_mul_f32_e32 v51, v51, v255
	v_cvt_pk_bf16_f32 v48, v48, v49
	v_cvt_pk_bf16_f32 v50, v50, v51
	global_store_short v183, v48, s[56:57]
	v_add_u32_e32 v251, 0x2000, v183
	global_store_short_d16_hi v251, v48, s[56:57]
	v_add_u32_e32 v252, 0x4000, v183
	global_store_short v252, v50, s[56:57]
	v_add_u32_e32 v253, 0x6000, v183
	global_store_short_d16_hi v253, v50, s[56:57]
	v_mul_f32_e32 v254, 0xbfb8aa3b, v52
	v_mul_f32_e32 v255, 0xbfb8aa3b, v53
	v_exp_f32_e32 v254, v254
	v_exp_f32_e32 v255, v255
	v_add_f32_e32 v254, 1.0, v254
	v_add_f32_e32 v255, 1.0, v255
	v_rcp_f32_e32 v254, v254
	v_rcp_f32_e32 v255, v255
	v_mul_f32_e32 v52, v52, v254
	v_mul_f32_e32 v53, v53, v255
	v_mul_f32_e32 v254, 0xbfb8aa3b, v54
	v_mul_f32_e32 v255, 0xbfb8aa3b, v55
	v_exp_f32_e32 v254, v254
	v_exp_f32_e32 v255, v255
	v_add_f32_e32 v254, 1.0, v254
	v_add_f32_e32 v255, 1.0, v255
	v_rcp_f32_e32 v254, v254
	v_rcp_f32_e32 v255, v255
	v_mul_f32_e32 v54, v54, v254
	v_mul_f32_e32 v55, v55, v255
	v_cvt_pk_bf16_f32 v52, v52, v53
	v_cvt_pk_bf16_f32 v54, v54, v55
	global_store_short v183, v52, s[56:57] offset:32
	global_store_short_d16_hi v251, v52, s[56:57] offset:32
	global_store_short v252, v54, s[56:57] offset:32
	global_store_short_d16_hi v253, v54, s[56:57] offset:32

; __device__ __forceinline__ u16 f2bf(float f) { return (u16)(cvtpk(f, f) & 0xffffu); }
; #define FOR_M _Pragma("unroll") for (int m = 0; m < 4; ++m)
; #define FOR_J _Pragma("unroll") for (int j = 0; j < 4; ++j)
; #define OPQ(x) asm volatile("" : "+v"(x))
; #define ENDM __builtin_amdgcn_sched_barrier(0)
; template <int EPI>
; __device__ __forceinline__ void epi_quad(const Params& P, f32x4 (&acc)[4][2], int rowb, int pn, int wc, int fr, int fq,
;                                          const float* xres, float* yout, const float* rstd_q) {
;     ...
;     } else if (pn < 128) {
;       char* gb_ = (char*)(P_gate + (size_t)rowb * DM + (pn - 96) * 128);
;       const unsigned vo = (r4 * DM + cg) * 2;
;       FOR_M { unsigned vom = vo + (unsigned)(m * 16 * DM) * 2; OPQ(vom);
;         FOR_J {
; #pragma unroll
;           for (int n = 0; n < 2; ++n) {
;             const float v = acc[m][n][j];
;             ST16(gb_, vom + (unsigned)(j * DM + n * 16) * 2, f2bf(v * __builtin_amdgcn_rcpf(1.f + __expf(-v))));
;           }
;         } ENDM; }
.LBB0_904:
	s_and_b64 vcc, exec, s[6:7]
	s_cbranch_vccnz .LBB0_906
	s_add_u32 s0, s84, s0
	s_addc_u32 s1, s85, s1
	s_add_u32 s0, s0, 0x16f0a000
	s_addc_u32 s1, s1, 0
	v_mul_f32_e32 v254, 0xbfb8aa3b, v24
	v_mul_f32_e32 v255, 0xbfb8aa3b, v25
	v_exp_f32_e32 v254, v254
	v_exp_f32_e32 v255, v255
	v_add_f32_e32 v254, 1.0, v254
	v_add_f32_e32 v255, 1.0, v255
	v_rcp_f32_e32 v254, v254
	v_rcp_f32_e32 v255, v255
	v_mul_f32_e32 v24, v24, v254
	v_mul_f32_e32 v25, v25, v255
	v_mul_f32_e32 v254, 0xbfb8aa3b, v26
	v_mul_f32_e32 v255, 0xbfb8aa3b, v27
	v_exp_f32_e32 v254, v254
	v_exp_f32_e32 v255, v255
	v_add_f32_e32 v254, 1.0, v254
	v_add_f32_e32 v255, 1.0, v255
	v_rcp_f32_e32 v254, v254
	v_rcp_f32_e32 v255, v255
	v_mul_f32_e32 v26, v26, v254
	v_mul_f32_e32 v27, v27, v255
	v_cvt_pk_bf16_f32 v24, v24, v25
	v_cvt_pk_bf16_f32 v26, v26, v27
	global_store_short v132, v24, s[0:1]
	v_add_u32_e32 v251, 0x2000, v132
	global_store_short_d16_hi v251, v24, s[0:1]
	v_add_u32_e32 v252, 0x4000, v132
	global_store_short v252, v26, s[0:1]
	v_add_u32_e32 v253, 0x6000, v132
	global_store_short_d16_hi v253, v26, s[0:1]
	v_mul_f32_e32 v254, 0xbfb8aa3b, v28
	v_mul_f32_e32 v255, 0xbfb8aa3b, v29
	v_exp_f32_e32 v254, v254
	v_exp_f32_e32 v255, v255
	v_add_f32_e32 v254, 1.0, v254
	v_add_f32_e32 v255, 1.0, v255
	v_rcp_f32_e32 v254, v254
	v_rcp_f32_e32 v255, v255
	v_mul_f32_e32 v28, v28, v254
	v_mul_f32_e32 v29, v29, v255
	v_mul_f32_e32 v254, 0xbfb8aa3b, v30
	v_mul_f32_e32 v255, 0xbfb8aa3b, v31
	v_exp_f32_e32 v254, v254
	v_exp_f32_e32 v255, v255
	v_add_f32_e32 v254, 1.0, v254
	v_add_f32_e32 v255, 1.0, v255
	v_rcp_f32_e32 v254, v254
	v_rcp_f32_e32 v255, v255
	v_mul_f32_e32 v30, v30, v254
	v_mul_f32_e32 v31, v31, v255
	v_cvt_pk_bf16_f32 v28, v28, v29
	v_cvt_pk_bf16_f32 v30, v30, v31
	global_store_short v132, v28, s[0:1] offset:32
	global_store_short_d16_hi v251, v28, s[0:1] offset:32
	global_store_short v252, v30, s[0:1] offset:32
	global_store_short_d16_hi v253, v30, s[0:1] offset:32
	v_mul_f32_e32 v254, 0xbfb8aa3b, v0
	v_mul_f32_e32 v255, 0xbfb8aa3b, v1
	v_exp_f32_e32 v254, v254
	v_exp_f32_e32 v255, v255
	v_add_f32_e32 v254, 1.0, v254
	v_add_f32_e32 v255, 1.0, v255
	v_rcp_f32_e32 v254, v254
	v_rcp_f32_e32 v255, v255
	v_mul_f32_e32 v0, v0, v254
	v_mul_f32_e32 v1, v1, v255
	v_mul_f32_e32 v254, 0xbfb8aa3b, v2
	v_mul_f32_e32 v255, 0xbfb8aa3b, v3
	v_exp_f32_e32 v254, v254
	v_exp_f32_e32 v255, v255
	v_add_f32_e32 v254, 1.0, v254
	v_add_f32_e32 v255, 1.0, v255
	v_rcp_f32_e32 v254, v254
	v_rcp_f32_e32 v255, v255
	v_mul_f32_e32 v2, v2, v254
	v_mul_f32_e32 v3, v3, v255
	v_cvt_pk_bf16_f32 v0, v0, v1
	v_cvt_pk_bf16_f32 v2, v2, v3
	global_store_short v181, v0, s[0:1]
	v_add_u32_e32 v251, 0x2000, v181
	global_store_short_d16_hi v251, v0, s[0:1]
	v_add_u32_e32 v252, 0x4000, v181
	global_store_short v252, v2, s[0:1]
	v_add_u32_e32 v253, 0x6000, v181
	global_store_short_d16_hi v253, v2, s[0:1]
	v_mul_f32_e32 v254, 0xbfb8aa3b, v4
	v_mul_f32_e32 v255, 0xbfb8aa3b, v5
	v_exp_f32_e32 v254, v254
	v_exp_f32_e32 v255, v255
	v_add_f32_e32 v254, 1.0, v254
	v_add_f32_e32 v255, 1.0, v255
	v_rcp_f32_e32 v254, v254
	v_rcp_f32_e32 v255, v255
	v_mul_f32_e32 v4, v4, v254
	v_mul_f32_e32 v5, v5, v255
	v_mul_f32_e32 v254, 0xbfb8aa3b, v6
	v_mul_f32_e32 v255, 0xbfb8aa3b, v7
	v_exp_f32_e32 v254, v254
	v_exp_f32_e32 v255, v255
	v_add_f32_e32 v254, 1.0, v254
	v_add_f32_e32 v255, 1.0, v255
	v_rcp_f32_e32 v254, v254
	v_rcp_f32_e32 v255, v255
	v_mul_f32_e32 v6, v6, v254
	v_mul_f32_e32 v7, v7, v255
	v_cvt_pk_bf16_f32 v4, v4, v5
	v_cvt_pk_bf16_f32 v6, v6, v7
	global_store_short v181, v4, s[0:1] offset:32
	global_store_short_d16_hi v251, v4, s[0:1] offset:32
	global_store_short v252, v6, s[0:1] offset:32
; __device__ __forceinline__ u16 f2bf(float f) { return (u16)(cvtpk(f, f) & 0xffffu); }
; #define FOR_M _Pragma("unroll") for (int m = 0; m < 4; ++m)
; #define FOR_J _Pragma("unroll") for (int j = 0; j < 4; ++j)
; #define OPQ(x) asm volatile("" : "+v"(x))
; #define ENDM __builtin_amdgcn_sched_barrier(0)
; template <int EPI>
; __device__ __forceinline__ void epi_quad(const Params& P, f32x4 (&acc)[4][2], int rowb, int pn, int wc, int fr, int fq,
;                                          const float* xres, float* yout, const float* rstd_q) {
;     ...
;       char* gb_ = (char*)(P_gate + (size_t)rowb * DM + (pn - 96) * 128);
;       const unsigned vo = (r4 * DM + cg) * 2;
;       FOR_M { unsigned vom = vo + (unsigned)(m * 16 * DM) * 2; OPQ(vom);
;         FOR_J {
; #pragma unroll
;           for (int n = 0; n < 2; ++n) {
;             const float v = acc[m][n][j];
;             ST16(gb_, vom + (unsigned)(j * DM + n * 16) * 2, f2bf(v * __builtin_amdgcn_rcpf(1.f + __expf(-v))));
;           }
;         } ENDM; }
	global_store_short_d16_hi v253, v6, s[0:1] offset:32
	v_mul_f32_e32 v254, 0xbfb8aa3b, v8
	v_mul_f32_e32 v255, 0xbfb8aa3b, v9
	v_exp_f32_e32 v254, v254
	v_exp_f32_e32 v255, v255
	v_add_f32_e32 v254, 1.0, v254
	v_add_f32_e32 v255, 1.0, v255
	v_rcp_f32_e32 v254, v254
	v_rcp_f32_e32 v255, v255
	v_mul_f32_e32 v8, v8, v254
	v_mul_f32_e32 v9, v9, v255
	v_mul_f32_e32 v254, 0xbfb8aa3b, v10
	v_mul_f32_e32 v255, 0xbfb8aa3b, v11
	v_exp_f32_e32 v254, v254
	v_exp_f32_e32 v255, v255
	v_add_f32_e32 v254, 1.0, v254
	v_add_f32_e32 v255, 1.0, v255
	v_rcp_f32_e32 v254, v254
	v_rcp_f32_e32 v255, v255
	v_mul_f32_e32 v10, v10, v254
	v_mul_f32_e32 v11, v11, v255
	v_cvt_pk_bf16_f32 v8, v8, v9
	v_cvt_pk_bf16_f32 v10, v10, v11
	global_store_short v182, v8, s[0:1]
	v_add_u32_e32 v251, 0x2000, v182
	global_store_short_d16_hi v251, v8, s[0:1]
	v_add_u32_e32 v252, 0x4000, v182
	global_store_short v252, v10, s[0:1]
	v_add_u32_e32 v253, 0x6000, v182
	global_store_short_d16_hi v253, v10, s[0:1]
	v_mul_f32_e32 v254, 0xbfb8aa3b, v12
	v_mul_f32_e32 v255, 0xbfb8aa3b, v13
	v_exp_f32_e32 v254, v254
	v_exp_f32_e32 v255, v255
	v_add_f32_e32 v254, 1.0, v254
	v_add_f32_e32 v255, 1.0, v255
	v_rcp_f32_e32 v254, v254
	v_rcp_f32_e32 v255, v255
	v_mul_f32_e32 v12, v12, v254
	v_mul_f32_e32 v13, v13, v255
	v_mul_f32_e32 v254, 0xbfb8aa3b, v14
	v_mul_f32_e32 v255, 0xbfb8aa3b, v15
	v_exp_f32_e32 v254, v254
	v_exp_f32_e32 v255, v255
	v_add_f32_e32 v254, 1.0, v254
	v_add_f32_e32 v255, 1.0, v255
	v_rcp_f32_e32 v254, v254
	v_rcp_f32_e32 v255, v255
	v_mul_f32_e32 v14, v14, v254
	v_mul_f32_e32 v15, v15, v255
	v_cvt_pk_bf16_f32 v12, v12, v13
	v_cvt_pk_bf16_f32 v14, v14, v15
	global_store_short v182, v12, s[0:1] offset:32
	global_store_short_d16_hi v251, v12, s[0:1] offset:32
	global_store_short v252, v14, s[0:1] offset:32
	global_store_short_d16_hi v253, v14, s[0:1] offset:32
	v_mul_f32_e32 v254, 0xbfb8aa3b, v16
	v_mul_f32_e32 v255, 0xbfb8aa3b, v17
	v_exp_f32_e32 v254, v254
	v_exp_f32_e32 v255, v255
	v_add_f32_e32 v254, 1.0, v254
	v_add_f32_e32 v255, 1.0, v255
	v_rcp_f32_e32 v254, v254
	v_rcp_f32_e32 v255, v255
	v_mul_f32_e32 v16, v16, v254
	v_mul_f32_e32 v17, v17, v255
	v_mul_f32_e32 v254, 0xbfb8aa3b, v18
	v_mul_f32_e32 v255, 0xbfb8aa3b, v19
	v_exp_f32_e32 v254, v254
	v_exp_f32_e32 v255, v255
	v_add_f32_e32 v254, 1.0, v254
	v_add_f32_e32 v255, 1.0, v255
	v_rcp_f32_e32 v254, v254
	v_rcp_f32_e32 v255, v255
	v_mul_f32_e32 v18, v18, v254
	v_mul_f32_e32 v19, v19, v255
	v_cvt_pk_bf16_f32 v16, v16, v17
	v_cvt_pk_bf16_f32 v18, v18, v19
	global_store_short v183, v16, s[0:1]
	v_add_u32_e32 v251, 0x2000, v183
	global_store_short_d16_hi v251, v16, s[0:1]
	v_add_u32_e32 v252, 0x4000, v183
	global_store_short v252, v18, s[0:1]
	v_add_u32_e32 v253, 0x6000, v183
	global_store_short_d16_hi v253, v18, s[0:1]
	v_mul_f32_e32 v254, 0xbfb8aa3b, v20
	v_mul_f32_e32 v255, 0xbfb8aa3b, v21
	v_exp_f32_e32 v254, v254
	v_exp_f32_e32 v255, v255
	v_add_f32_e32 v254, 1.0, v254
	v_add_f32_e32 v255, 1.0, v255
	v_rcp_f32_e32 v254, v254
	v_rcp_f32_e32 v255, v255
	v_mul_f32_e32 v20, v20, v254
	v_mul_f32_e32 v21, v21, v255
	v_mul_f32_e32 v254, 0xbfb8aa3b, v22
	v_mul_f32_e32 v255, 0xbfb8aa3b, v23
	v_exp_f32_e32 v254, v254
	v_exp_f32_e32 v255, v255
	v_add_f32_e32 v254, 1.0, v254
	v_add_f32_e32 v255, 1.0, v255
	v_rcp_f32_e32 v254, v254
	v_rcp_f32_e32 v255, v255
	v_mul_f32_e32 v22, v22, v254
	v_mul_f32_e32 v23, v23, v255
	v_cvt_pk_bf16_f32 v20, v20, v21
	v_cvt_pk_bf16_f32 v22, v22, v23
	global_store_short v183, v20, s[0:1] offset:32
	global_store_short_d16_hi v251, v20, s[0:1] offset:32
	global_store_short v252, v22, s[0:1] offset:32
	global_store_short_d16_hi v253, v22, s[0:1] offset:32

; __device__ __forceinline__ u16 f2bf(float f) { return (u16)(cvtpk(f, f) & 0xffffu); }
; #define FOR_M _Pragma("unroll") for (int m = 0; m < 4; ++m)
; #define FOR_J _Pragma("unroll") for (int j = 0; j < 4; ++j)
; #define OPQ(x) asm volatile("" : "+v"(x))
; #define ENDM __builtin_amdgcn_sched_barrier(0)
; template <int EPI>
; __device__ __forceinline__ void epi_quad(const Params& P, f32x4 (&acc)[4][2], int rowb, int pn, int wc, int fr, int fq,
;                                          const float* xres, float* yout, const float* rstd_q) {
;     ...
;     if (pn < 96) {
;       const int which = pn >> 5, h = pn & 31;
;       u16* base = which == 0 ? P_q1 : (which == 1 ? P_k1 : P_v1);
;       const float sc = which == 0 ? QSCALE : 1.f;
;       char* ob_ = (char*)(base + ((size_t)(b * 32 + h) * SEQ + pos0) * 128);
;       const unsigned vo = (r4 * 128 + cg) * 2;
;       FOR_M { unsigned vom = vo + (unsigned)(m * 16 * 128) * 2; OPQ(vom);
;         FOR_J {
; #pragma unroll
;           for (int n = 0; n < 2; ++n) ST16(ob_, vom + (unsigned)(j * 128 + n * 16) * 2, f2bf(acc[m][n][j] * sc));
;         } ENDM; }
.LBB0_908:
	s_or_b32 s2, s62, s81
	s_ashr_i32 s3, s2, 31
	s_lshl_b64 s[2:3], s[2:3], 20
	s_add_u32 s2, s55, s2
	s_addc_u32 s3, s66, s3
	s_lshl_b32 s56, s33, 1
	s_add_u32 s56, s2, s56
	s_addc_u32 s57, s3, 0
	v_mul_f32_e32 v32, v137, v32
	v_mul_f32_e32 v33, v137, v33
	v_mul_f32_e32 v34, v137, v34
	v_mul_f32_e32 v35, v137, v35
	v_cvt_pk_bf16_f32 v32, v32, v33
	v_cvt_pk_bf16_f32 v34, v34, v35
	global_store_short v131, v32, s[56:57]
	global_store_short_d16_hi v131, v32, s[56:57] offset:256
	global_store_short v131, v34, s[56:57] offset:512
	global_store_short_d16_hi v131, v34, s[56:57] offset:768
	v_mul_f32_e32 v36, v137, v36
	v_mul_f32_e32 v37, v137, v37
	v_mul_f32_e32 v38, v137, v38
	v_mul_f32_e32 v39, v137, v39
	v_cvt_pk_bf16_f32 v36, v36, v37
	v_cvt_pk_bf16_f32 v38, v38, v39
	global_store_short v131, v36, s[56:57] offset:32
	global_store_short_d16_hi v131, v36, s[56:57] offset:288
	global_store_short v131, v38, s[56:57] offset:544
	global_store_short_d16_hi v131, v38, s[56:57] offset:800
	v_mul_f32_e32 v56, v137, v56
	v_mul_f32_e32 v57, v137, v57
	v_mul_f32_e32 v58, v137, v58
	v_mul_f32_e32 v59, v137, v59
	v_cvt_pk_bf16_f32 v56, v56, v57
	v_cvt_pk_bf16_f32 v58, v58, v59
	global_store_short v136, v56, s[56:57]
	global_store_short_d16_hi v136, v56, s[56:57] offset:256
	global_store_short v136, v58, s[56:57] offset:512
	global_store_short_d16_hi v136, v58, s[56:57] offset:768
	v_mul_f32_e32 v60, v137, v60
	v_mul_f32_e32 v61, v137, v61
	v_mul_f32_e32 v62, v137, v62
	v_mul_f32_e32 v63, v137, v63
	v_cvt_pk_bf16_f32 v60, v60, v61
	v_cvt_pk_bf16_f32 v62, v62, v63
	global_store_short v136, v60, s[56:57] offset:32
	global_store_short_d16_hi v136, v60, s[56:57] offset:288
	global_store_short v136, v62, s[56:57] offset:544
	global_store_short_d16_hi v136, v62, s[56:57] offset:800
	v_mul_f32_e32 v40, v137, v40
	v_mul_f32_e32 v41, v137, v41
	v_mul_f32_e32 v42, v137, v42
	v_mul_f32_e32 v43, v137, v43
	v_cvt_pk_bf16_f32 v40, v40, v41
	v_cvt_pk_bf16_f32 v42, v42, v43
	global_store_short v186, v40, s[56:57]
	global_store_short_d16_hi v186, v40, s[56:57] offset:256
	global_store_short v186, v42, s[56:57] offset:512
	global_store_short_d16_hi v186, v42, s[56:57] offset:768
	v_mul_f32_e32 v44, v137, v44
	v_mul_f32_e32 v45, v137, v45
	v_mul_f32_e32 v46, v137, v46
	v_mul_f32_e32 v47, v137, v47
	v_cvt_pk_bf16_f32 v44, v44, v45
	v_cvt_pk_bf16_f32 v46, v46, v47
	global_store_short v186, v44, s[56:57] offset:32
	global_store_short_d16_hi v186, v44, s[56:57] offset:288
	global_store_short v186, v46, s[56:57] offset:544
	global_store_short_d16_hi v186, v46, s[56:57] offset:800
	v_mul_f32_e32 v48, v137, v48
	v_mul_f32_e32 v49, v137, v49
	v_mul_f32_e32 v50, v137, v50
	v_mul_f32_e32 v51, v137, v51
	v_cvt_pk_bf16_f32 v48, v48, v49
	v_cvt_pk_bf16_f32 v50, v50, v51
	global_store_short v187, v48, s[56:57]
	global_store_short_d16_hi v187, v48, s[56:57] offset:256
	global_store_short v187, v50, s[56:57] offset:512
	global_store_short_d16_hi v187, v50, s[56:57] offset:768
	v_mul_f32_e32 v52, v137, v52
	v_mul_f32_e32 v53, v137, v53
	v_mul_f32_e32 v54, v137, v54
	v_mul_f32_e32 v55, v137, v55
	v_cvt_pk_bf16_f32 v52, v52, v53
	v_cvt_pk_bf16_f32 v54, v54, v55
	global_store_short v187, v52, s[56:57] offset:32
	global_store_short_d16_hi v187, v52, s[56:57] offset:288
	global_store_short v187, v54, s[56:57] offset:544
	global_store_short_d16_hi v187, v54, s[56:57] offset:800
	s_andn2_b64 vcc, exec, s[60:61]
	s_mov_b64 s[2:3], -1
	s_cbranch_vccz .LBB0_904

; __device__ __forceinline__ u16 f2bf(float f) { return (u16)(cvtpk(f, f) & 0xffffu); }
; #define FOR_M _Pragma("unroll") for (int m = 0; m < 4; ++m)
; #define FOR_J _Pragma("unroll") for (int j = 0; j < 4; ++j)
; #define OPQ(x) asm volatile("" : "+v"(x))
; #define ENDM __builtin_amdgcn_sched_barrier(0)
; template <int EPI>
; __device__ __forceinline__ void epi_quad(const Params& P, f32x4 (&acc)[4][2], int rowb, int pn, int wc, int fr, int fq,
;                                          const float* xres, float* yout, const float* rstd_q) {
;     ...
;     if (pn < 96) {
;       const int which = pn >> 5, h = pn & 31;
;       u16* base = which == 0 ? P_q1 : (which == 1 ? P_k1 : P_v1);
;       const float sc = which == 0 ? QSCALE : 1.f;
;       char* ob_ = (char*)(base + ((size_t)(b * 32 + h) * SEQ + pos0) * 128);
;       const unsigned vo = (r4 * 128 + cg) * 2;
;       FOR_M { unsigned vom = vo + (unsigned)(m * 16 * 128) * 2; OPQ(vom);
;         FOR_J {
; #pragma unroll
;           for (int n = 0; n < 2; ++n) ST16(ob_, vom + (unsigned)(j * 128 + n * 16) * 2, f2bf(acc[m][n][j] * sc));
;         } ENDM; }
.LBB0_910:
	s_or_b32 s0, s62, s64
	s_ashr_i32 s1, s0, 31
	s_lshl_b64 s[0:1], s[0:1], 20
	s_add_u32 s0, s55, s0
	s_addc_u32 s1, s66, s1
	s_lshl_b32 s2, s33, 1
	s_add_u32 s0, s0, s2
	s_addc_u32 s1, s1, 0
	v_mul_f32_e32 v0, v137, v0
	v_mul_f32_e32 v1, v137, v1
	v_mul_f32_e32 v2, v137, v2
	v_mul_f32_e32 v3, v137, v3
	v_cvt_pk_bf16_f32 v0, v0, v1
	v_cvt_pk_bf16_f32 v2, v2, v3
	global_store_short v131, v0, s[0:1]
	global_store_short_d16_hi v131, v0, s[0:1] offset:256
	global_store_short v131, v2, s[0:1] offset:512
	global_store_short_d16_hi v131, v2, s[0:1] offset:768
	v_mul_f32_e32 v4, v137, v4
	v_mul_f32_e32 v5, v137, v5
	v_mul_f32_e32 v6, v137, v6
	v_mul_f32_e32 v7, v137, v7
	v_cvt_pk_bf16_f32 v4, v4, v5
	v_cvt_pk_bf16_f32 v6, v6, v7
	global_store_short v131, v4, s[0:1] offset:32
	global_store_short_d16_hi v131, v4, s[0:1] offset:288
	global_store_short v131, v6, s[0:1] offset:544
	global_store_short_d16_hi v131, v6, s[0:1] offset:800
	v_mul_f32_e32 v24, v137, v24
	v_mul_f32_e32 v25, v137, v25
	v_mul_f32_e32 v26, v137, v26
	v_mul_f32_e32 v27, v137, v27
	v_cvt_pk_bf16_f32 v24, v24, v25
	v_cvt_pk_bf16_f32 v26, v26, v27
	global_store_short v136, v24, s[0:1]
	global_store_short_d16_hi v136, v24, s[0:1] offset:256
	global_store_short v136, v26, s[0:1] offset:512
	global_store_short_d16_hi v136, v26, s[0:1] offset:768
	v_mul_f32_e32 v28, v137, v28
	v_mul_f32_e32 v29, v137, v29
	v_mul_f32_e32 v30, v137, v30
	v_mul_f32_e32 v31, v137, v31
	v_cvt_pk_bf16_f32 v28, v28, v29
	v_cvt_pk_bf16_f32 v30, v30, v31
	global_store_short v136, v28, s[0:1] offset:32
	global_store_short_d16_hi v136, v28, s[0:1] offset:288
	global_store_short v136, v30, s[0:1] offset:544
	global_store_short_d16_hi v136, v30, s[0:1] offset:800
	v_mul_f32_e32 v8, v137, v8
	v_mul_f32_e32 v9, v137, v9
	v_mul_f32_e32 v10, v137, v10
	v_mul_f32_e32 v11, v137, v11
	v_cvt_pk_bf16_f32 v8, v8, v9
	v_cvt_pk_bf16_f32 v10, v10, v11
	global_store_short v186, v8, s[0:1]
	global_store_short_d16_hi v186, v8, s[0:1] offset:256
	global_store_short v186, v10, s[0:1] offset:512
	global_store_short_d16_hi v186, v10, s[0:1] offset:768
	v_mul_f32_e32 v12, v137, v12
	v_mul_f32_e32 v13, v137, v13
	v_mul_f32_e32 v14, v137, v14
	v_mul_f32_e32 v15, v137, v15
	v_cvt_pk_bf16_f32 v12, v12, v13
	v_cvt_pk_bf16_f32 v14, v14, v15
	global_store_short v186, v12, s[0:1] offset:32
	global_store_short_d16_hi v186, v12, s[0:1] offset:288
	global_store_short v186, v14, s[0:1] offset:544
	global_store_short_d16_hi v186, v14, s[0:1] offset:800
	v_mul_f32_e32 v16, v137, v16
	v_mul_f32_e32 v17, v137, v17
	v_mul_f32_e32 v18, v137, v18
	v_mul_f32_e32 v19, v137, v19
	v_cvt_pk_bf16_f32 v16, v16, v17
	v_cvt_pk_bf16_f32 v18, v18, v19
	global_store_short v187, v16, s[0:1]
	global_store_short_d16_hi v187, v16, s[0:1] offset:256
	global_store_short v187, v18, s[0:1] offset:512
	global_store_short_d16_hi v187, v18, s[0:1] offset:768
	v_mul_f32_e32 v20, v137, v20
	v_mul_f32_e32 v21, v137, v21
	v_mul_f32_e32 v22, v137, v22
	v_mul_f32_e32 v23, v137, v23
	v_cvt_pk_bf16_f32 v20, v20, v21
	v_cvt_pk_bf16_f32 v22, v22, v23
	global_store_short v187, v20, s[0:1] offset:32
	global_store_short_d16_hi v187, v20, s[0:1] offset:288
	global_store_short v187, v22, s[0:1] offset:544
	global_store_short_d16_hi v187, v22, s[0:1] offset:800

; __device__ __forceinline__ u16 f2bf(float f) { return (u16)(cvtpk(f, f) & 0xffffu); }
; #define FOR_M _Pragma("unroll") for (int m = 0; m < 4; ++m)
; #define FOR_J _Pragma("unroll") for (int j = 0; j < 4; ++j)
; #define OPQ(x) asm volatile("" : "+v"(x))
; #define ENDM __builtin_amdgcn_sched_barrier(0)
; template <int EPI>
; __device__ __forceinline__ void epi_quad(const Params& P, f32x4 (&acc)[4][2], int rowb, int pn, int wc, int fr, int fq,
;                                          const float* xres, float* yout, const float* rstd_q) {
;     ...
;   if constexpr (EPI == EPI_OUT) {
;     char* hb_ = (char*)((u16*)yout + (size_t)rowb * DM + pn * 128);
;     const unsigned vo = (r4 * DM + cg) * 2;
;     FOR_M { unsigned vom = vo + (unsigned)(m * 16 * DM) * 2; OPQ(vom);
;       FOR_J {
; #pragma unroll
;         for (int n = 0; n < 2; ++n) ST16(hb_, vom + (unsigned)(j * DM + n * 16) * 2, f2bf(acc[m][n][j]));
;       } ENDM; }
.LBB0_1082:
	s_add_i32 s2, s6, s33
	s_ashr_i32 s3, s2, 31
	v_mov_b32_e32 v128, v133
	v_mov_b32_e32 v158, v132
	s_lshl_b64 s[2:3], s[2:3], 13
	s_add_u32 s6, s16, s2
	v_lshlrev_b32_e32 v128, 15, v128
	v_lshlrev_b32_e32 v158, 1, v158
	s_addc_u32 s36, s17, s3
	s_lshl_b64 s[2:3], s[34:35], 1
	v_add3_u32 v160, v158, s48, v128
	s_add_u32 s34, s6, s2
	s_addc_u32 s35, s36, s3
	v_mov_b32_e32 v161, v160
	v_cvt_pk_bf16_f32 v92, v92, v93
	v_cvt_pk_bf16_f32 v94, v94, v95
	global_store_short v160, v92, s[34:35] offset:256
	v_add_u32_e32 v251, 0x2000, v160
	global_store_short_d16_hi v251, v92, s[34:35] offset:256
	v_add_u32_e32 v252, 0x4000, v160
	global_store_short v252, v94, s[34:35] offset:256
	v_add_u32_e32 v253, 0x6000, v160
	global_store_short_d16_hi v253, v94, s[34:35] offset:256
	v_cvt_pk_bf16_f32 v88, v88, v89
	v_cvt_pk_bf16_f32 v90, v90, v91
	global_store_short v160, v88, s[34:35] offset:288
	global_store_short_d16_hi v251, v88, s[34:35] offset:288
	global_store_short v252, v90, s[34:35] offset:288
	global_store_short_d16_hi v253, v90, s[34:35] offset:288
	v_cvt_pk_bf16_f32 v116, v116, v117
	v_cvt_pk_bf16_f32 v118, v118, v119
	v_add_u32_e32 v251, 0x20000, v160
	global_store_short v251, v116, s[34:35]
	v_add_u32_e32 v252, 0x22000, v160
	global_store_short_d16_hi v252, v116, s[34:35]
	v_add_u32_e32 v253, 0x24000, v160
	global_store_short v253, v118, s[34:35]
	v_add_u32_e32 v251, 0x26000, v160
	global_store_short_d16_hi v251, v118, s[34:35]
	v_cvt_pk_bf16_f32 v112, v112, v113
	v_cvt_pk_bf16_f32 v114, v114, v115
	v_add_u32_e32 v252, 0x20000, v160
	global_store_short v252, v112, s[34:35] offset:32
	v_add_u32_e32 v253, 0x22000, v160
	global_store_short_d16_hi v253, v112, s[34:35] offset:32
	v_add_u32_e32 v251, 0x24000, v160
	global_store_short v251, v114, s[34:35] offset:32
	v_add_u32_e32 v252, 0x26000, v160
	global_store_short_d16_hi v252, v114, s[34:35] offset:32
	v_cvt_pk_bf16_f32 v84, v84, v85
	v_cvt_pk_bf16_f32 v86, v86, v87
	v_add_u32_e32 v253, 0x20000, v160
	global_store_short v253, v84, s[34:35] offset:256
	v_add_u32_e32 v251, 0x22000, v160
	global_store_short_d16_hi v251, v84, s[34:35] offset:256
	v_add_u32_e32 v252, 0x24000, v160
	global_store_short v252, v86, s[34:35] offset:256
	v_add_u32_e32 v253, 0x26000, v160
	global_store_short_d16_hi v253, v86, s[34:35] offset:256
	v_cvt_pk_bf16_f32 v80, v80, v81
	v_cvt_pk_bf16_f32 v82, v82, v83
	v_add_u32_e32 v251, 0x20000, v160
	global_store_short v251, v80, s[34:35] offset:288
	v_add_u32_e32 v252, 0x22000, v160
	global_store_short_d16_hi v252, v80, s[34:35] offset:288
	v_add_u32_e32 v253, 0x24000, v160
	global_store_short v253, v82, s[34:35] offset:288
	v_add_u32_e32 v251, 0x26000, v160
	global_store_short_d16_hi v251, v82, s[34:35] offset:288
	v_cvt_pk_bf16_f32 v108, v108, v109
	v_cvt_pk_bf16_f32 v110, v110, v111
	v_add_u32_e32 v252, 0x40000, v160
	global_store_short v252, v108, s[34:35]
	v_add_u32_e32 v253, 0x42000, v160
	global_store_short_d16_hi v253, v108, s[34:35]
	v_add_u32_e32 v251, 0x44000, v160
	global_store_short v251, v110, s[34:35]
	v_add_u32_e32 v252, 0x46000, v160
	global_store_short_d16_hi v252, v110, s[34:35]
	v_cvt_pk_bf16_f32 v104, v104, v105
	v_cvt_pk_bf16_f32 v106, v106, v107
	v_add_u32_e32 v253, 0x40000, v160
	global_store_short v253, v104, s[34:35] offset:32
	v_add_u32_e32 v251, 0x42000, v160
	global_store_short_d16_hi v251, v104, s[34:35] offset:32
	v_add_u32_e32 v252, 0x44000, v160
	global_store_short v252, v106, s[34:35] offset:32
	v_add_u32_e32 v253, 0x46000, v160
	global_store_short_d16_hi v253, v106, s[34:35] offset:32
	v_cvt_pk_bf16_f32 v76, v76, v77
	v_cvt_pk_bf16_f32 v78, v78, v79
	v_add_u32_e32 v251, 0x40000, v160
	global_store_short v251, v76, s[34:35] offset:256
	v_add_u32_e32 v252, 0x42000, v160
	global_store_short_d16_hi v252, v76, s[34:35] offset:256
	v_add_u32_e32 v253, 0x44000, v160
	global_store_short v253, v78, s[34:35] offset:256
	v_add_u32_e32 v251, 0x46000, v160
	global_store_short_d16_hi v251, v78, s[34:35] offset:256
	v_cvt_pk_bf16_f32 v72, v72, v73
	v_cvt_pk_bf16_f32 v74, v74, v75
	v_add_u32_e32 v252, 0x40000, v160
	global_store_short v252, v72, s[34:35] offset:288
	v_add_u32_e32 v253, 0x42000, v160
	global_store_short_d16_hi v253, v72, s[34:35] offset:288
	v_add_u32_e32 v251, 0x44000, v160
	global_store_short v251, v74, s[34:35] offset:288
	v_add_u32_e32 v252, 0x46000, v160
	global_store_short_d16_hi v252, v74, s[34:35] offset:288
	v_cvt_pk_bf16_f32 v100, v100, v101
	v_cvt_pk_bf16_f32 v102, v102, v103
	v_add_u32_e32 v253, 0x60000, v160
	global_store_short v253, v100, s[34:35]
	v_add_u32_e32 v251, 0x62000, v160
	global_store_short_d16_hi v251, v100, s[34:35]
	v_add_u32_e32 v252, 0x64000, v160
	global_store_short v252, v102, s[34:35]
	v_add_u32_e32 v253, 0x66000, v160
	global_store_short_d16_hi v253, v102, s[34:35]
	v_cvt_pk_bf16_f32 v96, v96, v97
	v_cvt_pk_bf16_f32 v98, v98, v99
	v_add_u32_e32 v251, 0x60000, v160
	global_store_short v251, v96, s[34:35] offset:32
	v_add_u32_e32 v252, 0x62000, v160
	global_store_short_d16_hi v252, v96, s[34:35] offset:32
	v_add_u32_e32 v253, 0x64000, v160
	global_store_short v253, v98, s[34:35] offset:32
	v_add_u32_e32 v251, 0x66000, v160
	global_store_short_d16_hi v251, v98, s[34:35] offset:32
	v_cvt_pk_bf16_f32 v68, v68, v69
	v_cvt_pk_bf16_f32 v70, v70, v71
	v_add_u32_e32 v252, 0x60000, v160
	global_store_short v252, v68, s[34:35] offset:256
	v_add_u32_e32 v253, 0x62000, v160
	global_store_short_d16_hi v253, v68, s[34:35] offset:256
	v_add_u32_e32 v251, 0x64000, v160
	global_store_short v251, v70, s[34:35] offset:256
	v_add_u32_e32 v252, 0x66000, v160
	global_store_short_d16_hi v252, v70, s[34:35] offset:256
; __device__ __forceinline__ u16 f2bf(float f) { return (u16)(cvtpk(f, f) & 0xffffu); }
; #define FOR_M _Pragma("unroll") for (int m = 0; m < 4; ++m)
; #define FOR_J _Pragma("unroll") for (int j = 0; j < 4; ++j)
; #define OPQ(x) asm volatile("" : "+v"(x))
; #define ENDM __builtin_amdgcn_sched_barrier(0)
; template <int EPI>
; __device__ __forceinline__ void epi_quad(const Params& P, f32x4 (&acc)[4][2], int rowb, int pn, int wc, int fr, int fq,
;                                          const float* xres, float* yout, const float* rstd_q) {
;     ...
;   if constexpr (EPI == EPI_OUT) {
;     char* hb_ = (char*)((u16*)yout + (size_t)rowb * DM + pn * 128);
;     const unsigned vo = (r4 * DM + cg) * 2;
;     FOR_M { unsigned vom = vo + (unsigned)(m * 16 * DM) * 2; OPQ(vom);
;       FOR_J {
; #pragma unroll
;         for (int n = 0; n < 2; ++n) ST16(hb_, vom + (unsigned)(j * DM + n * 16) * 2, f2bf(acc[m][n][j]));
;       } ENDM; }
	v_cvt_pk_bf16_f32 v64, v64, v65
	v_cvt_pk_bf16_f32 v66, v66, v67
	v_add_u32_e32 v253, 0x60000, v160
	global_store_short v253, v64, s[34:35] offset:288
	v_add_u32_e32 v251, 0x62000, v160
	global_store_short_d16_hi v251, v64, s[34:35] offset:288
	v_add_u32_e32 v252, 0x64000, v160
	global_store_short v252, v66, s[34:35] offset:288
	v_add_u32_e32 v253, 0x66000, v160
	global_store_short_d16_hi v253, v66, s[34:35] offset:288
	v_cvt_pk_bf16_f32 v124, v124, v125
	v_cvt_pk_bf16_f32 v126, v126, v127
	global_store_short v161, v124, s[34:35]
	v_add_u32_e32 v251, 0x2000, v161
	global_store_short_d16_hi v251, v124, s[34:35]
	v_add_u32_e32 v252, 0x4000, v161
	global_store_short v252, v126, s[34:35]
	v_add_u32_e32 v253, 0x6000, v161
	global_store_short_d16_hi v253, v126, s[34:35]
	v_cvt_pk_bf16_f32 v120, v120, v121
	v_cvt_pk_bf16_f32 v122, v122, v123
	global_store_short v161, v120, s[34:35] offset:32
	global_store_short_d16_hi v251, v120, s[34:35] offset:32
	global_store_short v252, v122, s[34:35] offset:32
	global_store_short_d16_hi v253, v122, s[34:35] offset:32
	s_add_u32 s34, s34, 0x100000
	s_addc_u32 s35, s35, 0
	v_cvt_pk_bf16_f32 v60, v60, v61
	v_cvt_pk_bf16_f32 v62, v62, v63
	global_store_short v160, v60, s[34:35]
	v_add_u32_e32 v251, 0x2000, v160
	global_store_short_d16_hi v251, v60, s[34:35]
	v_add_u32_e32 v252, 0x4000, v160
	global_store_short v252, v62, s[34:35]
	v_add_u32_e32 v253, 0x6000, v160
	global_store_short_d16_hi v253, v62, s[34:35]
	v_cvt_pk_bf16_f32 v56, v56, v57
	v_cvt_pk_bf16_f32 v58, v58, v59
	global_store_short v160, v56, s[34:35] offset:32
	global_store_short_d16_hi v251, v56, s[34:35] offset:32
	global_store_short v252, v58, s[34:35] offset:32
	global_store_short_d16_hi v253, v58, s[34:35] offset:32
	v_cvt_pk_bf16_f32 v28, v28, v29
	v_cvt_pk_bf16_f32 v30, v30, v31
	global_store_short v160, v28, s[34:35] offset:256
	global_store_short_d16_hi v251, v28, s[34:35] offset:256
	global_store_short v252, v30, s[34:35] offset:256
	global_store_short_d16_hi v253, v30, s[34:35] offset:256
	v_cvt_pk_bf16_f32 v24, v24, v25
	v_cvt_pk_bf16_f32 v26, v26, v27
	global_store_short v160, v24, s[34:35] offset:288
	global_store_short_d16_hi v251, v24, s[34:35] offset:288
	global_store_short v252, v26, s[34:35] offset:288
	global_store_short_d16_hi v253, v26, s[34:35] offset:288
	v_cvt_pk_bf16_f32 v52, v52, v53
	v_cvt_pk_bf16_f32 v54, v54, v55
	v_add_u32_e32 v251, 0x20000, v160
	global_store_short v251, v52, s[34:35]
	v_add_u32_e32 v252, 0x22000, v160
	global_store_short_d16_hi v252, v52, s[34:35]
	v_add_u32_e32 v253, 0x24000, v160
	global_store_short v253, v54, s[34:35]
	v_add_u32_e32 v251, 0x26000, v160
	global_store_short_d16_hi v251, v54, s[34:35]
	v_cvt_pk_bf16_f32 v48, v48, v49
	v_cvt_pk_bf16_f32 v50, v50, v51
	v_add_u32_e32 v252, 0x20000, v160
	global_store_short v252, v48, s[34:35] offset:32
	v_add_u32_e32 v253, 0x22000, v160
	global_store_short_d16_hi v253, v48, s[34:35] offset:32
	v_add_u32_e32 v251, 0x24000, v160
	global_store_short v251, v50, s[34:35] offset:32
	v_add_u32_e32 v252, 0x26000, v160
	global_store_short_d16_hi v252, v50, s[34:35] offset:32
	v_cvt_pk_bf16_f32 v20, v20, v21
	v_cvt_pk_bf16_f32 v22, v22, v23
	v_add_u32_e32 v253, 0x20000, v160
	global_store_short v253, v20, s[34:35] offset:256
	v_add_u32_e32 v251, 0x22000, v160
	global_store_short_d16_hi v251, v20, s[34:35] offset:256
	v_add_u32_e32 v252, 0x24000, v160
	global_store_short v252, v22, s[34:35] offset:256
	v_add_u32_e32 v253, 0x26000, v160
	global_store_short_d16_hi v253, v22, s[34:35] offset:256
	v_cvt_pk_bf16_f32 v16, v16, v17
	v_cvt_pk_bf16_f32 v18, v18, v19
	v_add_u32_e32 v251, 0x20000, v160
	global_store_short v251, v16, s[34:35] offset:288
	v_add_u32_e32 v252, 0x22000, v160
; __device__ __forceinline__ u16 f2bf(float f) { return (u16)(cvtpk(f, f) & 0xffffu); }
; #define FOR_M _Pragma("unroll") for (int m = 0; m < 4; ++m)
; #define FOR_J _Pragma("unroll") for (int j = 0; j < 4; ++j)
; #define OPQ(x) asm volatile("" : "+v"(x))
; #define ENDM __builtin_amdgcn_sched_barrier(0)
; template <int EPI>
; __device__ __forceinline__ void epi_quad(const Params& P, f32x4 (&acc)[4][2], int rowb, int pn, int wc, int fr, int fq,
;                                          const float* xres, float* yout, const float* rstd_q) {
;     ...
;   if constexpr (EPI == EPI_OUT) {
;     char* hb_ = (char*)((u16*)yout + (size_t)rowb * DM + pn * 128);
;     const unsigned vo = (r4 * DM + cg) * 2;
;     FOR_M { unsigned vom = vo + (unsigned)(m * 16 * DM) * 2; OPQ(vom);
;       FOR_J {
; #pragma unroll
;         for (int n = 0; n < 2; ++n) ST16(hb_, vom + (unsigned)(j * DM + n * 16) * 2, f2bf(acc[m][n][j]));
;       } ENDM; }
; template <int EPI, bool SPLIT>
; __device__ __forceinline__ void gemm_phase(const Params& P, const u16* __restrict__ A, const u16* __restrict__ Bt, int NT  , int K,
;                                            const float* xres, float* yout, char* lds) {
;     ...
;     for (int ai = 0; ai < 2; ++ai)
; #pragma unroll
;       for (int bj = 0; bj < 2; ++bj)
;         epi_quad<EPI>(P, acc[ai][bj], brow + ai * 128 + wr * 64, pn * 2 + bj, wc, fr_e, fq_e, xres, yout, rstd_l + ai * 128 + wr * 64);
;     }
;     __syncthreads();
	global_store_short_d16_hi v252, v16, s[34:35] offset:288
	v_add_u32_e32 v253, 0x24000, v160
	global_store_short v253, v18, s[34:35] offset:288
	v_add_u32_e32 v251, 0x26000, v160
	global_store_short_d16_hi v251, v18, s[34:35] offset:288
	v_cvt_pk_bf16_f32 v44, v44, v45
	v_cvt_pk_bf16_f32 v46, v46, v47
	v_add_u32_e32 v252, 0x40000, v160
	global_store_short v252, v44, s[34:35]
	v_add_u32_e32 v253, 0x42000, v160
	global_store_short_d16_hi v253, v44, s[34:35]
	v_add_u32_e32 v251, 0x44000, v160
	global_store_short v251, v46, s[34:35]
	v_add_u32_e32 v252, 0x46000, v160
	global_store_short_d16_hi v252, v46, s[34:35]
	v_cvt_pk_bf16_f32 v40, v40, v41
	v_cvt_pk_bf16_f32 v42, v42, v43
	v_add_u32_e32 v253, 0x40000, v160
	global_store_short v253, v40, s[34:35] offset:32
	v_add_u32_e32 v251, 0x42000, v160
	global_store_short_d16_hi v251, v40, s[34:35] offset:32
	v_add_u32_e32 v252, 0x44000, v160
	global_store_short v252, v42, s[34:35] offset:32
	v_add_u32_e32 v253, 0x46000, v160
	global_store_short_d16_hi v253, v42, s[34:35] offset:32
	v_cvt_pk_bf16_f32 v12, v12, v13
	v_cvt_pk_bf16_f32 v14, v14, v15
	v_add_u32_e32 v251, 0x40000, v160
	global_store_short v251, v12, s[34:35] offset:256
	v_add_u32_e32 v252, 0x42000, v160
	global_store_short_d16_hi v252, v12, s[34:35] offset:256
	v_add_u32_e32 v253, 0x44000, v160
	global_store_short v253, v14, s[34:35] offset:256
	v_add_u32_e32 v251, 0x46000, v160
	global_store_short_d16_hi v251, v14, s[34:35] offset:256
	v_cvt_pk_bf16_f32 v8, v8, v9
	v_cvt_pk_bf16_f32 v10, v10, v11
	v_add_u32_e32 v252, 0x40000, v160
	global_store_short v252, v8, s[34:35] offset:288
	v_add_u32_e32 v253, 0x42000, v160
	global_store_short_d16_hi v253, v8, s[34:35] offset:288
	v_add_u32_e32 v251, 0x44000, v160
	global_store_short v251, v10, s[34:35] offset:288
	v_add_u32_e32 v252, 0x46000, v160
	global_store_short_d16_hi v252, v10, s[34:35] offset:288
	v_cvt_pk_bf16_f32 v36, v36, v37
	v_cvt_pk_bf16_f32 v38, v38, v39
	v_add_u32_e32 v253, 0x60000, v160
	global_store_short v253, v36, s[34:35]
	v_add_u32_e32 v251, 0x62000, v160
	global_store_short_d16_hi v251, v36, s[34:35]
	v_add_u32_e32 v252, 0x64000, v160
	global_store_short v252, v38, s[34:35]
	v_add_u32_e32 v253, 0x66000, v160
	global_store_short_d16_hi v253, v38, s[34:35]
	v_cvt_pk_bf16_f32 v32, v32, v33
	v_cvt_pk_bf16_f32 v34, v34, v35
	v_add_u32_e32 v251, 0x60000, v160
	global_store_short v251, v32, s[34:35] offset:32
	v_add_u32_e32 v252, 0x62000, v160
	global_store_short_d16_hi v252, v32, s[34:35] offset:32
	v_add_u32_e32 v253, 0x64000, v160
	global_store_short v253, v34, s[34:35] offset:32
	v_add_u32_e32 v251, 0x66000, v160
	global_store_short_d16_hi v251, v34, s[34:35] offset:32
	v_cvt_pk_bf16_f32 v4, v4, v5
	v_cvt_pk_bf16_f32 v6, v6, v7
	v_add_u32_e32 v252, 0x60000, v160
	global_store_short v252, v4, s[34:35] offset:256
	v_add_u32_e32 v253, 0x62000, v160
	global_store_short_d16_hi v253, v4, s[34:35] offset:256
	v_add_u32_e32 v251, 0x64000, v160
	global_store_short v251, v6, s[34:35] offset:256
	v_add_u32_e32 v252, 0x66000, v160
	global_store_short_d16_hi v252, v6, s[34:35] offset:256
	v_cvt_pk_bf16_f32 v0, v0, v1
	v_cvt_pk_bf16_f32 v2, v2, v3
	v_add_u32_e32 v253, 0x60000, v160
	global_store_short v253, v0, s[34:35] offset:288
	v_add_u32_e32 v251, 0x62000, v160
	global_store_short_d16_hi v251, v0, s[34:35] offset:288
	v_add_u32_e32 v252, 0x64000, v160
	global_store_short v252, v2, s[34:35] offset:288
	v_add_u32_e32 v253, 0x66000, v160
	global_store_short_d16_hi v253, v2, s[34:35] offset:288
	v_readlane_b32 s2, v250, 27
	s_add_i32 s49, s49, s90
	s_add_i32 s2, s2, s84
	s_cmpk_lt_i32 s49, 0x200
	s_waitcnt vmcnt(0)
	s_barrier
	v_writelane_b32 v250, s2, 27
	s_cbranch_scc0 .LBB0_1093
